# v7 plus write-through (sc1) stores in P4 so the full barrier's L2 writeback has little left to flush
# baseline (speedup 1.0000x reference)
; #define LAS __attribute__((address_space(3)))
; __device__ __forceinline__ float fexp(float x) { return __builtin_amdgcn_exp2f(x * LOG2E); }
; __device__ __forceinline__ float bflo(unsigned w) { return __uint_as_float(w << 16); }
; __device__ __forceinline__ float bfhi(unsigned w) { return __uint_as_float(w & 0xffff0000u); }
; __device__ __forceinline__ void ml_out_unit(LAS unsigned char* lds, const MixBufs& B, int b, int h, int seg, int tid) {
;     ...
;             const float fl = SQ[2 * ch], ml = SQ[2 * ch + 1], mn = fmaxf(fl + m, ml);
;             int cg = cg0, ts = ts0; asm volatile("" : "+v"(cg), "+v"(ts));
;             MLO_STAGE();
;             const size_t trow = t0 + 16 * ti + c;
;             if (ch + 1 < 8 * seg + 8) MLO_PREFETCH(ch + 1);
;             __syncthreads();
;             LAS unsigned char* CTc = lds + (cur ? O_CT1 : O_CT0); const LAS float* NVc = (const LAS float*)(lds + (cur ? O_NV1 : O_NV0));
;             const float fct = FC[16 * ti + c];
;             float mx = -INFINITY;
; #pragma unroll
;             for (int s4 = 0; s4 < 4; ++s4) { const f32x4 l4 = *(const LAS f32x4*)(LI + 16 * g + 4 * s4), f4 = *(const LAS f32x4*)(FC + 16 * g + 4 * s4);
; #pragma unroll
;                 for (int e = 0; e < 4; ++e) mx = fmaxf(mx, l4[e] - fabsf(fct - f4[e])); }
;             mx = fmaxf(mx, __shfl_xor(mx, 16)); mx = fmaxf(mx, __shfl_xor(mx, 32));
;             const float gi = fct + m, mt = fmaxf(gi, mx), sc = fexp(gi - mt);
;             bf16x8 qf[4];
; #pragma unroll
;             for (int kk = 0; kk < 4; ++kk) qf[kk] = frag_row(lds + O_Q, GP128, 16 * ti, 32 * kk, lane);
;             float qn = 0.f;
; #pragma unroll
;             for (int kk = 0; kk < 4; ++kk) { const v4u qq = __builtin_bit_cast(v4u, qf[kk]); const f32x4 n0 = *(const LAS f32x4*)(NVc + 32 * kk + 8 * g), n1 = *(const LAS f32x4*)(NVc + 32 * kk + 8 * g + 4);
;                 qn += (bflo(qq.x) * n0[0] + bfhi(qq.x) * n0[1]) + (bflo(qq.y) * n0[2] + bfhi(qq.y) * n0[3]) + (bflo(qq.z) * n1[0] + bfhi(qq.z) * n1[1]) + (bflo(qq.w) * n1[2] + bfhi(qq.w) * n1[3]); }
;             qn += __shfl_xor(qn, 16); qn += __shfl_xor(qn, 32);
.LBB0_672:
	v_add_f32_e32 v2, v186, v12
	v_max_f32_e32 v12, v13, v13
	v_max_f32_e32 v198, v2, v12
	s_waitcnt lgkmcnt(0)
	s_barrier
	ds_read_b32 v2, v157
	ds_read_b128 v[12:15], v159
	ds_read_b128 v[16:19], v159 offset:16
	ds_read_b128 v[20:23], v159 offset:32
	ds_read_b128 v[24:27], v159 offset:48
	ds_read_b128 v[28:31], v160
	ds_read_b128 v[32:35], v160 offset:16
	ds_read_b128 v[36:39], v160 offset:32
	ds_read_b128 v[40:43], v160 offset:48
	s_mov_b32 s5, 0xff800000
	s_waitcnt lgkmcnt(3)
	v_sub_f32_e32 v28, v2, v28
	v_sub_f32_e64 v12, v12, |v28|
	v_sub_f32_e32 v28, v2, v29
	v_sub_f32_e64 v13, v13, |v28|
	v_max3_f32 v12, v12, s5, v13
	v_sub_f32_e32 v13, v2, v30
	v_sub_f32_e64 v13, v14, |v13|
	v_sub_f32_e32 v14, v2, v31
	v_sub_f32_e64 v14, v15, |v14|
	v_max3_f32 v12, v12, v13, v14
	s_waitcnt lgkmcnt(2)
	v_sub_f32_e32 v13, v2, v32
	v_sub_f32_e32 v14, v2, v33
	v_sub_f32_e64 v13, v16, |v13|
	v_sub_f32_e64 v14, v17, |v14|
	v_max3_f32 v12, v12, v13, v14
	v_sub_f32_e32 v13, v2, v34
	v_sub_f32_e32 v14, v2, v35
	v_sub_f32_e64 v13, v18, |v13|
	v_sub_f32_e64 v14, v19, |v14|
	v_max3_f32 v12, v12, v13, v14
	s_waitcnt lgkmcnt(1)
	v_sub_f32_e32 v13, v2, v36
	v_sub_f32_e32 v14, v2, v37
	v_sub_f32_e64 v13, v20, |v13|
	v_sub_f32_e64 v14, v21, |v14|
	v_max3_f32 v12, v12, v13, v14
	v_sub_f32_e32 v13, v2, v38
	v_sub_f32_e32 v14, v2, v39
	v_sub_f32_e64 v13, v22, |v13|
	v_sub_f32_e64 v14, v23, |v14|
	v_max3_f32 v12, v12, v13, v14
	s_waitcnt lgkmcnt(0)
	v_sub_f32_e32 v13, v2, v40
	v_sub_f32_e32 v14, v2, v41
	v_sub_f32_e64 v13, v24, |v13|
	v_sub_f32_e64 v14, v25, |v14|
	v_max3_f32 v12, v12, v13, v14
	v_sub_f32_e32 v13, v2, v42
	v_sub_f32_e32 v14, v2, v43
	v_sub_f32_e64 v13, v26, |v13|
	v_sub_f32_e64 v14, v27, |v14|
	v_max3_f32 v12, v12, v13, v14
	v_and_b32_e32 v14, 64, v183
	v_xor_b32_e32 v13, 16, v183
	v_add_u32_e32 v14, 64, v14
	v_cmp_lt_i32_e32 vcc, v13, v14
	s_cmp_eq_u32 s7, 0
	s_cselect_b32 s5, 0x22000, s97
	v_cndmask_b32_e32 v13, v183, v13, vcc
	v_lshlrev_b32_e32 v200, 2, v13
	ds_bpermute_b32 v13, v200, v12
	v_add_u32_e32 v47, s5, v163
	s_cselect_b32 s4, 0x11000, s96
	s_waitcnt lgkmcnt(0)
	v_max_f32_e32 v13, v13, v13
	v_max_f32_e32 v12, v12, v13
	v_xor_b32_e32 v13, 32, v183
	v_cmp_lt_i32_e32 vcc, v13, v14
	v_add_f32_e32 v14, v186, v2
	s_nop 0
	v_cndmask_b32_e32 v13, v183, v13, vcc
	v_lshlrev_b32_e32 v199, 2, v13
	ds_bpermute_b32 v13, v199, v12
	s_waitcnt lgkmcnt(0)
	v_max3_f32 v102, v14, v12, v13
	v_sub_f32_e32 v12, v14, v102
	v_mul_f32_e32 v46, 0x3fb8aa3b, v12
	v_add_u32_e32 v12, v161, v158
	ds_read_b128 v[24:27], v12
	ds_read_b128 v[20:23], v12 offset:64
	ds_read_b128 v[16:19], v12 offset:128
	ds_read_b128 v[12:15], v12 offset:192
	ds_read_b128 v[28:31], v47
	ds_read_b128 v[32:35], v47 offset:16
	s_waitcnt lgkmcnt(5)
	v_lshlrev_b32_e32 v40, 16, v24
	v_and_b32_e32 v41, 0xffff0000, v25
	v_and_b32_e32 v36, 0xffff0000, v24
	s_waitcnt lgkmcnt(1)
	v_mov_b32_e32 v38, v29
	v_mov_b32_e32 v29, v31
	v_lshlrev_b32_e32 v37, 16, v25
	v_mov_b32_e32 v39, v30
	v_pk_mul_f32 v[28:29], v[28:29], v[40:41]
	v_and_b32_e32 v41, 0xffff0000, v21
	v_pk_fma_f32 v[44:45], v[38:39], v[36:37], v[28:29]
	ds_read_b128 v[28:31], v47 offset:128
	ds_read_b128 v[36:39], v47 offset:144
	v_lshlrev_b32_e32 v40, 16, v21
	v_and_b32_e32 v51, 0xffff0000, v20
	v_and_b32_e32 v50, 0xffff0000, v22
	s_waitcnt lgkmcnt(1)
	v_mul_f32_e32 v42, v31, v41
	v_pk_fma_f32 v[30:31], v[30:31], v[40:41], v[42:43] op_sel_hi:[1,1,0]
	v_mov_b32_e32 v43, v28
	s_waitcnt lgkmcnt(0)
	v_mov_b32_e32 v28, v37
	v_lshlrev_b32_e32 v41, 16, v20
	v_lshlrev_b32_e32 v40, 16, v22
	v_mov_b32_e32 v42, v36
	v_pk_mul_f32 v[28:29], v[28:29], v[50:51]
	v_and_b32_e32 v49, 0xffff0000, v26
	v_pk_fma_f32 v[28:29], v[42:43], v[40:41], v[28:29]
	v_lshlrev_b32_e32 v48, 16, v26
	v_pk_add_f32 v[30:31], v[28:29], v[30:31] op_sel:[1,0] op_sel_hi:[0,1]
	v_pk_add_f32 v[36:37], v[28:29], v[30:31]
	ds_read_b128 v[28:31], v47 offset:256
	ds_read_b128 v[40:43], v47 offset:272
	v_lshlrev_b32_e32 v37, 16, v17
	v_and_b32_e32 v51, 0xffff0000, v23
	v_lshlrev_b32_e32 v50, 16, v23
	s_waitcnt lgkmcnt(1)
	v_mul_f32_e32 v70, v30, v37
	v_and_b32_e32 v30, 0xffff0000, v17
	v_mul_f32_e32 v71, v31, v30
	v_lshlrev_b32_e32 v30, 16, v18
	v_and_b32_e32 v31, 0xffff0000, v18
	s_waitcnt lgkmcnt(0)
	v_mul_f32_e32 v68, v40, v30
	v_pk_fma_f32 v[30:31], v[40:41], v[30:31], v[68:69] op_sel_hi:[1,1,0]
	v_pk_mov_b32 v[40:41], v[26:27], v[16:17] op_sel:[1,0]
	v_lshlrev_b32_e32 v30, 16, v19
	v_mul_f32_e32 v72, v42, v30
	v_and_b32_e32 v30, 0xffff0000, v19
	v_mul_f32_e32 v37, v43, v30
	v_mul_f32_e32 v30, v33, v49
	v_mov_b32_e32 v68, v34
	v_mov_b32_e32 v69, v28
	v_and_b32_e32 v41, 0xffff0000, v41
	v_and_b32_e32 v40, 0xffff0000, v40
	v_mov_b32_e32 v28, v35
	v_pk_fma_f32 v[32:33], v[32:33], v[48:49], v[30:31] op_sel_hi:[1,1,0]
	v_pk_add_f32 v[34:35], v[44:45], v[44:45] op_sel:[0,1] op_sel_hi:[1,0]
	v_lshlrev_b32_e32 v43, 16, v16
	v_lshlrev_b32_e32 v42, 16, v27
	v_pk_mul_f32 v[28:29], v[28:29], v[40:41]
	v_mov_b32_e32 v33, v70
	v_mov_b32_e32 v35, v71
	v_pk_fma_f32 v[28:29], v[68:69], v[42:43], v[28:29]
	v_pk_add_f32 v[32:33], v[32:33], v[34:35]
	v_mov_b32_e32 v30, v3
	v_pk_add_f32 v[28:29], v[28:29], v[32:33]
	s_nop 0
	v_pk_add_f32 v[28:29], v[28:29], v[30:31]
	v_mul_f32_e32 v30, v39, v51
	v_pk_fma_f32 v[30:31], v[38:39], v[50:51], v[30:31] op_sel_hi:[1,1,0]
	s_nop 0
	v_mov_b32_e32 v31, v72
	v_pk_add_f32 v[30:31], v[30:31], v[36:37]
	v_lshlrev_b32_e32 v36, 16, v12
	v_pk_add_f32 v[28:29], v[30:31], v[28:29]
	s_nop 0
	v_pk_add_f32 v[68:69], v[28:29], v[28:29] op_sel:[0,1] op_sel_hi:[1,0]
	ds_read_b128 v[28:31], v47 offset:384
	ds_read_b128 v[32:35], v47 offset:400
	s_waitcnt lgkmcnt(1)
; #define LAS __attribute__((address_space(3)))
; #define MFMA16(a, b, c) __builtin_amdgcn_mfma_f32_16x16x32_bf16((a), (b), (c), 0, 0, 0)
; __device__ __forceinline__ float fexp(float x) { return __builtin_amdgcn_exp2f(x * LOG2E); }
; __device__ __forceinline__ unsigned cvtpk(float lo, float hi) { const f32x2_t v = {lo, hi}; const bf16x2_t b = __builtin_convertvector(v, bf16x2_t); return __builtin_bit_cast(unsigned, b); }
; __device__ __forceinline__ void ml_out_unit(LAS unsigned char* lds, const MixBufs& B, int b, int h, int seg, int tid) {
;     ...
;             float dsum = 0.f; bf16x8 pb[2];
; #pragma unroll
;             for (int ks = 0; ks < 2; ++ks) { f32x4 p2[2];
; #pragma unroll
;                 for (int jj = 0; jj < 2; ++jj) { const int sj = 2 * ks + jj;
;                     f32x4 acc = (f32x4){0.f, 0.f, 0.f, 0.f};
; #pragma unroll
;                     for (int kk = 0; kk < 4; ++kk) acc = MFMA16(frag_row(lds + O_K, GP128, 16 * sj, 32 * kk, lane), qf[kk], acc);
;                     const f32x4 li4 = *(const LAS f32x4*)(LI + 16 * sj + 4 * g), fc4 = *(const LAS f32x4*)(FC + 16 * sj + 4 * g);
; #pragma unroll
;                     for (int i = 0; i < 4; ++i) { p2[jj][i] = acc[i] * fexp(li4[i] - fabsf(fct - fc4[i]) - mt); dsum += p2[jj][i]; } }
;                 v4u pk; pk.x = cvtpk(p2[0][0], p2[0][1]); pk.y = cvtpk(p2[0][2], p2[0][3]); pk.z = cvtpk(p2[1][0], p2[1][1]); pk.w = cvtpk(p2[1][2], p2[1][3]);
;                 pb[ks] = __builtin_bit_cast(bf16x8, pk); }
;             dsum += __shfl_xor(dsum, 16); dsum += __shfl_xor(dsum, 32);
	v_mul_f32_e32 v72, v28, v36
	v_and_b32_e32 v28, 0xffff0000, v12
	v_mul_f32_e32 v78, v29, v28
	v_and_b32_e32 v29, 0xffff0000, v13
	v_lshlrev_b32_e32 v28, 16, v13
	v_mul_f32_e32 v36, v31, v29
	v_pk_fma_f32 v[76:77], v[30:31], v[28:29], v[36:37] op_sel_hi:[1,1,0]
	v_and_b32_e32 v29, 0xffff0000, v14
	v_lshlrev_b32_e32 v28, 16, v14
	s_waitcnt lgkmcnt(0)
	v_mul_f32_e32 v30, v33, v29
	v_pk_fma_f32 v[74:75], v[32:33], v[28:29], v[30:31] op_sel_hi:[1,1,0]
	v_and_b32_e32 v29, 0xffff0000, v15
	v_lshlrev_b32_e32 v28, 16, v15
	v_mul_f32_e32 v30, v35, v29
	v_pk_fma_f32 v[70:71], v[34:35], v[28:29], v[30:31] op_sel_hi:[1,1,0]
	ds_read_b128 v[28:31], v170 offset:17408
	ds_read_b128 v[32:35], v170 offset:17472
	s_waitcnt lgkmcnt(1)
	v_mfma_f32_16x16x32_bf16 v[28:31], v[28:31], v[24:27], 0
	s_waitcnt lgkmcnt(0)
	v_mfma_f32_16x16x32_bf16 v[28:31], v[32:35], v[20:23], v[28:31]
	ds_read_b128 v[32:35], v170 offset:17536
	s_waitcnt lgkmcnt(0)
	v_mfma_f32_16x16x32_bf16 v[28:31], v[32:35], v[16:19], v[28:31]
	ds_read_b128 v[32:35], v170 offset:17600
	s_waitcnt lgkmcnt(0)
	v_mfma_f32_16x16x32_bf16 v[28:31], v[32:35], v[12:15], v[28:31]
	ds_read_b128 v[32:35], v164
	ds_read_b128 v[36:39], v165
	s_waitcnt lgkmcnt(0)
	v_sub_f32_e32 v36, v2, v36
	v_sub_f32_e64 v32, v32, |v36|
	v_sub_f32_e32 v36, v2, v37
	v_sub_f32_e64 v33, v33, |v36|
	v_sub_f32_e32 v32, v32, v102
	v_sub_f32_e32 v33, v33, v102
	v_mul_f32_e32 v32, 0x3fb8aa3b, v32
	v_mul_f32_e32 v33, 0x3fb8aa3b, v33
	v_exp_f32_e32 v32, v32
	v_exp_f32_e32 v33, v33
	s_nop 0
	v_pk_mul_f32 v[40:41], v[28:29], v[32:33]
	s_nop 0
	v_add_f32_e32 v28, 0, v40
	v_add_f32_e32 v32, v41, v28
	v_sub_f32_e32 v28, v2, v38
	v_sub_f32_e32 v29, v2, v39
	v_sub_f32_e64 v28, v34, |v28|
	v_sub_f32_e64 v29, v35, |v29|
	v_sub_f32_e32 v28, v28, v102
	v_sub_f32_e32 v29, v29, v102
	v_mul_f32_e32 v28, 0x3fb8aa3b, v28
	v_mul_f32_e32 v29, 0x3fb8aa3b, v29
	v_exp_f32_e32 v28, v28
	v_exp_f32_e32 v29, v29
	s_nop 0
	v_pk_mul_f32 v[42:43], v[30:31], v[28:29]
	s_nop 0
	v_add_f32_e32 v28, v42, v32
	v_add_f32_e32 v44, v43, v28
	ds_read_b128 v[28:31], v170 offset:21760
	ds_read_b128 v[32:35], v170 offset:21824
	s_waitcnt lgkmcnt(1)
	v_mfma_f32_16x16x32_bf16 v[28:31], v[28:31], v[24:27], 0
	s_waitcnt lgkmcnt(0)
	v_mfma_f32_16x16x32_bf16 v[28:31], v[32:35], v[20:23], v[28:31]
	ds_read_b128 v[32:35], v170 offset:21888
	s_waitcnt lgkmcnt(0)
	v_mfma_f32_16x16x32_bf16 v[28:31], v[32:35], v[16:19], v[28:31]
	ds_read_b128 v[32:35], v170 offset:21952
	s_waitcnt lgkmcnt(0)
	v_mfma_f32_16x16x32_bf16 v[28:31], v[32:35], v[12:15], v[28:31]
	ds_read_b128 v[32:35], v164 offset:64
	ds_read_b128 v[36:39], v165 offset:64
	s_waitcnt lgkmcnt(0)
	v_sub_f32_e32 v36, v2, v36
	v_sub_f32_e64 v32, v32, |v36|
	v_sub_f32_e32 v36, v2, v37
	v_sub_f32_e64 v33, v33, |v36|
	v_sub_f32_e32 v32, v32, v102
	v_sub_f32_e32 v33, v33, v102
	v_mul_f32_e32 v32, 0x3fb8aa3b, v32
	v_mul_f32_e32 v33, 0x3fb8aa3b, v33
	v_exp_f32_e32 v32, v32
	v_exp_f32_e32 v33, v33
	s_nop 0
	v_pk_mul_f32 v[32:33], v[28:29], v[32:33]
	s_nop 0
	v_add_f32_e32 v28, v44, v32
	v_add_f32_e32 v36, v33, v28
	v_sub_f32_e32 v28, v2, v38
	v_sub_f32_e32 v29, v2, v39
	v_sub_f32_e64 v28, v34, |v28|
	v_sub_f32_e64 v29, v35, |v29|
	v_sub_f32_e32 v28, v28, v102
	v_sub_f32_e32 v29, v29, v102
	v_mul_f32_e32 v28, 0x3fb8aa3b, v28
	v_mul_f32_e32 v29, 0x3fb8aa3b, v29
	v_exp_f32_e32 v28, v28
	v_exp_f32_e32 v29, v29
	s_nop 0
	v_pk_mul_f32 v[34:35], v[30:31], v[28:29]
	s_nop 0
	v_add_f32_e32 v28, v34, v36
	v_add_f32_e32 v47, v35, v28
	v_cvt_pk_bf16_f32 v30, v32, v33
	v_cvt_pk_bf16_f32 v31, v34, v35
	ds_read_b128 v[32:35], v170 offset:26112
	ds_read_b128 v[36:39], v170 offset:26176
	s_waitcnt lgkmcnt(1)
	v_mfma_f32_16x16x32_bf16 v[32:35], v[32:35], v[24:27], 0
	v_cvt_pk_bf16_f32 v28, v40, v41
	v_cvt_pk_bf16_f32 v29, v42, v43
	s_waitcnt lgkmcnt(0)
	v_mfma_f32_16x16x32_bf16 v[32:35], v[36:39], v[20:23], v[32:35]
	ds_read_b128 v[36:39], v170 offset:26240
	s_waitcnt lgkmcnt(0)
	v_mfma_f32_16x16x32_bf16 v[32:35], v[36:39], v[16:19], v[32:35]
	ds_read_b128 v[36:39], v170 offset:26304
	s_waitcnt lgkmcnt(0)
	v_mfma_f32_16x16x32_bf16 v[32:35], v[36:39], v[12:15], v[32:35]
	ds_read_b128 v[36:39], v164 offset:128
	ds_read_b128 v[40:43], v165 offset:128
	s_waitcnt lgkmcnt(0)
	v_sub_f32_e32 v40, v2, v40
	v_sub_f32_e64 v36, v36, |v40|
	v_sub_f32_e32 v40, v2, v41
	v_sub_f32_e64 v37, v37, |v40|
	v_sub_f32_e32 v36, v36, v102
	v_sub_f32_e32 v37, v37, v102
	v_mul_f32_e32 v36, 0x3fb8aa3b, v36
	v_mul_f32_e32 v37, 0x3fb8aa3b, v37
	v_exp_f32_e32 v36, v36
	v_exp_f32_e32 v37, v37
	s_nop 0
	v_pk_mul_f32 v[44:45], v[32:33], v[36:37]
	s_nop 0
	v_add_f32_e32 v32, v47, v44
	v_add_f32_e32 v36, v45, v32
	v_sub_f32_e32 v32, v2, v42
	v_sub_f32_e32 v33, v2, v43
	v_sub_f32_e64 v32, v38, |v32|
	v_sub_f32_e64 v33, v39, |v33|
	v_sub_f32_e32 v32, v32, v102
	v_sub_f32_e32 v33, v33, v102
	v_mul_f32_e32 v32, 0x3fb8aa3b, v32
	v_mul_f32_e32 v33, 0x3fb8aa3b, v33
	v_exp_f32_e32 v32, v32
	v_exp_f32_e32 v33, v33
	s_nop 0
	v_pk_mul_f32 v[80:81], v[34:35], v[32:33]
	ds_read_b128 v[32:35], v170 offset:30464
	v_add_f32_e32 v79, v80, v36
	ds_read_b128 v[36:39], v170 offset:30528
	s_waitcnt lgkmcnt(1)
	v_mfma_f32_16x16x32_bf16 v[32:35], v[32:35], v[24:27], 0
	s_waitcnt lgkmcnt(0)
	v_mfma_f32_16x16x32_bf16 v[32:35], v[36:39], v[20:23], v[32:35]
	ds_read_b128 v[36:39], v170 offset:30592
	s_waitcnt lgkmcnt(0)
	v_mfma_f32_16x16x32_bf16 v[32:35], v[36:39], v[16:19], v[32:35]
	ds_read_b128 v[36:39], v170 offset:30656
	s_waitcnt lgkmcnt(0)
	v_mfma_f32_16x16x32_bf16 v[32:35], v[36:39], v[12:15], v[32:35]
	ds_read_b128 v[36:39], v164 offset:192
	ds_read_b128 v[40:43], v165 offset:192
	s_waitcnt lgkmcnt(0)
; #define GAS __attribute__((address_space(1)))
; #define LAS __attribute__((address_space(3)))
; #define MFMA16(a, b, c) __builtin_amdgcn_mfma_f32_16x16x32_bf16((a), (b), (c), 0, 0, 0)
; __device__ __forceinline__ float fexp(float x) { return __builtin_amdgcn_exp2f(x * LOG2E); }
; __device__ __forceinline__ unsigned cvtpk(float lo, float hi) { const f32x2_t v = {lo, hi}; const bf16x2_t b = __builtin_convertvector(v, bf16x2_t); return __builtin_bit_cast(unsigned, b); }
; __device__ __forceinline__ void ml_out_unit(LAS unsigned char* lds, const MixBufs& B, int b, int h, int seg, int tid) {
;     ...
;                     const f32x4 li4 = *(const LAS f32x4*)(LI + 16 * sj + 4 * g), fc4 = *(const LAS f32x4*)(FC + 16 * sj + 4 * g);
; #pragma unroll
;                     for (int i = 0; i < 4; ++i) { p2[jj][i] = acc[i] * fexp(li4[i] - fabsf(fct - fc4[i]) - mt); dsum += p2[jj][i]; } }
;                 v4u pk; pk.x = cvtpk(p2[0][0], p2[0][1]); pk.y = cvtpk(p2[0][2], p2[0][3]); pk.z = cvtpk(p2[1][0], p2[1][1]); pk.w = cvtpk(p2[1][2], p2[1][3]);
;                 pb[ks] = __builtin_bit_cast(bf16x8, pk); }
;             dsum += __shfl_xor(dsum, 16); dsum += __shfl_xor(dsum, 32);
;             __builtin_amdgcn_sched_barrier(0);
;             u32x2 opv[8];
; #pragma unroll
;             for (int vt = 0; vt < 8; ++vt) opv[vt] = *(const GAS u32x2*)(B.PROJ + trow * NPROJ + PC_OP + h * 128 + 16 * vt + 4 * g);
;             f32x4 a1[8];
; #pragma unroll
;             for (int hv = 0; hv < 2; ++hv) {
;                 f32x4 a2[4];
; #pragma unroll
;                 for (int j = 0; j < 4; ++j) a2[j] = (f32x4){0.f, 0.f, 0.f, 0.f};
; #pragma unroll
;                 for (int kk = 0; kk < 4; ++kk)
; #pragma unroll
;                     for (int j = 0; j < 4; ++j) a2[j] = MFMA16(frag_row(CTc, GP128, 16 * (4 * hv + j), 32 * kk, lane), qf[kk], a2[j]);
; #pragma unroll
;                 for (int j = 0; j < 4; ++j) a1[4 * hv + j] = a2[j] * sc;
;                 __builtin_amdgcn_sched_barrier(0); }
	v_sub_f32_e32 v40, v2, v40
	v_sub_f32_e64 v36, v36, |v40|
	v_sub_f32_e32 v40, v2, v41
	v_sub_f32_e64 v37, v37, |v40|
	v_sub_f32_e32 v36, v36, v102
	v_sub_f32_e32 v37, v37, v102
	v_mul_f32_e32 v36, 0x3fb8aa3b, v36
	v_mul_f32_e32 v37, 0x3fb8aa3b, v37
	v_exp_f32_e32 v36, v36
	v_exp_f32_e32 v37, v37
	s_nop 0
	v_pk_mul_f32 v[96:97], v[32:33], v[36:37]
	v_sub_f32_e32 v32, v2, v42
	v_sub_f32_e32 v2, v2, v43
	v_sub_f32_e64 v32, v38, |v32|
	v_sub_f32_e64 v2, v39, |v2|
	v_sub_f32_e32 v32, v32, v102
	v_sub_f32_e32 v2, v2, v102
	v_mul_f32_e32 v32, 0x3fb8aa3b, v32
	v_mul_f32_e32 v2, 0x3fb8aa3b, v2
	v_exp_f32_e32 v32, v32
	v_exp_f32_e32 v33, v2
	v_exp_f32_e32 v2, v46
	v_pk_mul_f32 v[100:101], v[34:35], v[32:33]
	v_cvt_pk_bf16_f32 v32, v44, v45
	v_cvt_pk_bf16_f32 v33, v80, v81
	v_cvt_pk_bf16_f32 v34, v96, v97
	v_cvt_pk_bf16_f32 v35, v100, v101
	v_lshl_add_u64 v[36:37], s[88:89], 0, v[64:65]
	v_add_u32_e32 v69, s4, v170
	global_load_dwordx2 v[98:99], v[36:37], off offset:-128
	global_load_dwordx2 v[94:95], v[36:37], off offset:-96
	global_load_dwordx2 v[92:93], v[36:37], off offset:-64
	global_load_dwordx2 v[90:91], v[36:37], off offset:-32
	global_load_dwordx2 v[88:89], v[36:37], off
	global_load_dwordx2 v[86:87], v[36:37], off offset:32
	global_load_dwordx2 v[84:85], v[36:37], off offset:64
	global_load_dwordx2 v[82:83], v[36:37], off offset:96
	s_waitcnt lgkmcnt(0)
	ds_read_b128 v[214:217], v69
	ds_read_b128 v[218:221], v69 offset:4352
	ds_read_b128 v[222:225], v69 offset:8704
	ds_read_b128 v[226:229], v69 offset:13056
	ds_read_b128 v[230:233], v69 offset:64
	ds_read_b128 v[234:237], v69 offset:4416
	s_waitcnt lgkmcnt(5)
	v_mfma_f32_16x16x32_bf16 v[36:39], v[214:217], v[24:27], 0
	ds_read_b128 v[214:217], v69 offset:8768
	s_waitcnt lgkmcnt(5)
	v_mfma_f32_16x16x32_bf16 v[40:43], v[218:221], v[24:27], 0
	ds_read_b128 v[218:221], v69 offset:13120
	s_waitcnt lgkmcnt(5)
	v_mfma_f32_16x16x32_bf16 v[48:51], v[222:225], v[24:27], 0
	ds_read_b128 v[222:225], v69 offset:128
	s_waitcnt lgkmcnt(5)
	v_mfma_f32_16x16x32_bf16 v[44:47], v[226:229], v[24:27], 0
	ds_read_b128 v[226:229], v69 offset:4480
	s_waitcnt lgkmcnt(5)
	v_mfma_f32_16x16x32_bf16 v[36:39], v[230:233], v[20:23], v[36:39]
	ds_read_b128 v[230:233], v69 offset:8832
	s_waitcnt lgkmcnt(5)
	v_mfma_f32_16x16x32_bf16 v[40:43], v[234:237], v[20:23], v[40:43]
	ds_read_b128 v[234:237], v69 offset:13184
	s_waitcnt lgkmcnt(5)
	v_mfma_f32_16x16x32_bf16 v[48:51], v[214:217], v[20:23], v[48:51]
	ds_read_b128 v[214:217], v69 offset:192
	s_waitcnt lgkmcnt(5)
	v_mfma_f32_16x16x32_bf16 v[44:47], v[218:221], v[20:23], v[44:47]
	ds_read_b128 v[218:221], v69 offset:4544
	s_waitcnt lgkmcnt(5)
	v_mfma_f32_16x16x32_bf16 v[36:39], v[222:225], v[16:19], v[36:39]
	ds_read_b128 v[222:225], v69 offset:8896
	s_waitcnt lgkmcnt(5)
	v_mfma_f32_16x16x32_bf16 v[40:43], v[226:229], v[16:19], v[40:43]
	ds_read_b128 v[226:229], v69 offset:13248
	s_waitcnt lgkmcnt(5)
	v_mfma_f32_16x16x32_bf16 v[48:51], v[230:233], v[16:19], v[48:51]
	s_waitcnt lgkmcnt(4)
	v_mfma_f32_16x16x32_bf16 v[44:47], v[234:237], v[16:19], v[44:47]
	s_waitcnt lgkmcnt(3)
	v_mfma_f32_16x16x32_bf16 v[36:39], v[214:217], v[12:15], v[36:39]
	s_waitcnt lgkmcnt(2)
	v_mfma_f32_16x16x32_bf16 v[40:43], v[218:221], v[12:15], v[40:43]
	s_waitcnt lgkmcnt(1)
	v_mfma_f32_16x16x32_bf16 v[48:51], v[222:225], v[12:15], v[48:51]
	s_waitcnt lgkmcnt(0)
	v_mfma_f32_16x16x32_bf16 v[44:47], v[226:229], v[12:15], v[44:47]
	s_nop 7
	v_pk_mul_f32 v[36:37], v[2:3], v[36:37] op_sel_hi:[0,1]
	v_pk_mul_f32 v[38:39], v[2:3], v[38:39] op_sel_hi:[0,1]
	v_pk_mul_f32 v[40:41], v[2:3], v[40:41] op_sel_hi:[0,1]
	v_pk_mul_f32 v[42:43], v[2:3], v[42:43] op_sel_hi:[0,1]
	v_pk_mul_f32 v[48:49], v[2:3], v[48:49] op_sel_hi:[0,1]
	v_pk_mul_f32 v[50:51], v[2:3], v[50:51] op_sel_hi:[0,1]
	v_pk_mul_f32 v[44:45], v[2:3], v[44:45] op_sel_hi:[0,1]
	v_pk_mul_f32 v[46:47], v[2:3], v[46:47] op_sel_hi:[0,1]
	ds_read_b128 v[214:217], v69 offset:17408
	ds_read_b128 v[218:221], v69 offset:21760
	ds_read_b128 v[222:225], v69 offset:26112
	ds_read_b128 v[226:229], v69 offset:30464
	ds_read_b128 v[230:233], v69 offset:17472
	ds_read_b128 v[234:237], v69 offset:21824
	s_waitcnt lgkmcnt(5)
	v_mfma_f32_16x16x32_bf16 v[104:107], v[214:217], v[24:27], 0
	ds_read_b128 v[214:217], v69 offset:26176
	s_waitcnt lgkmcnt(5)
	v_mfma_f32_16x16x32_bf16 v[108:111], v[218:221], v[24:27], 0
	ds_read_b128 v[218:221], v69 offset:30528
	s_waitcnt lgkmcnt(5)
	v_mfma_f32_16x16x32_bf16 v[112:115], v[222:225], v[24:27], 0
	ds_read_b128 v[222:225], v69 offset:17536
	s_waitcnt lgkmcnt(5)
	v_mfma_f32_16x16x32_bf16 v[116:119], v[226:229], v[24:27], 0
	ds_read_b128 v[226:229], v69 offset:21888
	s_waitcnt lgkmcnt(5)
	v_mfma_f32_16x16x32_bf16 v[104:107], v[230:233], v[20:23], v[104:107]
	ds_read_b128 v[230:233], v69 offset:26240
	s_waitcnt lgkmcnt(5)
	v_mfma_f32_16x16x32_bf16 v[108:111], v[234:237], v[20:23], v[108:111]
	ds_read_b128 v[234:237], v69 offset:30592
	s_waitcnt lgkmcnt(5)
	v_mfma_f32_16x16x32_bf16 v[112:115], v[214:217], v[20:23], v[112:115]
	ds_read_b128 v[214:217], v69 offset:17600
	s_waitcnt lgkmcnt(5)
	v_mfma_f32_16x16x32_bf16 v[116:119], v[218:221], v[20:23], v[116:119]
	ds_read_b128 v[218:221], v69 offset:21952
	s_waitcnt lgkmcnt(5)
	v_mfma_f32_16x16x32_bf16 v[104:107], v[222:225], v[16:19], v[104:107]
	ds_read_b128 v[222:225], v69 offset:26304
	s_waitcnt lgkmcnt(5)
	v_mfma_f32_16x16x32_bf16 v[108:111], v[226:229], v[16:19], v[108:111]
	ds_read_b128 v[226:229], v69 offset:30656
	s_waitcnt lgkmcnt(5)
	v_mfma_f32_16x16x32_bf16 v[112:115], v[230:233], v[16:19], v[112:115]
	s_waitcnt lgkmcnt(4)
; #define MFMA16(a, b, c) __builtin_amdgcn_mfma_f32_16x16x32_bf16((a), (b), (c), 0, 0, 0)
; __device__ __forceinline__ float fexp(float x) { return __builtin_amdgcn_exp2f(x * LOG2E); }
; __device__ __forceinline__ float fsigmoid(float x) { return __builtin_amdgcn_rcpf(1.f + __builtin_amdgcn_exp2f(-LOG2E * x)); }
; __device__ __forceinline__ f32x4 bf4_to_f32(u32x2 w) { return (f32x4){bflo(w.x), bfhi(w.x), bflo(w.y), bfhi(w.y)}; }
; __device__ __forceinline__ void ml_out_unit(LAS unsigned char* lds, const MixBufs& B, int b, int h, int seg, int tid) {
;     ...
;                     for (int j = 0; j < 4; ++j) a2[j] = MFMA16(frag_row(CTc, GP128, 16 * (4 * hv + j), 32 * kk, lane), qf[kk], a2[j]);
; #pragma unroll
;                 for (int j = 0; j < 4; ++j) a1[4 * hv + j] = a2[j] * sc;
;                 __builtin_amdgcn_sched_barrier(0); }
; #pragma unroll
;             for (int ks = 0; ks < 2; ++ks)
; #pragma unroll
;                 for (int vt = 0; vt < 8; ++vt) a1[vt] = MFMA16(frag_tr_perm(lds + O_V, GP128, 32 * ks, 16 * vt, lane), pb[ks], a1[vt]);
;             float den = dsum + sc * qn;
;             den = fmaxf(fabsf(den), fexp(-mt));
;             const float rden = 1.f / den;
;             float s1 = 0.f, s2 = 0.f;
; #pragma unroll
;             for (int vt = 0; vt < 8; ++vt) { const f32x4 op = bf4_to_f32(opv[vt]);
; #pragma unroll
;                 for (int i = 0; i < 4; ++i) { const float x = a1[vt][i] * rden * fsigmoid(op[i]); a1[vt][i] = x; s1 += x; s2 += x * x; } }
	v_mfma_f32_16x16x32_bf16 v[116:119], v[234:237], v[16:19], v[116:119]
	s_waitcnt lgkmcnt(3)
	v_mfma_f32_16x16x32_bf16 v[104:107], v[214:217], v[12:15], v[104:107]
	s_waitcnt lgkmcnt(2)
	v_mfma_f32_16x16x32_bf16 v[108:111], v[218:221], v[12:15], v[108:111]
	s_waitcnt lgkmcnt(1)
	v_mfma_f32_16x16x32_bf16 v[112:115], v[222:225], v[12:15], v[112:115]
	s_waitcnt lgkmcnt(0)
	v_mfma_f32_16x16x32_bf16 v[116:119], v[226:229], v[12:15], v[116:119]
	s_nop 7
	v_pk_mul_f32 v[16:17], v[2:3], v[104:105] op_sel_hi:[0,1]
	v_pk_mul_f32 v[18:19], v[2:3], v[106:107] op_sel_hi:[0,1]
	v_pk_mul_f32 v[20:21], v[2:3], v[108:109] op_sel_hi:[0,1]
	v_pk_mul_f32 v[22:23], v[2:3], v[110:111] op_sel_hi:[0,1]
	v_pk_mul_f32 v[24:25], v[2:3], v[112:113] op_sel_hi:[0,1]
	v_pk_mul_f32 v[26:27], v[2:3], v[114:115] op_sel_hi:[0,1]
	v_pk_mul_f32 v[12:13], v[2:3], v[116:117] op_sel_hi:[0,1]
	v_pk_mul_f32 v[14:15], v[2:3], v[118:119] op_sel_hi:[0,1]
	ds_read_b64_tr_b16 v[104:105], v167 offset:34816
	ds_read_b64_tr_b16 v[106:107], v167 offset:39168
	ds_read_b64_tr_b16 v[110:111], v167 offset:39200
	ds_read_b64_tr_b16 v[108:109], v167 offset:34848
	ds_read_b64_tr_b16 v[112:113], v167 offset:34880
	ds_read_b64_tr_b16 v[116:117], v167 offset:34912
	ds_read_b64_tr_b16 v[114:115], v167 offset:39232
	ds_read_b64_tr_b16 v[118:119], v167 offset:39264
	s_waitcnt lgkmcnt(6)
	v_mfma_f32_16x16x32_bf16 v[36:39], v[104:107], v[28:31], v[36:39]
	v_mov_b32_e32 v73, v81
	v_mov_b32_e32 v77, v96
	v_mov_b32_e32 v75, v97
	s_waitcnt lgkmcnt(4)
	v_mfma_f32_16x16x32_bf16 v[104:107], v[108:111], v[28:31], v[40:43]
	s_nop 2
	ds_read_b64_tr_b16 v[40:41], v167 offset:34944
	ds_read_b64_tr_b16 v[42:43], v167 offset:39296
	ds_read_b64_tr_b16 v[110:111], v167 offset:39328
	v_mov_b32_e32 v71, v100
	v_mov_b32_e32 v69, v101
	s_waitcnt lgkmcnt(4)
	v_mfma_f32_16x16x32_bf16 v[48:51], v[112:115], v[28:31], v[48:51]
	s_xor_b32 s7, s7, 1
	s_add_u32 s14, s14, 0x10000
	s_addc_u32 s15, s15, 0
	s_waitcnt lgkmcnt(3)
	v_mfma_f32_16x16x32_bf16 v[44:47], v[116:119], v[28:31], v[44:47]
	ds_read_b64_tr_b16 v[108:109], v167 offset:34976
	ds_read_b64_tr_b16 v[112:113], v167 offset:35008
	ds_read_b64_tr_b16 v[116:117], v167 offset:35040
	ds_read_b64_tr_b16 v[114:115], v167 offset:39360
	ds_read_b64_tr_b16 v[118:119], v167 offset:39392
	s_add_u32 s12, s12, 64
	s_addc_u32 s13, s13, 0
	s_waitcnt lgkmcnt(6)
	v_mfma_f32_16x16x32_bf16 v[16:19], v[40:43], v[28:31], v[16:19]
	ds_read_b64_tr_b16 v[40:41], v167 offset:43520
	s_add_i32 s20, s20, 1
	s_add_i32 s26, s26, 8
	s_waitcnt lgkmcnt(5)
	v_mfma_f32_16x16x32_bf16 v[20:23], v[108:111], v[28:31], v[20:23]
	s_cmp_eq_u32 s14, 0x80000
	s_waitcnt lgkmcnt(2)
	v_mfma_f32_16x16x32_bf16 v[108:111], v[112:115], v[28:31], v[24:27]
	ds_read_b64_tr_b16 v[42:43], v167 offset:47872
	s_nop 1
	ds_read_b64_tr_b16 v[26:27], v167 offset:47904
	s_waitcnt lgkmcnt(3)
	v_mfma_f32_16x16x32_bf16 v[112:115], v[116:119], v[28:31], v[12:15]
	ds_read_b64_tr_b16 v[24:25], v167 offset:43552
	s_nop 1
	ds_read_b64_tr_b16 v[12:13], v167 offset:43584
	ds_read_b64_tr_b16 v[116:117], v167 offset:43616
	ds_read_b64_tr_b16 v[14:15], v167 offset:47936
	ds_read_b64_tr_b16 v[118:119], v167 offset:47968
	ds_read_b64_tr_b16 v[120:121], v167 offset:43648
	ds_read_b64_tr_b16 v[124:125], v167 offset:43680
	ds_read_b64_tr_b16 v[128:129], v167 offset:43712
	ds_read_b64_tr_b16 v[132:133], v167 offset:43744
	ds_read_b64_tr_b16 v[122:123], v167 offset:48000
	ds_read_b64_tr_b16 v[126:127], v167 offset:48032
	ds_read_b64_tr_b16 v[130:131], v167 offset:48064
	ds_read_b64_tr_b16 v[134:135], v167 offset:48096
	s_waitcnt lgkmcnt(14)
	v_mfma_f32_16x16x32_bf16 v[40:43], v[40:43], v[32:35], v[36:39]
	s_waitcnt lgkmcnt(9)
	v_mfma_f32_16x16x32_bf16 v[36:39], v[12:15], v[32:35], v[48:51]
	v_add_f32_e64 v12, v72, v78
	v_add_f32_e64 v13, v73, v79
	v_pk_add_f32 v[12:13], v[12:13], v[76:77]
	v_mfma_f32_16x16x32_bf16 v[28:31], v[24:27], v[32:35], v[104:107]
	s_waitcnt lgkmcnt(8)
	v_mfma_f32_16x16x32_bf16 v[24:27], v[116:119], v[32:35], v[44:47]
	s_nop 2
	v_add_f32_e64 v44, v74, v12
	v_add_f32_e64 v45, v75, v13
	s_waitcnt lgkmcnt(3)
	v_mfma_f32_16x16x32_bf16 v[12:15], v[120:123], v[32:35], v[16:19]
	s_nop 2
	v_add_f32_e64 v16, v70, v44
	v_add_f32_e64 v17, v71, v45
	v_mul_f32_e32 v44, 0xbfb8aa3b, v102
	v_pk_add_f32 v[16:17], v[68:69], v[16:17]
	ds_bpermute_b32 v18, v200, v16
	ds_bpermute_b32 v19, v200, v17
	v_exp_f32_e32 v48, v44
	s_waitcnt lgkmcnt(4)
	v_mfma_f32_16x16x32_bf16 v[20:23], v[124:127], v[32:35], v[20:23]
	s_waitcnt lgkmcnt(0)
	v_pk_add_f32 v[16:17], v[16:17], v[18:19]
	ds_bpermute_b32 v18, v199, v16
	ds_bpermute_b32 v19, v199, v17
	v_mfma_f32_16x16x32_bf16 v[44:47], v[128:131], v[32:35], v[108:111]
	s_waitcnt lgkmcnt(0)
	v_pk_add_f32 v[16:17], v[16:17], v[18:19]
	s_nop 0
	v_fmac_f32_e32 v17, v2, v16
	v_max_f32_e64 v2, |v17|, v48
	v_div_scale_f32 v48, s[4:5], v2, v2, 1.0
	v_rcp_f32_e32 v49, v48
	v_mfma_f32_16x16x32_bf16 v[16:19], v[132:135], v[32:35], v[112:115]
	s_waitcnt vmcnt(7)
	v_and_b32_e32 v35, 0xffff0000, v99
	s_brev_b32 s4, 60
	v_fma_f32 v32, -v48, v49, 1.0
	v_fmac_f32_e32 v49, v32, v49
	v_div_scale_f32 v32, vcc, 1.0, v2, 1.0
	v_mul_f32_e32 v33, v32, v49
	v_fma_f32 v34, -v48, v33, v32
	v_fmac_f32_e32 v33, v34, v49
	v_fma_f32 v32, -v48, v33, v32
	v_div_fmas_f32 v32, v32, v49, v33
	v_div_fixup_f32 v2, v32, v2, 1.0
	v_lshlrev_b32_e32 v32, 16, v98
	v_and_b32_e32 v33, 0xffff0000, v98
	v_mul_f32_e32 v32, 0xbfb8aa3b, v32
	v_exp_f32_e32 v32, v32
	v_mul_f32_e32 v33, 0xbfb8aa3b, v33
	v_exp_f32_e32 v33, v33
	v_lshlrev_b32_e32 v34, 16, v99
	v_add_f32_e32 v32, 1.0, v32
	v_rcp_f32_e32 v48, v32
	v_add_f32_e32 v32, 1.0, v33
	v_mul_f32_e32 v33, 0xbfb8aa3b, v34
	v_exp_f32_e32 v33, v33
	v_mul_f32_e32 v34, 0xbfb8aa3b, v35
	v_exp_f32_e32 v34, v34
	v_rcp_f32_e32 v49, v32
	v_add_f32_e32 v32, 1.0, v33
	v_rcp_f32_e32 v50, v32
	v_add_f32_e32 v32, 1.0, v34
	v_rcp_f32_e32 v51, v32
	s_waitcnt vmcnt(6)
; #define LAS __attribute__((address_space(3)))
; __device__ __forceinline__ float fexp(float x) { return __builtin_amdgcn_exp2f(x * LOG2E); }
; __device__ __forceinline__ float fsigmoid(float x) { return __builtin_amdgcn_rcpf(1.f + __builtin_amdgcn_exp2f(-LOG2E * x)); }
; __device__ __forceinline__ f32x4 bf4_to_f32(u32x2 w) { return (f32x4){bflo(w.x), bfhi(w.x), bflo(w.y), bfhi(w.y)}; }
; __device__ __forceinline__ void ml_out_unit(LAS unsigned char* lds, const MixBufs& B, int b, int h, int seg, int tid) {
;     ...
;             float den = dsum + sc * qn;
;             den = fmaxf(fabsf(den), fexp(-mt));
;             const float rden = 1.f / den;
;             float s1 = 0.f, s2 = 0.f;
; #pragma unroll
;             for (int vt = 0; vt < 8; ++vt) { const f32x4 op = bf4_to_f32(opv[vt]);
; #pragma unroll
;                 for (int i = 0; i < 4; ++i) { const float x = a1[vt][i] * rden * fsigmoid(op[i]); a1[vt][i] = x; s1 += x; s2 += x * x; } }
;             s1 += __shfl_xor(s1, 16); s1 += __shfl_xor(s1, 32); s2 += __shfl_xor(s2, 16); s2 += __shfl_xor(s2, 32);
;             const float mu = s1 * (1.f / 128.f), var = s2 * (1.f / 128.f) - mu * mu, rstd = 1.f / sqrtf(fmaxf(var, 0.f) + EPS);
; #pragma unroll
;             for (int vt = 0; vt < 8; ++vt) { const int cl = 16 * vt + 4 * g; const f32x4 xc = bf4_to_f32(*(const LAS u32x2*)(lds + O_XC + (16 * ti + c) * GP128 + cl * 2)), gn = *(const LAS f32x4*)(GN + cl), sk = *(const LAS f32x4*)(SK + cl);
	v_lshlrev_b32_e32 v32, 16, v94
	v_and_b32_e32 v33, 0xffff0000, v94
	v_mul_f32_e32 v32, 0xbfb8aa3b, v32
	v_exp_f32_e32 v32, v32
	v_mul_f32_e32 v33, 0xbfb8aa3b, v33
	v_exp_f32_e32 v33, v33
	v_lshlrev_b32_e32 v34, 16, v95
	v_add_f32_e32 v32, 1.0, v32
	v_and_b32_e32 v35, 0xffff0000, v95
	v_rcp_f32_e32 v68, v32
	v_add_f32_e32 v32, 1.0, v33
	v_mul_f32_e32 v33, 0xbfb8aa3b, v34
	v_exp_f32_e32 v33, v33
	v_mul_f32_e32 v34, 0xbfb8aa3b, v35
	v_exp_f32_e32 v34, v34
	v_rcp_f32_e32 v69, v32
	v_add_f32_e32 v32, 1.0, v33
	v_rcp_f32_e32 v70, v32
	v_add_f32_e32 v32, 1.0, v34
	v_rcp_f32_e32 v71, v32
	s_waitcnt vmcnt(5)
	v_lshlrev_b32_e32 v32, 16, v92
	v_and_b32_e32 v33, 0xffff0000, v92
	v_mul_f32_e32 v32, 0xbfb8aa3b, v32
	v_exp_f32_e32 v32, v32
	v_mul_f32_e32 v33, 0xbfb8aa3b, v33
	v_exp_f32_e32 v33, v33
	v_lshlrev_b32_e32 v34, 16, v93
	v_add_f32_e32 v32, 1.0, v32
	v_and_b32_e32 v35, 0xffff0000, v93
	v_rcp_f32_e32 v72, v32
	v_add_f32_e32 v32, 1.0, v33
	v_mul_f32_e32 v33, 0xbfb8aa3b, v34
	v_exp_f32_e32 v33, v33
	v_mul_f32_e32 v34, 0xbfb8aa3b, v35
	v_exp_f32_e32 v34, v34
	v_rcp_f32_e32 v73, v32
	v_add_f32_e32 v32, 1.0, v33
	v_rcp_f32_e32 v74, v32
	v_add_f32_e32 v32, 1.0, v34
	v_rcp_f32_e32 v75, v32
	s_waitcnt vmcnt(4)
	v_lshlrev_b32_e32 v32, 16, v90
	v_and_b32_e32 v33, 0xffff0000, v90
	v_mul_f32_e32 v32, 0xbfb8aa3b, v32
	v_exp_f32_e32 v32, v32
	v_mul_f32_e32 v33, 0xbfb8aa3b, v33
	v_exp_f32_e32 v33, v33
	v_lshlrev_b32_e32 v34, 16, v91
	v_add_f32_e32 v32, 1.0, v32
	v_and_b32_e32 v35, 0xffff0000, v91
	v_rcp_f32_e32 v76, v32
	v_add_f32_e32 v32, 1.0, v33
	v_mul_f32_e32 v33, 0xbfb8aa3b, v34
	v_exp_f32_e32 v33, v33
	v_mul_f32_e32 v34, 0xbfb8aa3b, v35
	v_exp_f32_e32 v34, v34
	v_rcp_f32_e32 v77, v32
	v_add_f32_e32 v32, 1.0, v33
	v_rcp_f32_e32 v78, v32
	v_add_f32_e32 v32, 1.0, v34
	v_rcp_f32_e32 v79, v32
	s_waitcnt vmcnt(3)
	v_lshlrev_b32_e32 v32, 16, v88
	v_and_b32_e32 v33, 0xffff0000, v88
	v_mul_f32_e32 v32, 0xbfb8aa3b, v32
	v_exp_f32_e32 v32, v32
	v_mul_f32_e32 v33, 0xbfb8aa3b, v33
	v_exp_f32_e32 v33, v33
	v_pk_mul_f32 v[94:95], v[2:3], v[20:21] op_sel_hi:[0,1]
	s_waitcnt vmcnt(1)
	v_lshlrev_b32_e32 v20, 16, v84
	v_lshlrev_b32_e32 v34, 16, v89
	v_add_f32_e32 v32, 1.0, v32
	v_and_b32_e32 v21, 0xffff0000, v84
	v_mul_f32_e32 v20, 0xbfb8aa3b, v20
	v_and_b32_e32 v35, 0xffff0000, v89
	v_rcp_f32_e32 v80, v32
	v_add_f32_e32 v32, 1.0, v33
	v_mul_f32_e32 v33, 0xbfb8aa3b, v34
	v_exp_f32_e32 v20, v20
	v_mul_f32_e32 v21, 0xbfb8aa3b, v21
	v_exp_f32_e32 v33, v33
	v_mul_f32_e32 v34, 0xbfb8aa3b, v35
	v_exp_f32_e32 v21, v21
	v_exp_f32_e32 v34, v34
	v_add_f32_e32 v20, 1.0, v20
	v_rcp_f32_e32 v81, v32
	v_add_f32_e32 v32, 1.0, v33
	v_pk_mul_f32 v[92:93], v[2:3], v[22:23] op_sel_hi:[0,1]
	v_lshlrev_b32_e32 v22, 16, v85
	v_rcp_f32_e32 v84, v20
	v_add_f32_e32 v20, 1.0, v21
	v_rcp_f32_e32 v88, v32
	v_add_f32_e32 v32, 1.0, v34
	v_and_b32_e32 v23, 0xffff0000, v85
	v_rcp_f32_e32 v85, v20
	v_mul_f32_e32 v20, 0xbfb8aa3b, v22
	v_rcp_f32_e32 v89, v32
	v_lshlrev_b32_e32 v32, 16, v86
	v_exp_f32_e32 v20, v20
	v_mul_f32_e32 v21, 0xbfb8aa3b, v23
	v_and_b32_e32 v33, 0xffff0000, v86
	v_mul_f32_e32 v32, 0xbfb8aa3b, v32
	v_exp_f32_e32 v21, v21
	v_exp_f32_e32 v32, v32
	v_mul_f32_e32 v33, 0xbfb8aa3b, v33
	v_exp_f32_e32 v33, v33
	v_add_f32_e32 v20, 1.0, v20
	v_rcp_f32_e32 v98, v20
	v_add_f32_e32 v20, 1.0, v21
	v_lshlrev_b32_e32 v34, 16, v87
	v_add_f32_e32 v32, 1.0, v32
	v_rcp_f32_e32 v99, v20
	s_waitcnt vmcnt(0)
	v_lshlrev_b32_e32 v20, 16, v82
	v_lshlrev_b32_e32 v22, 16, v83
	v_and_b32_e32 v35, 0xffff0000, v87
	v_rcp_f32_e32 v86, v32
	v_add_f32_e32 v32, 1.0, v33
	v_mul_f32_e32 v33, 0xbfb8aa3b, v34
	v_and_b32_e32 v21, 0xffff0000, v82
	v_mul_f32_e32 v20, 0xbfb8aa3b, v20
	v_and_b32_e32 v23, 0xffff0000, v83
	v_pk_mul_f32 v[102:103], v[2:3], v[16:17] op_sel_hi:[0,1]
	v_mul_f32_e32 v16, 0xbfb8aa3b, v22
	v_exp_f32_e32 v33, v33
	v_mul_f32_e32 v34, 0xbfb8aa3b, v35
	v_exp_f32_e32 v20, v20
	v_mul_f32_e32 v21, 0xbfb8aa3b, v21
	v_exp_f32_e32 v16, v16
	v_mul_f32_e32 v17, 0xbfb8aa3b, v23
	v_exp_f32_e32 v34, v34
	v_exp_f32_e32 v21, v21
	v_exp_f32_e32 v17, v17
	v_rcp_f32_e32 v87, v32
	v_add_f32_e32 v32, 1.0, v33
	v_add_f32_e32 v20, 1.0, v20
	v_add_f32_e32 v16, 1.0, v16
	v_rcp_f32_e32 v90, v32
	v_add_f32_e32 v32, 1.0, v34
	v_rcp_f32_e32 v82, v20
	v_add_f32_e32 v20, 1.0, v21
	v_rcp_f32_e32 v104, v16
	v_add_f32_e32 v16, 1.0, v17
	v_rcp_f32_e32 v91, v32
	v_rcp_f32_e32 v83, v20
	v_rcp_f32_e32 v105, v16
	v_pk_mul_f32 v[106:107], v[2:3], v[18:19] op_sel_hi:[0,1]
	ds_read_b64 v[32:33], v168 offset:52224
	ds_read_b128 v[16:19], v171
	ds_read_b128 v[20:23], v172
	v_pk_mul_f32 v[114:115], v[2:3], v[40:41] op_sel_hi:[0,1]
	v_pk_mul_f32 v[40:41], v[48:49], v[114:115]
	v_pk_mul_f32 v[108:109], v[2:3], v[42:43] op_sel_hi:[0,1]
	s_waitcnt lgkmcnt(2)
	v_lshlrev_b32_e32 v112, 16, v33
	v_and_b32_e32 v113, 0xffff0000, v33
	v_add_f32_e32 v33, 0, v40
	v_pk_mul_f32 v[96:97], v[2:3], v[44:45] op_sel_hi:[0,1]
	v_pk_mul_f32 v[34:35], v[50:51], v[108:109]
	ds_read_b64 v[44:45], v169 offset:52224
	ds_read_b64 v[202:203], v192 offset:52224
	ds_read_b64 v[204:205], v193 offset:52224
	v_add_f32_e32 v33, v41, v33
	v_mul_f32_e32 v42, v41, v41
	v_pk_fma_f32 v[40:41], v[40:41], v[40:41], v[42:43] op_sel_hi:[1,1,0]
	v_add_f32_e32 v42, v34, v33
	v_pk_mul_f32 v[122:123], v[2:3], v[28:29] op_sel_hi:[0,1]
	v_lshlrev_b32_e32 v120, 16, v32
	v_and_b32_e32 v121, 0xffff0000, v32
	v_pk_fma_f32 v[32:33], v[34:35], v[34:35], v[40:41]
	v_add_f32_e32 v124, v35, v42
	v_mul_f32_e32 v34, v35, v35
	v_pk_mul_f32 v[28:29], v[68:69], v[122:123]
	v_pk_mul_f32 v[100:101], v[2:3], v[46:47] op_sel_hi:[0,1]
	v_pk_add_f32 v[46:47], v[34:35], v[32:33] op_sel_hi:[0,1]
	v_pk_mul_f32 v[118:119], v[2:3], v[30:31] op_sel_hi:[0,1]
	s_waitcnt lgkmcnt(2)
; #define LAS __attribute__((address_space(3)))
; __device__ __forceinline__ float fsigmoid(float x) { return __builtin_amdgcn_rcpf(1.f + __builtin_amdgcn_exp2f(-LOG2E * x)); }
; __device__ __forceinline__ f32x4 bf4_to_f32(u32x2 w) { return (f32x4){bflo(w.x), bfhi(w.x), bflo(w.y), bfhi(w.y)}; }
; __device__ __forceinline__ void ml_out_unit(LAS unsigned char* lds, const MixBufs& B, int b, int h, int seg, int tid) {
;     ...
; #pragma unroll
;             for (int vt = 0; vt < 8; ++vt) { const f32x4 op = bf4_to_f32(opv[vt]);
; #pragma unroll
;                 for (int i = 0; i < 4; ++i) { const float x = a1[vt][i] * rden * fsigmoid(op[i]); a1[vt][i] = x; s1 += x; s2 += x * x; } }
;             s1 += __shfl_xor(s1, 16); s1 += __shfl_xor(s1, 32); s2 += __shfl_xor(s2, 16); s2 += __shfl_xor(s2, 32);
;             const float mu = s1 * (1.f / 128.f), var = s2 * (1.f / 128.f) - mu * mu, rstd = 1.f / sqrtf(fmaxf(var, 0.f) + EPS);
; #pragma unroll
;             for (int vt = 0; vt < 8; ++vt) { const int cl = 16 * vt + 4 * g; const f32x4 xc = bf4_to_f32(*(const LAS u32x2*)(lds + O_XC + (16 * ti + c) * GP128 + cl * 2)), gn = *(const LAS f32x4*)(GN + cl), sk = *(const LAS f32x4*)(SK + cl);
	v_lshlrev_b32_e32 v116, 16, v45
	v_and_b32_e32 v117, 0xffff0000, v45
	v_add_f32_e32 v45, v28, v124
	v_pk_mul_f32 v[30:31], v[70:71], v[118:119]
	v_pk_fma_f32 v[46:47], v[28:29], v[28:29], v[46:47]
	v_add_f32_e32 v45, v29, v45
	v_mul_f32_e32 v28, v29, v29
	v_pk_add_f32 v[28:29], v[28:29], v[46:47] op_sel_hi:[0,1]
	v_lshlrev_b32_e32 v126, 16, v44
	v_and_b32_e32 v127, 0xffff0000, v44
	v_add_f32_e32 v44, v30, v45
	v_pk_mul_f32 v[36:37], v[2:3], v[36:37] op_sel_hi:[0,1]
	v_pk_fma_f32 v[28:29], v[30:31], v[30:31], v[28:29]
	v_add_f32_e32 v186, v31, v44
	v_mul_f32_e32 v30, v31, v31
	v_pk_mul_f32 v[210:211], v[72:73], v[36:37]
	v_pk_add_f32 v[128:129], v[30:31], v[28:29] op_sel_hi:[0,1]
	v_pk_mul_f32 v[124:125], v[2:3], v[38:39] op_sel_hi:[0,1]
	v_add_f32_e32 v186, v210, v186
	v_pk_mul_f32 v[208:209], v[74:75], v[124:125]
	v_pk_fma_f32 v[128:129], v[210:211], v[210:211], v[128:129]
	v_add_f32_e32 v201, v211, v186
	v_mul_f32_e32 v186, v211, v211
	v_pk_add_f32 v[210:211], v[186:187], v[128:129] op_sel_hi:[0,1]
	v_add_f32_e32 v186, v208, v201
	v_pk_mul_f32 v[24:25], v[2:3], v[24:25] op_sel_hi:[0,1]
	s_waitcnt lgkmcnt(1)
	v_lshlrev_b32_e32 v38, 16, v203
	v_and_b32_e32 v39, 0xffff0000, v203
	v_lshlrev_b32_e32 v128, 16, v202
	v_and_b32_e32 v129, 0xffff0000, v202
	v_pk_fma_f32 v[202:203], v[208:209], v[208:209], v[210:211]
	v_add_f32_e32 v201, v209, v186
	v_mul_f32_e32 v186, v209, v209
	v_pk_mul_f32 v[210:211], v[76:77], v[24:25]
	v_pk_add_f32 v[202:203], v[186:187], v[202:203] op_sel_hi:[0,1]
	v_pk_mul_f32 v[26:27], v[2:3], v[26:27] op_sel_hi:[0,1]
	v_add_f32_e32 v186, v210, v201
	v_pk_mul_f32 v[208:209], v[78:79], v[26:27]
	v_pk_fma_f32 v[202:203], v[210:211], v[210:211], v[202:203]
	v_add_f32_e32 v201, v211, v186
	v_mul_f32_e32 v186, v211, v211
	v_pk_add_f32 v[202:203], v[186:187], v[202:203] op_sel_hi:[0,1]
	v_add_f32_e32 v186, v208, v201
	v_pk_mul_f32 v[12:13], v[2:3], v[12:13] op_sel_hi:[0,1]
	v_pk_fma_f32 v[202:203], v[208:209], v[208:209], v[202:203]
	v_add_f32_e32 v201, v209, v186
	v_mul_f32_e32 v186, v209, v209
	v_pk_mul_f32 v[212:213], v[80:81], v[12:13]
	v_pk_add_f32 v[202:203], v[186:187], v[202:203] op_sel_hi:[0,1]
	v_pk_mul_f32 v[14:15], v[2:3], v[14:15] op_sel_hi:[0,1]
	v_add_f32_e32 v2, v212, v201
	v_pk_mul_f32 v[208:209], v[88:89], v[14:15]
	v_pk_fma_f32 v[202:203], v[212:213], v[212:213], v[202:203]
	v_add_f32_e32 v186, v213, v2
	v_mul_f32_e32 v2, v213, v213
	v_pk_add_f32 v[202:203], v[2:3], v[202:203] op_sel_hi:[0,1]
	v_add_f32_e32 v2, v208, v186
	v_pk_mul_f32 v[130:131], v[86:87], v[94:95]
	v_pk_fma_f32 v[202:203], v[208:209], v[208:209], v[202:203]
	v_add_f32_e32 v186, v209, v2
	v_mul_f32_e32 v2, v209, v209
	v_mov_b32_e32 v210, v130
	v_mov_b32_e32 v211, v209
	v_pk_add_f32 v[202:203], v[2:3], v[202:203] op_sel_hi:[0,1]
	v_add_f32_e32 v2, v130, v186
	v_pk_mul_f32 v[132:133], v[90:91], v[92:93]
	v_pk_fma_f32 v[202:203], v[210:211], v[210:211], v[202:203]
	v_add_f32_e32 v186, v131, v2
	v_mul_f32_e32 v2, v131, v131
	v_mov_b32_e32 v134, v132
	v_mov_b32_e32 v135, v131
	v_pk_add_f32 v[130:131], v[2:3], v[202:203] op_sel_hi:[0,1]
	v_add_f32_e32 v2, v132, v186
	v_pk_mul_f32 v[136:137], v[84:85], v[96:97]
	v_pk_fma_f32 v[130:131], v[134:135], v[134:135], v[130:131]
	v_add_f32_e32 v132, v133, v2
	v_mul_f32_e32 v2, v133, v133
	v_mov_b32_e32 v140, v136
	v_mov_b32_e32 v141, v133
	v_pk_add_f32 v[130:131], v[2:3], v[130:131] op_sel_hi:[0,1]
	v_add_f32_e32 v2, v136, v132
	v_pk_mul_f32 v[138:139], v[98:99], v[100:101]
	v_pk_fma_f32 v[130:131], v[140:141], v[140:141], v[130:131]
	v_add_f32_e32 v132, v137, v2
	v_mul_f32_e32 v2, v137, v137
	v_mov_b32_e32 v142, v138
	v_mov_b32_e32 v143, v137
	v_pk_add_f32 v[130:131], v[2:3], v[130:131] op_sel_hi:[0,1]
	v_add_f32_e32 v2, v138, v132
	v_pk_mul_f32 v[144:145], v[82:83], v[102:103]
	v_pk_fma_f32 v[130:131], v[142:143], v[142:143], v[130:131]
	v_add_f32_e32 v132, v139, v2
	v_mul_f32_e32 v2, v139, v139
	v_mov_b32_e32 v148, v144
	v_mov_b32_e32 v149, v139
	v_pk_add_f32 v[130:131], v[2:3], v[130:131] op_sel_hi:[0,1]
	v_add_f32_e32 v2, v144, v132
	v_pk_mul_f32 v[146:147], v[104:105], v[106:107]
	v_pk_fma_f32 v[130:131], v[148:149], v[148:149], v[130:131]
	v_add_f32_e32 v132, v145, v2
	v_mul_f32_e32 v2, v145, v145
	v_mov_b32_e32 v150, v146
	v_mov_b32_e32 v151, v145
	v_pk_add_f32 v[130:131], v[2:3], v[130:131] op_sel_hi:[0,1]
	v_pk_fma_f32 v[130:131], v[150:151], v[150:151], v[130:131]
	v_mul_f32_e32 v206, v147, v147
	v_add_f32_e32 v207, v146, v132
	v_mov_b32_e32 v131, v147
	v_pk_add_f32 v[130:131], v[130:131], v[206:207]
	ds_bpermute_b32 v141, v200, v131
	ds_bpermute_b32 v140, v200, v130
	ds_read_b128 v[32:35], v173
	ds_read_b128 v[40:43], v174
	ds_read_b128 v[28:31], v175
	ds_read_b128 v[44:47], v176
	ds_read_b128 v[132:135], v177
	ds_read_b128 v[136:139], v178
	v_lshl_add_u64 v[110:111], s[88:89], 0, v[66:67]
	s_waitcnt lgkmcnt(6)
	v_pk_add_f32 v[130:131], v[130:131], v[140:141]
	ds_bpermute_b32 v201, v199, v131
	ds_bpermute_b32 v200, v199, v130
	ds_read_b64 v[202:203], v194 offset:52224
	ds_read_b128 v[140:143], v179
	ds_read_b128 v[144:147], v180
	v_lshlrev_b32_e32 v148, 16, v205
	v_and_b32_e32 v149, 0xffff0000, v205
	s_waitcnt lgkmcnt(2)
; #define GAS __attribute__((address_space(1)))
; #define LAS __attribute__((address_space(3)))
; __device__ __forceinline__ float fsigmoid(float x) { return __builtin_amdgcn_rcpf(1.f + __builtin_amdgcn_exp2f(-LOG2E * x)); }
; __device__ __forceinline__ f32x4 bf4_to_f32(u32x2 w) { return (f32x4){bflo(w.x), bfhi(w.x), bflo(w.y), bfhi(w.y)}; }
; __device__ __forceinline__ u32x2 f32_to_bf4(f32x4 v) { u32x2 w; w.x = cvtpk(v[0], v[1]); w.y = cvtpk(v[2], v[3]); return w; }
; __device__ __forceinline__ void ml_out_unit(LAS unsigned char* lds, const MixBufs& B, int b, int h, int seg, int tid) {
;     ...
;                 for (int i = 0; i < 4; ++i) { const float x = a1[vt][i] * rden * fsigmoid(op[i]); a1[vt][i] = x; s1 += x; s2 += x * x; } }
;             s1 += __shfl_xor(s1, 16); s1 += __shfl_xor(s1, 32); s2 += __shfl_xor(s2, 16); s2 += __shfl_xor(s2, 32);
;             const float mu = s1 * (1.f / 128.f), var = s2 * (1.f / 128.f) - mu * mu, rstd = 1.f / sqrtf(fmaxf(var, 0.f) + EPS);
; #pragma unroll
;             for (int vt = 0; vt < 8; ++vt) { const int cl = 16 * vt + 4 * g; const f32x4 xc = bf4_to_f32(*(const LAS u32x2*)(lds + O_XC + (16 * ti + c) * GP128 + cl * 2)), gn = *(const LAS f32x4*)(GN + cl), sk = *(const LAS f32x4*)(SK + cl);
;                 f32x4 r;
; #pragma unroll
;                 for (int i = 0; i < 4; ++i) r[i] = (a1[vt][i] - mu) * rstd * gn[i] + sk[i] * xc[i];
;                 *(GAS u32x2*)(B.A_b + trow * 1024 + h * 128 + cl) = f32_to_bf4(r); }
	v_lshlrev_b32_e32 v210, 16, v202
	v_pk_add_f32 v[130:131], v[130:131], v[200:201]
	v_and_b32_e32 v211, 0xffff0000, v202
	v_pk_mul_f32 v[130:131], v[130:131], s[4:5] op_sel_hi:[1,0]
	v_lshlrev_b32_e32 v208, 16, v203
	v_fma_f32 v2, -v131, v131, v130
	v_max_f32_e32 v2, 0, v2
	v_add_f32_e32 v2, 0x358637bd, v2
	v_mul_f32_e32 v186, 0x4f800000, v2
	v_cmp_gt_f32_e32 vcc, s68, v2
	v_pk_fma_f32 v[48:49], v[48:49], v[114:115], v[130:131] op_sel:[0,0,1] neg_lo:[0,0,1] neg_hi:[0,0,1]
	v_lshlrev_b32_e32 v150, 16, v204
	v_cndmask_b32_e32 v2, v2, v186, vcc
	v_sqrt_f32_e32 v186, v2
	v_and_b32_e32 v151, 0xffff0000, v204
	ds_read_b64 v[200:201], v195 offset:52224
	ds_read_b64 v[204:205], v196 offset:52224
	ds_read_b64 v[206:207], v197 offset:52224
	v_pk_fma_f32 v[12:13], v[80:81], v[12:13], v[130:131] op_sel:[0,0,1] neg_lo:[0,0,1] neg_hi:[0,0,1]
	v_add_u32_e32 v199, -1, v186
	v_fma_f32 v209, -v199, v186, v2
	v_cmp_ge_f32_e64 s[4:5], 0, v209
	v_add_u32_e32 v209, 1, v186
	v_pk_fma_f32 v[14:15], v[88:89], v[14:15], v[130:131] op_sel:[0,0,1] neg_lo:[0,0,1] neg_hi:[0,0,1]
	v_cndmask_b32_e64 v199, v186, v199, s[4:5]
	v_fma_f32 v186, -v209, v186, v2
	v_cmp_lt_f32_e64 s[4:5], 0, v186
	s_nop 1
	v_cndmask_b32_e64 v186, v199, v209, s[4:5]
	v_mul_f32_e32 v199, 0x37800000, v186
	v_cndmask_b32_e32 v186, v186, v199, vcc
	v_cmp_class_f32_e32 vcc, v2, v1
	v_and_b32_e32 v209, 0xffff0000, v203
	s_nop 0
	v_cndmask_b32_e32 v2, v186, v2, vcc
	v_div_scale_f32 v186, s[4:5], v2, v2, 1.0
	v_rcp_f32_e32 v199, v186
	s_mov_b64 s[4:5], 0x400
	v_lshl_add_u64 v[60:61], v[60:61], 0, s[4:5]
	s_mov_b64 s[4:5], 0x98000
	v_fma_f32 v202, -v186, v199, 1.0
	v_fmac_f32_e32 v199, v202, v199
	v_div_scale_f32 v202, vcc, 1.0, v2, 1.0
	v_mul_f32_e32 v203, v202, v199
	v_fma_f32 v212, -v186, v203, v202
	v_fmac_f32_e32 v203, v212, v199
	v_fma_f32 v186, -v186, v203, v202
	v_div_fmas_f32 v186, v186, v199, v203
	v_div_fixup_f32 v2, v186, v2, 1.0
	v_pk_mul_f32 v[48:49], v[48:49], v[2:3] op_sel_hi:[1,0]
	v_pk_mul_f32 v[12:13], v[12:13], v[2:3] op_sel_hi:[1,0]
	v_pk_mul_f32 v[16:17], v[16:17], v[48:49]
	v_pk_mul_f32 v[14:15], v[14:15], v[2:3] op_sel_hi:[1,0]
	v_pk_fma_f32 v[16:17], v[20:21], v[120:121], v[16:17]
	v_pk_fma_f32 v[20:21], v[50:51], v[108:109], v[130:131] op_sel:[0,0,1] neg_lo:[0,0,1] neg_hi:[0,0,1]
	v_cvt_pk_bf16_f32 v16, v16, v17
	v_pk_mul_f32 v[20:21], v[20:21], v[2:3] op_sel_hi:[1,0]
	s_waitcnt lgkmcnt(4)
	v_pk_mul_f32 v[12:13], v[140:141], v[12:13]
	v_pk_mul_f32 v[18:19], v[18:19], v[20:21]
	v_pk_mul_f32 v[14:15], v[142:143], v[14:15]
	v_pk_fma_f32 v[18:19], v[22:23], v[112:113], v[18:19]
	s_waitcnt lgkmcnt(3)
	v_pk_fma_f32 v[12:13], v[144:145], v[210:211], v[12:13]
	v_cvt_pk_bf16_f32 v17, v18, v19
	global_store_dwordx2 v[110:111], v[16:17], off offset:-128 sc1
	v_pk_fma_f32 v[16:17], v[68:69], v[122:123], v[130:131] op_sel:[0,0,1] neg_lo:[0,0,1] neg_hi:[0,0,1]
	v_pk_fma_f32 v[18:19], v[70:71], v[118:119], v[130:131] op_sel:[0,0,1] neg_lo:[0,0,1] neg_hi:[0,0,1]
	v_pk_mul_f32 v[16:17], v[16:17], v[2:3] op_sel_hi:[1,0]
	v_pk_mul_f32 v[18:19], v[18:19], v[2:3] op_sel_hi:[1,0]
	v_pk_mul_f32 v[16:17], v[32:33], v[16:17]
	v_pk_mul_f32 v[18:19], v[34:35], v[18:19]
	v_pk_fma_f32 v[16:17], v[40:41], v[126:127], v[16:17]
	v_pk_fma_f32 v[18:19], v[42:43], v[116:117], v[18:19]
	v_cvt_pk_bf16_f32 v16, v16, v17
	v_cvt_pk_bf16_f32 v17, v18, v19
	global_store_dwordx2 v[110:111], v[16:17], off offset:-96 sc1
	v_pk_fma_f32 v[16:17], v[72:73], v[36:37], v[130:131] op_sel:[0,0,1] neg_lo:[0,0,1] neg_hi:[0,0,1]
	v_pk_fma_f32 v[18:19], v[74:75], v[124:125], v[130:131] op_sel:[0,0,1] neg_lo:[0,0,1] neg_hi:[0,0,1]
	v_pk_mul_f32 v[16:17], v[16:17], v[2:3] op_sel_hi:[1,0]
	v_pk_mul_f32 v[18:19], v[18:19], v[2:3] op_sel_hi:[1,0]
	v_pk_mul_f32 v[16:17], v[28:29], v[16:17]
	v_pk_mul_f32 v[18:19], v[30:31], v[18:19]
	v_pk_fma_f32 v[16:17], v[44:45], v[128:129], v[16:17]
	v_pk_fma_f32 v[18:19], v[46:47], v[38:39], v[18:19]
	v_cvt_pk_bf16_f32 v16, v16, v17
	v_cvt_pk_bf16_f32 v17, v18, v19
	global_store_dwordx2 v[110:111], v[16:17], off offset:-64 sc1
	v_pk_fma_f32 v[16:17], v[76:77], v[24:25], v[130:131] op_sel:[0,0,1] neg_lo:[0,0,1] neg_hi:[0,0,1]
	v_pk_fma_f32 v[18:19], v[78:79], v[26:27], v[130:131] op_sel:[0,0,1] neg_lo:[0,0,1] neg_hi:[0,0,1]
	v_pk_mul_f32 v[16:17], v[16:17], v[2:3] op_sel_hi:[1,0]
	v_pk_mul_f32 v[18:19], v[18:19], v[2:3] op_sel_hi:[1,0]
	v_pk_mul_f32 v[16:17], v[132:133], v[16:17]
	v_pk_mul_f32 v[18:19], v[134:135], v[18:19]
	v_pk_fma_f32 v[16:17], v[136:137], v[150:151], v[16:17]
	v_pk_fma_f32 v[18:19], v[138:139], v[148:149], v[18:19]
	v_pk_fma_f32 v[14:15], v[146:147], v[208:209], v[14:15]
	v_cvt_pk_bf16_f32 v16, v16, v17
	v_cvt_pk_bf16_f32 v17, v18, v19
	v_cvt_pk_bf16_f32 v12, v12, v13
	v_cvt_pk_bf16_f32 v13, v14, v15
	global_store_dwordx2 v[110:111], v[16:17], off offset:-32 sc1
	global_store_dwordx2 v[110:111], v[12:13], off sc1
	ds_read_b128 v[12:15], v181
	ds_read_b128 v[16:19], v187
	s_waitcnt lgkmcnt(4)
; #define GAS __attribute__((address_space(1)))
; #define LAS __attribute__((address_space(3)))
; __device__ __forceinline__ f32x4 bf4_to_f32(u32x2 w) { return (f32x4){bflo(w.x), bfhi(w.x), bflo(w.y), bfhi(w.y)}; }
; __device__ __forceinline__ u32x2 f32_to_bf4(f32x4 v) { u32x2 w; w.x = cvtpk(v[0], v[1]); w.y = cvtpk(v[2], v[3]); return w; }
; __device__ __forceinline__ void ml_out_unit(LAS unsigned char* lds, const MixBufs& B, int b, int h, int seg, int tid) {
;     ...
; #pragma unroll
;             for (int vt = 0; vt < 8; ++vt) { const int cl = 16 * vt + 4 * g; const f32x4 xc = bf4_to_f32(*(const LAS u32x2*)(lds + O_XC + (16 * ti + c) * GP128 + cl * 2)), gn = *(const LAS f32x4*)(GN + cl), sk = *(const LAS f32x4*)(SK + cl);
;                 f32x4 r;
; #pragma unroll
;                 for (int i = 0; i < 4; ++i) r[i] = (a1[vt][i] - mu) * rstd * gn[i] + sk[i] * xc[i];
;                 *(GAS u32x2*)(B.A_b + trow * 1024 + h * 128 + cl) = f32_to_bf4(r); }
;             m = mn;
;             __syncthreads();
	v_lshlrev_b32_e32 v20, 16, v200
	v_and_b32_e32 v21, 0xffff0000, v200
	v_pk_fma_f32 v[22:23], v[86:87], v[94:95], v[130:131] op_sel:[0,0,1] neg_lo:[0,0,1] neg_hi:[0,0,1]
	v_lshl_add_u64 v[64:65], v[64:65], 0, s[4:5]
	v_pk_mul_f32 v[22:23], v[22:23], v[2:3] op_sel_hi:[1,0]
	s_waitcnt lgkmcnt(0)
	v_pk_mul_f32 v[16:17], v[16:17], v[20:21]
	v_pk_fma_f32 v[20:21], v[90:91], v[92:93], v[130:131] op_sel:[0,0,1] neg_lo:[0,0,1] neg_hi:[0,0,1]
	v_pk_fma_f32 v[12:13], v[22:23], v[12:13], v[16:17]
	v_lshlrev_b32_e32 v16, 16, v201
	v_and_b32_e32 v17, 0xffff0000, v201
	v_pk_mul_f32 v[20:21], v[20:21], v[2:3] op_sel_hi:[1,0]
	v_pk_mul_f32 v[16:17], v[18:19], v[16:17]
	v_cvt_pk_bf16_f32 v12, v12, v13
	v_pk_fma_f32 v[14:15], v[20:21], v[14:15], v[16:17]
	v_lshlrev_b32_e32 v20, 16, v204
	v_cvt_pk_bf16_f32 v13, v14, v15
	global_store_dwordx2 v[110:111], v[12:13], off offset:32 sc1
	ds_read_b128 v[12:15], v188
	ds_read_b128 v[16:19], v189
	v_and_b32_e32 v21, 0xffff0000, v204
	v_pk_fma_f32 v[22:23], v[84:85], v[96:97], v[130:131] op_sel:[0,0,1] neg_lo:[0,0,1] neg_hi:[0,0,1]
	s_mov_b64 s[4:5], 0x20000
	v_pk_mul_f32 v[22:23], v[22:23], v[2:3] op_sel_hi:[1,0]
	s_waitcnt lgkmcnt(0)
	v_pk_mul_f32 v[16:17], v[16:17], v[20:21]
	v_pk_fma_f32 v[20:21], v[98:99], v[100:101], v[130:131] op_sel:[0,0,1] neg_lo:[0,0,1] neg_hi:[0,0,1]
	v_pk_fma_f32 v[12:13], v[22:23], v[12:13], v[16:17]
	v_lshlrev_b32_e32 v16, 16, v205
	v_and_b32_e32 v17, 0xffff0000, v205
	v_pk_mul_f32 v[20:21], v[20:21], v[2:3] op_sel_hi:[1,0]
	v_pk_mul_f32 v[16:17], v[18:19], v[16:17]
	v_cvt_pk_bf16_f32 v12, v12, v13
	v_pk_fma_f32 v[14:15], v[20:21], v[14:15], v[16:17]
	v_lshlrev_b32_e32 v20, 16, v206
	v_cvt_pk_bf16_f32 v13, v14, v15
	global_store_dwordx2 v[110:111], v[12:13], off offset:64 sc1
	ds_read_b128 v[12:15], v190
	ds_read_b128 v[16:19], v191
	v_and_b32_e32 v21, 0xffff0000, v206
	v_pk_fma_f32 v[22:23], v[82:83], v[102:103], v[130:131] op_sel:[0,0,1] neg_lo:[0,0,1] neg_hi:[0,0,1]
	v_lshl_add_u64 v[66:67], v[66:67], 0, s[4:5]
	v_pk_mul_f32 v[22:23], v[22:23], v[2:3] op_sel_hi:[1,0]
	s_waitcnt lgkmcnt(0)
	v_pk_mul_f32 v[16:17], v[16:17], v[20:21]
	v_pk_fma_f32 v[20:21], v[104:105], v[106:107], v[130:131] op_sel:[0,0,1] neg_lo:[0,0,1] neg_hi:[0,0,1]
	v_pk_fma_f32 v[12:13], v[22:23], v[12:13], v[16:17]
	v_lshlrev_b32_e32 v16, 16, v207
	v_and_b32_e32 v17, 0xffff0000, v207
	v_pk_mul_f32 v[20:21], v[20:21], v[2:3] op_sel_hi:[1,0]
	v_pk_mul_f32 v[16:17], v[18:19], v[16:17]
	v_cvt_pk_bf16_f32 v12, v12, v13
	v_pk_fma_f32 v[14:15], v[20:21], v[14:15], v[16:17]
	v_mov_b32_e32 v186, v198
	v_cvt_pk_bf16_f32 v13, v14, v15
	global_store_dwordx2 v[110:111], v[12:13], off offset:96 sc1
	s_barrier
	s_cbranch_scc1 .LBB0_678

; #define GAS __attribute__((address_space(1)))
; #define LAS __attribute__((address_space(3)))
; __device__ __forceinline__ float fsigmoid(float x) { return __builtin_amdgcn_rcpf(1.f + __builtin_amdgcn_exp2f(-LOG2E * x)); }
; __device__ __forceinline__ f32x4 bf4_to_f32(u32x2 w) { return (f32x4){bflo(w.x), bfhi(w.x), bflo(w.y), bfhi(w.y)}; }
; __device__ __forceinline__ u32x2 f32_to_bf4(f32x4 v) { u32x2 w; w.x = cvtpk(v[0], v[1]); w.y = cvtpk(v[2], v[3]); return w; }
; template <bool FULL> __device__ __forceinline__ void gla_unit(LAS unsigned char* lds, const MixBufs& B, int b, int h, int seg, int tid) {
;     ...
;             const float rstd = 1.f / sqrtf((SSQ[16 * ti + c] + SSQ[64 + 16 * ti + c]) * (1.f / 128.f) + EPS);
; #pragma unroll
;             for (int j = 0; j < 4; ++j) { const f32x4 gg = bf4_to_f32(gv[j]), gnj = *(const LAS f32x4*)(GNL + 16 * (4 * vh + j) + 4 * g);
;                 f32x4 r;
; #pragma unroll
;                 for (int i = 0; i < 4; ++i) r[i] = o[j][i] * rstd * gnj[i] * (gg[i] * fsigmoid(gg[i]));
;                 *(GAS u32x2*)(B.A_a + trow * 1024 + h * 128 + 16 * (4 * vh + j) + 4 * g) = f32_to_bf4(r); }
.LBB0_719:
	s_or_b64 exec, exec, s[34:35]
	s_waitcnt lgkmcnt(0)
	s_barrier
	ds_read2st64_b32 v[212:213], v191 offset1:1
	v_lshlrev_b32_e32 v133, 2, v176
	v_and_or_b32 v133, v133, 12, s79
	v_lshlrev_b32_e32 v153, 1, v133
	s_or_b32 s34, s79, s73
	s_waitcnt lgkmcnt(0)
	v_add_f32_e32 v133, v212, v213
	v_fmamk_f32 v133, v133, 0x3c000000, v182
	v_cmp_gt_f32_e32 vcc, s68, v133
	v_mul_f32_e32 v143, 0x4f800000, v133
	s_or_b32 s73, s90, s34
	v_cndmask_b32_e32 v133, v133, v143, vcc
	v_sqrt_f32_e32 v143, v133
	s_lshl_b32 s34, s60, 2
	s_add_i32 s58, s34, 0
	s_waitcnt vmcnt(30)
	v_lshlrev_b32_e32 v216, 16, v174
	v_add_u32_e32 v176, -1, v143
	v_fma_f32 v203, -v176, v143, v133
	v_cmp_ge_f32_e64 s[34:35], 0, v203
	v_add_u32_e32 v203, 1, v143
	v_and_b32_e32 v217, 0xffff0000, v174
	v_cndmask_b32_e64 v176, v143, v176, s[34:35]
	v_fma_f32 v143, -v203, v143, v133
	v_cmp_lt_f32_e64 s[34:35], 0, v143
	v_mov_b32_e32 v211, s91
	v_or_b32_e32 v210, s73, v177
	v_cndmask_b32_e64 v143, v176, v203, s[34:35]
	v_mul_f32_e32 v176, 0x37800000, v143
	v_cndmask_b32_e32 v143, v143, v176, vcc
	v_cmp_class_f32_e32 vcc, v133, v1
	v_lshlrev_b32_e32 v174, 16, v175
	v_lshlrev_b64 v[214:215], 11, v[210:211]
	v_cndmask_b32_e32 v133, v143, v133, vcc
	v_div_scale_f32 v143, s[34:35], v133, v133, 1.0
	v_rcp_f32_e32 v176, v143
	v_and_b32_e32 v175, 0xffff0000, v175
	v_readlane_b32 s34, v240, 14
	v_readlane_b32 s35, v240, 15
	v_fma_f32 v203, -v143, v176, 1.0
	v_fmac_f32_e32 v176, v203, v176
	v_div_scale_f32 v203, vcc, 1.0, v133, 1.0
	v_mul_f32_e32 v206, v203, v176
	v_fma_f32 v212, -v143, v206, v203
	v_fmac_f32_e32 v206, v212, v176
	v_fma_f32 v143, -v143, v206, v203
	v_div_fmas_f32 v143, v143, v176, v206
	v_div_fixup_f32 v176, v143, v133, 1.0
	v_lshl_add_u32 v133, v184, 2, s58
	v_add_u32_e32 v184, 0x16d00, v133
	v_mul_f32_e32 v133, 0xbfb8aa3b, v216
	v_exp_f32_e32 v133, v133
	ds_read_b128 v[210:213], v184
	v_pk_mul_f32 v[124:125], v[124:125], v[176:177] op_sel_hi:[1,0]
	v_pk_mul_f32 v[126:127], v[126:127], v[176:177] op_sel_hi:[1,0]
	v_add_f32_e32 v133, 1.0, v133
	v_rcp_f32_e32 v218, v133
	v_mul_f32_e32 v133, 0xbfb8aa3b, v217
	v_exp_f32_e32 v133, v133
	s_waitcnt lgkmcnt(0)
	v_pk_mul_f32 v[124:125], v[210:211], v[124:125]
	v_pk_mul_f32 v[126:127], v[212:213], v[126:127]
	v_pk_mul_f32 v[120:121], v[120:121], v[176:177] op_sel_hi:[1,0]
	v_add_f32_e32 v133, 1.0, v133
	v_rcp_f32_e32 v219, v133
	v_mul_f32_e32 v133, 0xbfb8aa3b, v174
	v_exp_f32_e32 v133, v133
	v_pk_mul_f32 v[122:123], v[122:123], v[176:177] op_sel_hi:[1,0]
	v_pk_mul_f32 v[210:211], v[218:219], v[216:217]
	v_pk_mul_f32 v[116:117], v[116:117], v[176:177] op_sel_hi:[1,0]
	v_add_f32_e32 v133, 1.0, v133
	v_pk_mul_f32 v[124:125], v[210:211], v[124:125]
	v_rcp_f32_e32 v210, v133
	v_mul_f32_e32 v133, 0xbfb8aa3b, v175
	v_exp_f32_e32 v133, v133
	v_pk_mul_f32 v[118:119], v[118:119], v[176:177] op_sel_hi:[1,0]
	v_pk_mul_f32 v[112:113], v[112:113], v[176:177] op_sel_hi:[1,0]
	v_pk_mul_f32 v[114:115], v[114:115], v[176:177] op_sel_hi:[1,0]
	v_add_f32_e32 v133, 1.0, v133
	v_rcp_f32_e32 v211, v133
	v_mov_b32_e32 v133, v3
	v_pk_mul_f32 v[174:175], v[210:211], v[174:175]
	s_nop 0
	v_pk_mul_f32 v[126:127], v[174:175], v[126:127]
	v_cvt_pk_bf16_f32 v174, v124, v125
	v_lshl_add_u64 v[124:125], s[34:35], 0, v[214:215]
	v_lshl_add_u64 v[124:125], v[124:125], 0, s[8:9]
	v_cvt_pk_bf16_f32 v175, v126, v127
	v_lshl_add_u64 v[124:125], s[60:61], 1, v[124:125]
	s_waitcnt vmcnt(29)
	v_lshlrev_b32_e32 v126, 16, v166
	v_lshl_add_u64 v[124:125], v[124:125], 0, v[132:133]
	v_mul_f32_e32 v133, 0xbfb8aa3b, v126
	v_exp_f32_e32 v133, v133
	v_and_b32_e32 v127, 0xffff0000, v166
	global_store_dwordx2 v[124:125], v[174:175], off sc1
	ds_read_b128 v[210:213], v184 offset:64
	v_add_f32_e32 v133, 1.0, v133
	v_rcp_f32_e32 v174, v133
	v_mul_f32_e32 v133, 0xbfb8aa3b, v127
	v_exp_f32_e32 v133, v133
	s_waitcnt lgkmcnt(0)
	v_pk_mul_f32 v[120:121], v[210:211], v[120:121]
	v_pk_mul_f32 v[122:123], v[212:213], v[122:123]
	s_add_i32 s34, s83, 0x14000
	v_add_f32_e32 v133, 1.0, v133
	v_rcp_f32_e32 v175, v133
	v_add_u32_e32 v203, s34, v152
	v_pk_mul_f32 v[126:127], v[174:175], v[126:127]
	s_nop 0
	v_pk_mul_f32 v[120:121], v[126:127], v[120:121]
	v_lshlrev_b32_e32 v126, 16, v167
	v_mul_f32_e32 v133, 0xbfb8aa3b, v126
	v_exp_f32_e32 v133, v133
	v_and_b32_e32 v127, 0xffff0000, v167
	v_cvt_pk_bf16_f32 v120, v120, v121
	v_add_u32_e32 v175, 0, v153
	v_add_f32_e32 v133, 1.0, v133
	v_rcp_f32_e32 v166, v133
	v_mul_f32_e32 v133, 0xbfb8aa3b, v127
	v_exp_f32_e32 v133, v133
	s_nop 0
	v_add_f32_e32 v133, 1.0, v133
	v_rcp_f32_e32 v167, v133
	s_nop 0
	v_pk_mul_f32 v[126:127], v[166:167], v[126:127]
	s_nop 0
	v_pk_mul_f32 v[122:123], v[126:127], v[122:123]
	s_waitcnt vmcnt(29)
	v_lshlrev_b32_e32 v126, 16, v156
	v_cvt_pk_bf16_f32 v121, v122, v123
	global_store_dwordx2 v[124:125], v[120:121], off offset:32 sc1
	ds_read_b128 v[120:123], v184 offset:128
	v_and_b32_e32 v127, 0xffff0000, v156
	v_mul_f32_e32 v133, 0xbfb8aa3b, v126
	v_exp_f32_e32 v133, v133
	s_waitcnt lgkmcnt(0)
	v_pk_mul_f32 v[116:117], v[120:121], v[116:117]
	v_mul_f32_e32 v120, 0xbfb8aa3b, v127
	v_exp_f32_e32 v120, v120
	v_add_f32_e32 v133, 1.0, v133
	v_rcp_f32_e32 v166, v133
	v_pk_mul_f32 v[118:119], v[122:123], v[118:119]
	v_add_f32_e32 v120, 1.0, v120
	v_rcp_f32_e32 v167, v120
	s_nop 0
	v_pk_mul_f32 v[120:121], v[166:167], v[126:127]
	s_nop 0
	v_pk_mul_f32 v[116:117], v[120:121], v[116:117]
	v_lshlrev_b32_e32 v120, 16, v157
	v_and_b32_e32 v121, 0xffff0000, v157
	v_mul_f32_e32 v126, 0xbfb8aa3b, v120
	v_mul_f32_e32 v122, 0xbfb8aa3b, v121
	v_exp_f32_e32 v126, v126
	v_exp_f32_e32 v122, v122
	v_cvt_pk_bf16_f32 v116, v116, v117
	v_add_f32_e32 v126, 1.0, v126
	v_add_f32_e32 v122, 1.0, v122
	v_rcp_f32_e32 v126, v126
	v_rcp_f32_e32 v127, v122
	s_nop 0
	v_pk_mul_f32 v[120:121], v[126:127], v[120:121]
	s_nop 0
	v_pk_mul_f32 v[118:119], v[120:121], v[118:119]
	s_waitcnt vmcnt(29)
; template <bool FULL> __device__ __forceinline__ void gla_unit(LAS unsigned char* lds, const MixBufs& B, int b, int h, int seg, int tid) {
;     ...
;         const int okf = (ci & 1) ? G_KF2 : G_KF; LAS float* DLc = (ci & 1) ? (LAS float*)(lds + G_DL2) : DL;
;         const int ov = (!FULL && (ci & 1)) ? G_ST : G_V;
;         { const v4u ee = re[st]; const f32x4 e0 = (f32x4){bflo(ee.x), bfhi(ee.x), bflo(ee.y), bfhi(ee.y)}, e1 = (f32x4){bflo(ee.z), bfhi(ee.z), bflo(ee.w), bfhi(ee.w)};
;           f32x4 i0, i1;
; #pragma unroll
;           for (int e = 0; e < 4; ++e) { i0[e] = __builtin_amdgcn_rcpf(e0[e]); i1[e] = __builtin_amdgcn_rcpf(e1[e]); }
;           *(LAS v4u*)(lds + okf + lr * GP64 + lc * 16) = mul_bf8(rk[st], i0, i1);
;           if (FULL) { *(LAS v4u*)(lds + G_KB + lr * GP64 + lc * 16) = mul_bf8(rk[st], e0, e1);
;                       *(LAS v4u*)(lds + G_QF + lr * GP64 + lc * 16) = mul_bf8(rq[st], e0, e1); *(LAS v4u*)(lds + G_QB + lr * GP64 + lc * 16) = mul_bf8(rq[st], i0, i1); } }
;         *(LAS v4u*)(lds + ov + vr * GP128 + vc * 16) = rv0[st]; *(LAS v4u*)(lds + ov + (vr + 32) * GP128 + vc * 16) = rv1[st];
;         if (tid < 64) DLc[tid] = rdl[st];
;         if (FULL) {
; #pragma unroll
;             for (int j = 0; j < 4; ++j) *(LAS u32x2*)(lds + G_ST + (16 * (4 * vh + j) + c) * GP64 + (16 * kt + 4 * g) * 2) = f32_to_bf4(S[j]);
;         }
;         const size_t trow = t0 + 16 * ti + c;
;         u32x2 gv[4];
;         if (FULL) {
; #pragma unroll
;             for (int j = 0; j < 4; ++j) gv[j] = gvp[st][j];
;         }
;         if (ci + 3 < 8) GLA_PREFETCH(st, ch + 3);
;     ...
;             for (int j = 0; j < 4; ++j) { const f32x4 gg = bf4_to_f32(gv[j]), gnj = *(const LAS f32x4*)(GNL + 16 * (4 * vh + j) + 4 * g);
;                 f32x4 r;
; #pragma unroll
;                 for (int i = 0; i < 4; ++i) r[i] = o[j][i] * rstd * gnj[i] * (gg[i] * fsigmoid(gg[i]));
;                 *(GAS u32x2*)(B.A_a + trow * 1024 + h * 128 + 16 * (4 * vh + j) + 4 * g) = f32_to_bf4(r); }
;         }
; #pragma unroll
;         for (int ks = 0; ks < 2; ++ks) { const bf16x8 kf = frag_tr(lds + okf, GP64, 32 * ks, 16 * kt, lane);
; #pragma unroll
;             for (int j = 0; j < 4; ++j) S[j] = MFMA16(kf, vfr[j][ks], S[j]); }
;         { const f32x4 dl = *(const LAS f32x4*)(DLc + 16 * kt + 4 * g);
; #pragma unroll
;           for (int j = 0; j < 4; ++j) S[j] *= dl; }
	v_lshlrev_b32_e32 v120, 16, v150
	v_cvt_pk_bf16_f32 v117, v118, v119
	global_store_dwordx2 v[124:125], v[116:117], off offset:64 sc1
	ds_read_b128 v[116:119], v184 offset:192
	v_and_b32_e32 v121, 0xffff0000, v150
	v_mul_f32_e32 v122, 0xbfb8aa3b, v120
	v_exp_f32_e32 v122, v122
	s_waitcnt lgkmcnt(0)
	v_pk_mul_f32 v[112:113], v[112:113], v[116:117]
	v_mul_f32_e32 v116, 0xbfb8aa3b, v121
	v_exp_f32_e32 v116, v116
	v_add_f32_e32 v122, 1.0, v122
	v_rcp_f32_e32 v122, v122
	v_pk_mul_f32 v[114:115], v[114:115], v[118:119]
	v_add_f32_e32 v116, 1.0, v116
	v_rcp_f32_e32 v123, v116
	s_nop 0
	v_pk_mul_f32 v[116:117], v[122:123], v[120:121]
	s_nop 0
	v_pk_mul_f32 v[112:113], v[116:117], v[112:113]
	v_lshlrev_b32_e32 v116, 16, v151
	v_and_b32_e32 v117, 0xffff0000, v151
	v_mul_f32_e32 v120, 0xbfb8aa3b, v116
	v_mul_f32_e32 v118, 0xbfb8aa3b, v117
	v_exp_f32_e32 v120, v120
	v_exp_f32_e32 v118, v118
	v_cvt_pk_bf16_f32 v112, v112, v113
	v_add_f32_e32 v120, 1.0, v120
	v_add_f32_e32 v118, 1.0, v118
	v_rcp_f32_e32 v120, v120
	v_rcp_f32_e32 v121, v118
	s_nop 0
	v_pk_mul_f32 v[116:117], v[120:121], v[116:117]
	s_nop 0
	v_pk_mul_f32 v[114:115], v[116:117], v[114:115]
	v_mad_u32_u24 v116, v208, s36, v175
	v_cvt_pk_bf16_f32 v113, v114, v115
	global_store_dwordx2 v[124:125], v[112:113], off offset:96 sc1
	ds_read_b64_tr_b16 v[112:113], v116 offset:18432
	ds_read_b64_tr_b16 v[114:115], v116 offset:19008
	s_waitcnt lgkmcnt(0)
	v_mfma_f32_16x16x32_bf16 v[40:43], v[112:115], v[100:103], v[40:43]
	ds_read_b64_tr_b16 v[100:101], v116 offset:23040
	ds_read_b64_tr_b16 v[102:103], v116 offset:23616
	v_mfma_f32_16x16x32_bf16 v[36:39], v[112:115], v[96:99], v[36:39]
	s_waitcnt lgkmcnt(0)
	v_mfma_f32_16x16x32_bf16 v[36:39], v[100:103], v[88:91], v[36:39]
	v_add_u32_e32 v88, s70, v147
	v_add_u32_e32 v176, v88, v146
	s_waitcnt vmcnt(28)
	v_lshlrev_b32_e32 v88, 16, v68
	v_mfma_f32_16x16x32_bf16 v[72:75], v[112:115], v[108:111], v[72:75]
	v_and_b32_e32 v89, 0xffff0000, v68
	v_rcp_f32_e32 v90, v88
	v_rcp_f32_e32 v91, v89
	v_mfma_f32_16x16x32_bf16 v[80:83], v[100:103], v[80:83], v[72:75]
	v_mfma_f32_16x16x32_bf16 v[96:99], v[112:115], v[104:107], v[32:35]
	s_nop 2
	v_lshlrev_b32_e32 v72, 16, v76
	v_and_b32_e32 v73, 0xffff0000, v76
	v_lshlrev_b32_e32 v74, 16, v77
	v_mfma_f32_16x16x32_bf16 v[32:35], v[100:103], v[92:95], v[40:43]
	v_mul_f32_e64 v92, v90, v72
	v_mul_f32_e64 v93, v91, v73
	v_and_b32_e32 v75, 0xffff0000, v77
	v_cvt_pk_bf16_f32 v68, v92, v93
	v_lshlrev_b32_e32 v92, 16, v69
	v_and_b32_e32 v93, 0xffff0000, v69
	v_rcp_f32_e32 v94, v92
	v_rcp_f32_e32 v95, v93
	v_mfma_f32_16x16x32_bf16 v[40:43], v[100:103], v[84:87], v[96:99]
	v_lshlrev_b32_e32 v76, 16, v78
	v_and_b32_e32 v77, 0xffff0000, v78
	v_pk_mul_f32 v[72:73], v[72:73], v[88:89]
	v_pk_mul_f32 v[96:97], v[94:95], v[74:75]
	v_pk_mul_f32 v[74:75], v[74:75], v[92:93]
	v_cvt_pk_bf16_f32 v69, v96, v97
	v_lshlrev_b32_e32 v96, 16, v70
	v_and_b32_e32 v97, 0xffff0000, v70
	v_rcp_f32_e32 v98, v96
	v_rcp_f32_e32 v99, v97
	v_cvt_pk_bf16_f32 v72, v72, v73
	v_cvt_pk_bf16_f32 v73, v74, v75
	v_lshlrev_b32_e32 v78, 16, v79
	v_pk_mul_f32 v[74:75], v[98:99], v[76:77]
	v_and_b32_e32 v79, 0xffff0000, v79
	v_cvt_pk_bf16_f32 v70, v74, v75
	v_pk_mul_f32 v[74:75], v[76:77], v[96:97]
	v_lshlrev_b32_e32 v76, 16, v71
	v_and_b32_e32 v77, 0xffff0000, v71
	v_rcp_f32_e32 v100, v76
	v_rcp_f32_e32 v101, v77
	ds_read_b128 v[84:87], v203
	v_cvt_pk_bf16_f32 v74, v74, v75
	v_pk_mul_f32 v[102:103], v[100:101], v[78:79]
	s_nop 0
	v_cvt_pk_bf16_f32 v71, v102, v103
	ds_write_b128 v176, v[68:71]
	v_pk_mul_f32 v[68:69], v[78:79], v[76:77]
	s_nop 0
	v_cvt_pk_bf16_f32 v75, v68, v69
	v_lshlrev_b32_e32 v68, 16, v60
	v_and_b32_e32 v69, 0xffff0000, v60
	v_pk_mul_f32 v[70:71], v[68:69], v[88:89]
	ds_write_b128 v180, v[72:75] offset:27648
	v_cvt_pk_bf16_f32 v60, v70, v71
	v_lshlrev_b32_e32 v70, 16, v61
	v_and_b32_e32 v71, 0xffff0000, v61
	v_pk_mul_f32 v[72:73], v[70:71], v[92:93]
	s_nop 0
	v_cvt_pk_bf16_f32 v61, v72, v73
	v_lshlrev_b32_e32 v72, 16, v62
	v_and_b32_e32 v73, 0xffff0000, v62
	v_pk_mul_f32 v[74:75], v[72:73], v[96:97]
	s_nop 0
	v_cvt_pk_bf16_f32 v62, v74, v75
	v_lshlrev_b32_e32 v74, 16, v63
	v_and_b32_e32 v75, 0xffff0000, v63
	v_pk_mul_f32 v[76:77], v[74:75], v[76:77]
	s_nop 0
	v_cvt_pk_bf16_f32 v63, v76, v77
	ds_write_b128 v180, v[60:63]
	v_pk_mul_f32 v[60:61], v[90:91], v[68:69]
	v_pk_mul_f32 v[62:63], v[94:95], v[70:71]
	v_cvt_pk_bf16_f32 v60, v60, v61
	v_cvt_pk_bf16_f32 v61, v62, v63
	v_pk_mul_f32 v[62:63], v[98:99], v[72:73]
	v_pk_mul_f32 v[68:69], v[100:101], v[74:75]
	v_cvt_pk_bf16_f32 v62, v62, v63
	v_cvt_pk_bf16_f32 v63, v68, v69
	ds_write_b128 v180, v[60:63] offset:9216
	s_waitcnt vmcnt(27)
	ds_write_b128 v181, v[48:51] offset:36864
	s_waitcnt vmcnt(26)
	ds_write_b128 v181, v[64:67] offset:45568
	s_and_saveexec_b64 s[34:35], s[2:3]
	v_add_u32_e32 v48, 0x16c00, v178
	ds_write_b32 v48, v179
	s_or_b64 exec, exec, s[34:35]
	s_waitcnt lgkmcnt(6)
	v_pk_mul_f32 v[66:67], v[34:35], v[86:87]
	v_pk_mul_f32 v[64:65], v[32:33], v[84:85]
	v_pk_mul_f32 v[70:71], v[38:39], v[86:87]
	v_pk_mul_f32 v[68:69], v[36:37], v[84:85]
	v_cvt_pk_bf16_f32 v32, v64, v65
	v_cvt_pk_bf16_f32 v33, v66, v67
	v_pk_mul_f32 v[74:75], v[42:43], v[86:87]
	v_pk_mul_f32 v[72:73], v[40:41], v[84:85]
	ds_write_b64 v185, v[32:33] offset:63488
	v_cvt_pk_bf16_f32 v32, v68, v69
	v_cvt_pk_bf16_f32 v33, v70, v71
	s_or_b32 s69, s80, 4
	v_pk_mul_f32 v[78:79], v[82:83], v[86:87]
	v_pk_mul_f32 v[76:77], v[80:81], v[84:85]
	ds_write_b64 v186, v[32:33] offset:63488
	v_cvt_pk_bf16_f32 v32, v72, v73
	v_cvt_pk_bf16_f32 v33, v74, v75
	s_lshl_b32 s34, s69, 6
	ds_write_b64 v187, v[32:33] offset:63488
	v_cvt_pk_bf16_f32 v32, v76, v77
	v_cvt_pk_bf16_f32 v33, v78, v79
	s_or_b32 s34, s90, s34
	s_mov_b32 s35, s91
	ds_write_b64 v188, v[32:33] offset:63488
	v_lshl_add_u64 v[32:33], s[34:35], 0, v[138:139]
	v_mov_b64_e32 v[34:35], s[52:53]
	v_mad_u64_u32 v[36:37], vcc, v32, s33, v[34:35]
	v_mad_i32_i24 v37, v33, s33, v37
	v_lshlrev_b64 v[32:33], 9, v[32:33]
	s_mov_b32 s77, s9
	v_lshl_add_u64 v[32:33], s[94:95], 0, v[32:33]
	v_lshl_add_u64 v[36:37], v[36:37], 0, s[76:77]
	v_lshl_add_u64 v[32:33], v[32:33], 0, s[76:77]
	v_lshl_add_u64 v[40:41], v[36:37], 0, v[2:3]
	v_lshl_add_u64 v[32:33], v[32:33], 0, v[2:3]
	global_load_dwordx4 v[36:39], v[40:41], off nt
	global_load_dwordx4 v[60:63], v[40:41], off offset:512 nt
	global_load_dwordx4 v[48:51], v[32:33], off nt
	v_lshl_add_u64 v[32:33], s[34:35], 0, v[136:137]
	v_mad_u64_u32 v[34:35], vcc, v32, s33, v[34:35]
	v_mad_i32_i24 v35, v33, s33, v35
	v_lshl_add_u64 v[32:33], v[34:35], 0, s[8:9]
	v_mov_b32_e32 v143, v3
	v_lshl_add_u64 v[40:41], v[32:33], 0, v[142:143]
	global_load_dwordx4 v[32:35], v[40:41], off offset:1024 nt
	v_add_co_u32_e32 v40, vcc, 0x4c000, v40
	s_nop 1
	v_addc_co_u32_e32 v41, vcc, 0, v41, vcc
	global_load_dwordx4 v[40:43], v[40:41], off offset:1024 nt
	s_and_saveexec_b64 vcc, s[2:3]
	s_cbranch_execz .LBB0_723
	s_lshl_b32 s58, s69, 10
	s_mov_b32 s59, s9
	v_lshl_add_u64 v[80:81], v[140:141], 0, s[58:59]
	s_lshl_b32 s58, s78, 2
	v_lshl_add_u64 v[80:81], v[80:81], 0, s[58:59]
	v_lshl_add_u64 v[80:81], v[134:135], 2, v[80:81]
	global_load_dword v179, v[80:81], off

; #define GAS __attribute__((address_space(1)))
; #define LAS __attribute__((address_space(3)))
; __device__ __forceinline__ float fsigmoid(float x) { return __builtin_amdgcn_rcpf(1.f + __builtin_amdgcn_exp2f(-LOG2E * x)); }
; __device__ __forceinline__ f32x4 bf4_to_f32(u32x2 w) { return (f32x4){bflo(w.x), bfhi(w.x), bflo(w.y), bfhi(w.y)}; }
; __device__ __forceinline__ u32x2 f32_to_bf4(f32x4 v) { u32x2 w; w.x = cvtpk(v[0], v[1]); w.y = cvtpk(v[2], v[3]); return w; }
; template <bool FULL> __device__ __forceinline__ void gla_unit(LAS unsigned char* lds, const MixBufs& B, int b, int h, int seg, int tid) {
;     ...
;             const float rstd = 1.f / sqrtf((SSQ[16 * ti + c] + SSQ[64 + 16 * ti + c]) * (1.f / 128.f) + EPS);
; #pragma unroll
;             for (int j = 0; j < 4; ++j) { const f32x4 gg = bf4_to_f32(gv[j]), gnj = *(const LAS f32x4*)(GNL + 16 * (4 * vh + j) + 4 * g);
;                 f32x4 r;
; #pragma unroll
;                 for (int i = 0; i < 4; ++i) r[i] = o[j][i] * rstd * gnj[i] * (gg[i] * fsigmoid(gg[i]));
;                 *(GAS u32x2*)(B.A_a + trow * 1024 + h * 128 + 16 * (4 * vh + j) + 4 * g) = f32_to_bf4(r); }
.LBB0_741:
	s_or_b64 exec, exec, s[34:35]
	s_waitcnt lgkmcnt(0)
	s_barrier
	ds_read2st64_b32 v[212:213], v191 offset1:1
	s_or_b32 s34, s79, s82
	s_or_b32 s34, s90, s34
	v_mul_u32_u24_e32 v210, 0x90, v208
	v_or_b32_e32 v208, s34, v177
	s_waitcnt lgkmcnt(0)
	v_add_f32_e32 v133, v212, v213
	v_fmamk_f32 v133, v133, 0x3c000000, v182
	v_cmp_gt_f32_e32 vcc, s68, v133
	v_mul_f32_e32 v143, 0x4f800000, v133
	s_waitcnt vmcnt(34)
	v_lshlrev_b32_e32 v216, 16, v172
	v_cndmask_b32_e32 v133, v133, v143, vcc
	v_sqrt_f32_e32 v143, v133
	v_and_b32_e32 v217, 0xffff0000, v172
	v_lshlrev_b32_e32 v172, 16, v173
	v_and_b32_e32 v173, 0xffff0000, v173
	v_add_u32_e32 v174, -1, v143
	v_fma_f32 v211, -v174, v143, v133
	v_cmp_ge_f32_e64 s[34:35], 0, v211
	v_add_u32_e32 v211, 1, v143
	v_mov_b32_e32 v209, s91
	v_cndmask_b32_e64 v174, v143, v174, s[34:35]
	v_fma_f32 v143, -v211, v143, v133
	v_cmp_lt_f32_e64 s[34:35], 0, v143
	v_lshlrev_b64 v[208:209], 11, v[208:209]
	s_add_i32 s83, s83, 0x16c00
	v_cndmask_b32_e64 v143, v174, v211, s[34:35]
	v_mul_f32_e32 v174, 0x37800000, v143
	v_cndmask_b32_e32 v143, v143, v174, vcc
	v_cmp_class_f32_e32 vcc, v133, v1
	s_nop 1
	v_cndmask_b32_e32 v133, v143, v133, vcc
	v_div_scale_f32 v143, s[34:35], v133, v133, 1.0
	v_rcp_f32_e32 v174, v143
	v_readlane_b32 s34, v240, 14
	v_readlane_b32 s35, v240, 15
	v_fma_f32 v211, -v143, v174, 1.0
	v_fmac_f32_e32 v174, v211, v174
	v_div_scale_f32 v211, vcc, 1.0, v133, 1.0
	v_mul_f32_e32 v212, v211, v174
	v_fma_f32 v213, -v143, v212, v211
	v_fmac_f32_e32 v212, v213, v174
	v_fma_f32 v143, -v143, v212, v211
	v_div_fmas_f32 v143, v143, v174, v212
	v_div_fixup_f32 v174, v143, v133, 1.0
	v_mul_f32_e32 v133, 0xbfb8aa3b, v216
	v_exp_f32_e32 v133, v133
	ds_read_b128 v[212:215], v184
	v_pk_mul_f32 v[124:125], v[124:125], v[174:175] op_sel_hi:[1,0]
	v_pk_mul_f32 v[126:127], v[126:127], v[174:175] op_sel_hi:[1,0]
	v_add_f32_e32 v133, 1.0, v133
	v_rcp_f32_e32 v218, v133
	v_mul_f32_e32 v133, 0xbfb8aa3b, v217
	v_exp_f32_e32 v133, v133
	s_waitcnt lgkmcnt(0)
	v_pk_mul_f32 v[124:125], v[212:213], v[124:125]
	v_pk_mul_f32 v[126:127], v[214:215], v[126:127]
	v_pk_mul_f32 v[120:121], v[120:121], v[174:175] op_sel_hi:[1,0]
	v_add_f32_e32 v133, 1.0, v133
	v_rcp_f32_e32 v219, v133
	v_mul_f32_e32 v133, 0xbfb8aa3b, v172
	v_exp_f32_e32 v133, v133
	v_pk_mul_f32 v[122:123], v[122:123], v[174:175] op_sel_hi:[1,0]
	v_pk_mul_f32 v[212:213], v[218:219], v[216:217]
	v_pk_mul_f32 v[116:117], v[116:117], v[174:175] op_sel_hi:[1,0]
	v_add_f32_e32 v133, 1.0, v133
	v_pk_mul_f32 v[124:125], v[212:213], v[124:125]
	v_rcp_f32_e32 v212, v133
	v_mul_f32_e32 v133, 0xbfb8aa3b, v173
	v_exp_f32_e32 v133, v133
	v_pk_mul_f32 v[118:119], v[118:119], v[174:175] op_sel_hi:[1,0]
	v_pk_mul_f32 v[112:113], v[112:113], v[174:175] op_sel_hi:[1,0]
	v_pk_mul_f32 v[114:115], v[114:115], v[174:175] op_sel_hi:[1,0]
	v_add_f32_e32 v133, 1.0, v133
	v_rcp_f32_e32 v213, v133
	v_mov_b32_e32 v133, v3
	v_pk_mul_f32 v[172:173], v[212:213], v[172:173]
	s_nop 0
	v_pk_mul_f32 v[126:127], v[172:173], v[126:127]
	v_cvt_pk_bf16_f32 v172, v124, v125
	v_lshl_add_u64 v[124:125], s[34:35], 0, v[208:209]
	v_lshl_add_u64 v[124:125], v[124:125], 0, s[8:9]
	v_cvt_pk_bf16_f32 v173, v126, v127
	v_lshl_add_u64 v[124:125], s[60:61], 1, v[124:125]
	s_waitcnt vmcnt(33)
	v_lshlrev_b32_e32 v126, 16, v170
	v_lshl_add_u64 v[124:125], v[124:125], 0, v[132:133]
	v_mul_f32_e32 v133, 0xbfb8aa3b, v126
	v_exp_f32_e32 v133, v133
	v_and_b32_e32 v127, 0xffff0000, v170
	global_store_dwordx2 v[124:125], v[172:173], off sc1
	ds_read_b128 v[212:215], v184 offset:64
	v_add_f32_e32 v133, 1.0, v133
	v_rcp_f32_e32 v172, v133
	v_mul_f32_e32 v133, 0xbfb8aa3b, v127
	v_exp_f32_e32 v133, v133
	s_waitcnt lgkmcnt(0)
	v_pk_mul_f32 v[120:121], v[212:213], v[120:121]
	v_pk_mul_f32 v[122:123], v[214:215], v[122:123]
	v_add_u32_e32 v209, s83, v152
	v_add_f32_e32 v133, 1.0, v133
	v_rcp_f32_e32 v173, v133
	s_nop 0
	v_pk_mul_f32 v[126:127], v[172:173], v[126:127]
	s_nop 0
	v_pk_mul_f32 v[120:121], v[126:127], v[120:121]
	v_lshlrev_b32_e32 v126, 16, v171
	v_mul_f32_e32 v133, 0xbfb8aa3b, v126
	v_exp_f32_e32 v133, v133
	v_and_b32_e32 v127, 0xffff0000, v171
	v_cvt_pk_bf16_f32 v120, v120, v121
	v_add_f32_e32 v133, 1.0, v133
	v_rcp_f32_e32 v170, v133
	v_mul_f32_e32 v133, 0xbfb8aa3b, v127
	v_exp_f32_e32 v133, v133
	s_nop 0
	v_add_f32_e32 v133, 1.0, v133
	v_rcp_f32_e32 v171, v133
	s_nop 0
	v_pk_mul_f32 v[126:127], v[170:171], v[126:127]
	s_nop 0
	v_pk_mul_f32 v[122:123], v[126:127], v[122:123]
	s_waitcnt vmcnt(33)
	v_lshlrev_b32_e32 v126, 16, v162
	v_cvt_pk_bf16_f32 v121, v122, v123
	global_store_dwordx2 v[124:125], v[120:121], off offset:32 sc1
	ds_read_b128 v[120:123], v184 offset:128
	v_and_b32_e32 v127, 0xffff0000, v162
	v_mul_f32_e32 v133, 0xbfb8aa3b, v126
	v_exp_f32_e32 v133, v133
	s_waitcnt lgkmcnt(0)
	v_pk_mul_f32 v[116:117], v[120:121], v[116:117]
	v_mul_f32_e32 v120, 0xbfb8aa3b, v127
	v_exp_f32_e32 v120, v120
	v_add_f32_e32 v133, 1.0, v133
	v_rcp_f32_e32 v170, v133
	v_pk_mul_f32 v[118:119], v[122:123], v[118:119]
	v_add_f32_e32 v120, 1.0, v120
	v_rcp_f32_e32 v171, v120
	s_nop 0
	v_pk_mul_f32 v[120:121], v[170:171], v[126:127]
	s_nop 0
	v_pk_mul_f32 v[116:117], v[120:121], v[116:117]
	v_lshlrev_b32_e32 v120, 16, v163
	v_and_b32_e32 v121, 0xffff0000, v163
	v_mul_f32_e32 v126, 0xbfb8aa3b, v120
	v_mul_f32_e32 v122, 0xbfb8aa3b, v121
	v_exp_f32_e32 v126, v126
	v_exp_f32_e32 v122, v122
	v_cvt_pk_bf16_f32 v116, v116, v117
	v_add_f32_e32 v126, 1.0, v126
	v_add_f32_e32 v122, 1.0, v122
	v_rcp_f32_e32 v126, v126
	v_rcp_f32_e32 v127, v122
	s_nop 0
	v_pk_mul_f32 v[120:121], v[126:127], v[120:121]
	s_nop 0
	v_pk_mul_f32 v[118:119], v[120:121], v[118:119]
	s_waitcnt vmcnt(33)
; #define GAS __attribute__((address_space(1)))
; #define LAS __attribute__((address_space(3)))
; #define MFMA16(a, b, c) __builtin_amdgcn_mfma_f32_16x16x32_bf16((a), (b), (c), 0, 0, 0)
; __device__ __forceinline__ float bflo(unsigned w) { return __uint_as_float(w << 16); }
; template <bool FULL> __device__ __forceinline__ void gla_unit(LAS unsigned char* lds, const MixBufs& B, int b, int h, int seg, int tid) {
;     ...
;     GLA_PREFETCH(0, 8 * seg); GLA_PREFETCH(1, 8 * seg + 1); GLA_PREFETCH(2, 8 * seg + 2);
; #pragma unroll
;     for (int ci = 0; ci < 8; ++ci) {
;         const int ch = 8 * seg + ci, st = ci % 3;
;         const size_t t0 = (size_t)b * T + (size_t)ch * CH;
;         const int okf = (ci & 1) ? G_KF2 : G_KF; LAS float* DLc = (ci & 1) ? (LAS float*)(lds + G_DL2) : DL;
;         const int ov = (!FULL && (ci & 1)) ? G_ST : G_V;
;         { const v4u ee = re[st]; const f32x4 e0 = (f32x4){bflo(ee.x), bfhi(ee.x), bflo(ee.y), bfhi(ee.y)}, e1 = (f32x4){bflo(ee.z), bfhi(ee.z), bflo(ee.w), bfhi(ee.w)};
;           f32x4 i0, i1;
; #pragma unroll
;           for (int e = 0; e < 4; ++e) { i0[e] = __builtin_amdgcn_rcpf(e0[e]); i1[e] = __builtin_amdgcn_rcpf(e1[e]); }
;           *(LAS v4u*)(lds + okf + lr * GP64 + lc * 16) = mul_bf8(rk[st], i0, i1);
;           if (FULL) { *(LAS v4u*)(lds + G_KB + lr * GP64 + lc * 16) = mul_bf8(rk[st], e0, e1);
;                       *(LAS v4u*)(lds + G_QF + lr * GP64 + lc * 16) = mul_bf8(rq[st], e0, e1); *(LAS v4u*)(lds + G_QB + lr * GP64 + lc * 16) = mul_bf8(rq[st], i0, i1); } }
;         *(LAS v4u*)(lds + ov + vr * GP128 + vc * 16) = rv0[st]; *(LAS v4u*)(lds + ov + (vr + 32) * GP128 + vc * 16) = rv1[st];
;         if (tid < 64) DLc[tid] = rdl[st];
;         if (FULL) {
; #pragma unroll
;             for (int j = 0; j < 4; ++j) *(LAS u32x2*)(lds + G_ST + (16 * (4 * vh + j) + c) * GP64 + (16 * kt + 4 * g) * 2) = f32_to_bf4(S[j]);
;     ...
;                 *(GAS u32x2*)(B.A_a + trow * 1024 + h * 128 + 16 * (4 * vh + j) + 4 * g) = f32_to_bf4(r); }
;         }
; #pragma unroll
;         for (int ks = 0; ks < 2; ++ks) { const bf16x8 kf = frag_tr(lds + okf, GP64, 32 * ks, 16 * kt, lane);
; #pragma unroll
;             for (int j = 0; j < 4; ++j) S[j] = MFMA16(kf, vfr[j][ks], S[j]); }
;         { const f32x4 dl = *(const LAS f32x4*)(DLc + 16 * kt + 4 * g);
; #pragma unroll
;           for (int j = 0; j < 4; ++j) S[j] *= dl; }
	v_lshlrev_b32_e32 v120, 16, v158
	v_cvt_pk_bf16_f32 v117, v118, v119
	global_store_dwordx2 v[124:125], v[116:117], off offset:64 sc1
	ds_read_b128 v[116:119], v184 offset:192
	v_and_b32_e32 v121, 0xffff0000, v158
	v_mul_f32_e32 v122, 0xbfb8aa3b, v120
	v_exp_f32_e32 v122, v122
	s_waitcnt lgkmcnt(0)
	v_pk_mul_f32 v[112:113], v[112:113], v[116:117]
	v_mul_f32_e32 v116, 0xbfb8aa3b, v121
	v_exp_f32_e32 v116, v116
	v_add_f32_e32 v122, 1.0, v122
	v_rcp_f32_e32 v122, v122
	v_pk_mul_f32 v[114:115], v[114:115], v[118:119]
	v_add_f32_e32 v116, 1.0, v116
	v_rcp_f32_e32 v123, v116
	s_nop 0
	v_pk_mul_f32 v[116:117], v[122:123], v[120:121]
	s_nop 0
	v_pk_mul_f32 v[112:113], v[116:117], v[112:113]
	v_lshlrev_b32_e32 v116, 16, v159
	v_and_b32_e32 v117, 0xffff0000, v159
	v_mul_f32_e32 v120, 0xbfb8aa3b, v116
	v_mul_f32_e32 v118, 0xbfb8aa3b, v117
	v_exp_f32_e32 v120, v120
	v_exp_f32_e32 v118, v118
	v_cvt_pk_bf16_f32 v112, v112, v113
	v_add_f32_e32 v120, 1.0, v120
	v_add_f32_e32 v118, 1.0, v118
	v_rcp_f32_e32 v120, v120
	v_rcp_f32_e32 v121, v118
	s_nop 0
	v_pk_mul_f32 v[116:117], v[120:121], v[116:117]
	s_nop 0
	v_pk_mul_f32 v[114:115], v[116:117], v[114:115]
	s_nop 0
	v_cvt_pk_bf16_f32 v113, v114, v115
	global_store_dwordx2 v[124:125], v[112:113], off offset:96 sc1
	v_add_u32_e32 v112, s70, v153
	v_add_u32_e32 v208, v112, v210
	ds_read_b64_tr_b16 v[112:113], v208
	ds_read_b64_tr_b16 v[114:115], v208 offset:576
	s_waitcnt lgkmcnt(0)
	v_mfma_f32_16x16x32_bf16 v[68:71], v[112:115], v[96:99], v[68:71]
	ds_read_b64_tr_b16 v[96:97], v208 offset:4608
	ds_read_b64_tr_b16 v[98:99], v208 offset:5184
	v_mfma_f32_16x16x32_bf16 v[64:67], v[112:115], v[100:103], v[64:67]
	v_mfma_f32_16x16x32_bf16 v[72:75], v[112:115], v[104:107], v[72:75]
	s_waitcnt lgkmcnt(0)
	v_mfma_f32_16x16x32_bf16 v[64:67], v[96:99], v[92:95], v[64:67]
	s_waitcnt vmcnt(32)
	v_lshlrev_b32_e32 v92, 16, v44
	v_and_b32_e32 v93, 0xffff0000, v44
	v_rcp_f32_e32 v94, v92
	v_rcp_f32_e32 v95, v93
	v_mfma_f32_16x16x32_bf16 v[76:79], v[112:115], v[108:111], v[76:79]
	v_mfma_f32_16x16x32_bf16 v[72:75], v[96:99], v[84:87], v[72:75]
	v_lshlrev_b32_e32 v84, 16, v56
	v_and_b32_e32 v85, 0xffff0000, v56
	v_lshlrev_b32_e32 v86, 16, v57
	v_and_b32_e32 v87, 0xffff0000, v57
	v_pk_mul_f32 v[56:57], v[94:95], v[84:85]
	v_mfma_f32_16x16x32_bf16 v[68:71], v[96:99], v[88:91], v[68:71]
	v_cvt_pk_bf16_f32 v44, v56, v57
	v_pk_mul_f32 v[56:57], v[84:85], v[92:93]
	v_lshlrev_b32_e32 v84, 16, v45
	v_and_b32_e32 v85, 0xffff0000, v45
	v_mfma_f32_16x16x32_bf16 v[76:79], v[96:99], v[80:83], v[76:79]
	v_rcp_f32_e32 v96, v84
	v_rcp_f32_e32 v97, v85
	v_lshlrev_b32_e32 v88, 16, v58
	v_and_b32_e32 v89, 0xffff0000, v58
	v_lshlrev_b32_e32 v90, 16, v59
	v_and_b32_e32 v91, 0xffff0000, v59
	v_pk_mul_f32 v[58:59], v[96:97], v[86:87]
	v_cvt_pk_bf16_f32 v56, v56, v57
	v_cvt_pk_bf16_f32 v45, v58, v59
	v_pk_mul_f32 v[58:59], v[86:87], v[84:85]
	v_lshlrev_b32_e32 v86, 16, v46
	v_and_b32_e32 v87, 0xffff0000, v46
	v_rcp_f32_e32 v98, v86
	v_rcp_f32_e32 v99, v87
	v_cvt_pk_bf16_f32 v57, v58, v59
	ds_read_b128 v[80:83], v209
	v_pk_mul_f32 v[58:59], v[98:99], v[88:89]
	s_nop 0
	v_cvt_pk_bf16_f32 v46, v58, v59
	v_pk_mul_f32 v[58:59], v[88:89], v[86:87]
	v_lshlrev_b32_e32 v88, 16, v47
	v_and_b32_e32 v89, 0xffff0000, v47
	v_rcp_f32_e32 v100, v88
	v_rcp_f32_e32 v101, v89
	v_cvt_pk_bf16_f32 v58, v58, v59
	v_pk_mul_f32 v[102:103], v[100:101], v[90:91]
	s_nop 0
	v_cvt_pk_bf16_f32 v47, v102, v103
	ds_write_b128 v180, v[44:47] offset:18432
	v_pk_mul_f32 v[44:45], v[90:91], v[88:89]
	s_nop 0
	v_cvt_pk_bf16_f32 v59, v44, v45
	v_lshlrev_b32_e32 v44, 16, v28
	v_and_b32_e32 v45, 0xffff0000, v28
	v_pk_mul_f32 v[46:47], v[44:45], v[92:93]
	ds_write_b128 v180, v[56:59] offset:27648
	v_cvt_pk_bf16_f32 v28, v46, v47
	v_lshlrev_b32_e32 v46, 16, v29
	v_and_b32_e32 v47, 0xffff0000, v29
	v_pk_mul_f32 v[56:57], v[46:47], v[84:85]
	s_nop 0
	v_cvt_pk_bf16_f32 v29, v56, v57
	v_lshlrev_b32_e32 v56, 16, v30
	v_and_b32_e32 v57, 0xffff0000, v30
	v_pk_mul_f32 v[58:59], v[56:57], v[86:87]
	s_nop 0
	v_cvt_pk_bf16_f32 v30, v58, v59
	v_lshlrev_b32_e32 v58, 16, v31
	v_and_b32_e32 v59, 0xffff0000, v31
	v_pk_mul_f32 v[84:85], v[58:59], v[88:89]
	s_nop 0
	v_cvt_pk_bf16_f32 v31, v84, v85
	ds_write_b128 v180, v[28:31]
	v_pk_mul_f32 v[28:29], v[94:95], v[44:45]
	v_pk_mul_f32 v[30:31], v[96:97], v[46:47]
	v_cvt_pk_bf16_f32 v28, v28, v29
	v_cvt_pk_bf16_f32 v29, v30, v31
	v_pk_mul_f32 v[30:31], v[98:99], v[56:57]
	v_pk_mul_f32 v[44:45], v[100:101], v[58:59]
	v_cvt_pk_bf16_f32 v30, v30, v31
	v_cvt_pk_bf16_f32 v31, v44, v45
	ds_write_b128 v180, v[28:31] offset:9216
	s_waitcnt vmcnt(31)
	ds_write_b128 v181, v[16:19] offset:36864
	s_waitcnt vmcnt(30)
	ds_write_b128 v181, v[24:27] offset:45568
	s_and_saveexec_b64 s[34:35], s[2:3]
	v_add_u32_e32 v16, 0x14000, v178
	ds_write_b32 v16, v207
	s_or_b64 exec, exec, s[34:35]
	s_waitcnt lgkmcnt(6)
	v_pk_mul_f32 v[66:67], v[66:67], v[82:83]
	v_pk_mul_f32 v[64:65], v[64:65], v[80:81]
	v_pk_mul_f32 v[70:71], v[70:71], v[82:83]
	v_pk_mul_f32 v[68:69], v[68:69], v[80:81]
	v_cvt_pk_bf16_f32 v16, v64, v65
	v_cvt_pk_bf16_f32 v17, v66, v67
	v_pk_mul_f32 v[74:75], v[74:75], v[82:83]
	v_pk_mul_f32 v[72:73], v[72:73], v[80:81]
	ds_write_b64 v185, v[16:17] offset:63488
	v_cvt_pk_bf16_f32 v16, v68, v69
	v_cvt_pk_bf16_f32 v17, v70, v71
	s_or_b32 s69, s80, 5
	v_pk_mul_f32 v[78:79], v[78:79], v[82:83]
	v_pk_mul_f32 v[76:77], v[76:77], v[80:81]
	ds_write_b64 v186, v[16:17] offset:63488
	v_cvt_pk_bf16_f32 v16, v72, v73
	v_cvt_pk_bf16_f32 v17, v74, v75
	s_lshl_b32 s34, s69, 6
	ds_write_b64 v187, v[16:17] offset:63488
	v_cvt_pk_bf16_f32 v16, v76, v77
	v_cvt_pk_bf16_f32 v17, v78, v79
	s_or_b32 s34, s90, s34
	s_mov_b32 s35, s91
	ds_write_b64 v188, v[16:17] offset:63488
	v_lshl_add_u64 v[16:17], s[34:35], 0, v[138:139]
	v_mov_b64_e32 v[18:19], s[52:53]
	v_mad_u64_u32 v[24:25], s[58:59], v16, s33, v[18:19]
	v_mad_i32_i24 v25, v17, s33, v25
	v_lshlrev_b64 v[16:17], 9, v[16:17]
	s_mov_b32 s77, s9
	v_lshl_add_u64 v[16:17], s[94:95], 0, v[16:17]
	v_lshl_add_u64 v[24:25], v[24:25], 0, s[76:77]
	v_lshl_add_u64 v[16:17], v[16:17], 0, s[76:77]
	v_lshl_add_u64 v[28:29], v[24:25], 0, v[2:3]
	v_lshl_add_u64 v[16:17], v[16:17], 0, v[2:3]
	global_load_dwordx4 v[24:27], v[28:29], off nt
	global_load_dwordx4 v[56:59], v[28:29], off offset:512 nt
	global_load_dwordx4 v[44:47], v[16:17], off nt
	v_lshl_add_u64 v[16:17], s[34:35], 0, v[136:137]
	v_mad_u64_u32 v[18:19], s[58:59], v16, s33, v[18:19]
	v_mad_i32_i24 v19, v17, s33, v19
	v_lshl_add_u64 v[16:17], v[18:19], 0, s[8:9]
	v_mov_b32_e32 v143, v3
	v_lshl_add_u64 v[28:29], v[16:17], 0, v[142:143]
	global_load_dwordx4 v[16:19], v[28:29], off offset:1024 nt
	v_add_co_u32_e32 v28, vcc, 0x4c000, v28
	s_nop 1
	v_addc_co_u32_e32 v29, vcc, 0, v29, vcc
	global_load_dwordx4 v[28:31], v[28:29], off offset:1024 nt
	s_and_saveexec_b64 vcc, s[2:3]
	s_cbranch_execz .LBB0_745
	s_lshl_b32 s58, s69, 10
	s_mov_b32 s59, s9
	v_lshl_add_u64 v[80:81], v[140:141], 0, s[58:59]
	s_lshl_b32 s58, s78, 2
	v_lshl_add_u64 v[80:81], v[80:81], 0, s[58:59]
	v_lshl_add_u64 v[80:81], v[134:135], 2, v[80:81]
	global_load_dword v207, v[80:81], off

; #define GAS __attribute__((address_space(1)))
; #define LAS __attribute__((address_space(3)))
; __device__ __forceinline__ float fsigmoid(float x) { return __builtin_amdgcn_rcpf(1.f + __builtin_amdgcn_exp2f(-LOG2E * x)); }
; __device__ __forceinline__ f32x4 bf4_to_f32(u32x2 w) { return (f32x4){bflo(w.x), bfhi(w.x), bflo(w.y), bfhi(w.y)}; }
; __device__ __forceinline__ u32x2 f32_to_bf4(f32x4 v) { u32x2 w; w.x = cvtpk(v[0], v[1]); w.y = cvtpk(v[2], v[3]); return w; }
; template <bool FULL> __device__ __forceinline__ void gla_unit(LAS unsigned char* lds, const MixBufs& B, int b, int h, int seg, int tid) {
;     ...
;             const float rstd = 1.f / sqrtf((SSQ[16 * ti + c] + SSQ[64 + 16 * ti + c]) * (1.f / 128.f) + EPS);
; #pragma unroll
;             for (int j = 0; j < 4; ++j) { const f32x4 gg = bf4_to_f32(gv[j]), gnj = *(const LAS f32x4*)(GNL + 16 * (4 * vh + j) + 4 * g);
;                 f32x4 r;
; #pragma unroll
;                 for (int i = 0; i < 4; ++i) r[i] = o[j][i] * rstd * gnj[i] * (gg[i] * fsigmoid(gg[i]));
;                 *(GAS u32x2*)(B.A_a + trow * 1024 + h * 128 + 16 * (4 * vh + j) + 4 * g) = f32_to_bf4(r); }
.LBB0_763:
	s_or_b64 exec, exec, s[34:35]
	s_waitcnt lgkmcnt(0)
	s_barrier
	ds_read2st64_b32 v[170:171], v191 offset1:1
	s_or_b32 s34, s79, s81
	s_or_b32 s34, s90, s34
	v_or_b32_e32 v212, s34, v177
	s_waitcnt vmcnt(38)
	v_lshlrev_b32_e32 v218, 16, v168
	s_waitcnt lgkmcnt(0)
	v_add_f32_e32 v133, v170, v171
	v_fmamk_f32 v133, v133, 0x3c000000, v182
	v_cmp_gt_f32_e32 vcc, s68, v133
	v_mul_f32_e32 v143, 0x4f800000, v133
	v_and_b32_e32 v219, 0xffff0000, v168
	v_cndmask_b32_e32 v133, v133, v143, vcc
	v_sqrt_f32_e32 v143, v133
	v_mov_b32_e32 v213, s91
	v_lshlrev_b32_e32 v168, 16, v169
	v_lshlrev_b64 v[216:217], 11, v[212:213]
	v_add_u32_e32 v170, -1, v143
	v_fma_f32 v171, -v170, v143, v133
	v_cmp_ge_f32_e64 s[34:35], 0, v171
	v_add_u32_e32 v171, 1, v143
	ds_read_b128 v[212:215], v184
	v_cndmask_b32_e64 v170, v143, v170, s[34:35]
	v_fma_f32 v143, -v171, v143, v133
	v_cmp_lt_f32_e64 s[34:35], 0, v143
	v_and_b32_e32 v169, 0xffff0000, v169
	v_add_u32_e32 v210, v175, v210
	v_cndmask_b32_e64 v143, v170, v171, s[34:35]
	v_mul_f32_e32 v170, 0x37800000, v143
	v_cndmask_b32_e32 v143, v143, v170, vcc
	v_cmp_class_f32_e32 vcc, v133, v1
	s_nop 1
	v_cndmask_b32_e32 v133, v143, v133, vcc
	v_div_scale_f32 v143, s[34:35], v133, v133, 1.0
	v_rcp_f32_e32 v170, v143
	v_readlane_b32 s34, v240, 14
	v_readlane_b32 s35, v240, 15
	v_fma_f32 v171, -v143, v170, 1.0
	v_fmac_f32_e32 v170, v171, v170
	v_div_scale_f32 v171, vcc, 1.0, v133, 1.0
	v_mul_f32_e32 v174, v171, v170
	v_fma_f32 v211, -v143, v174, v171
	v_fmac_f32_e32 v174, v211, v170
	v_fma_f32 v143, -v143, v174, v171
	v_div_fmas_f32 v143, v143, v170, v174
	v_div_fixup_f32 v170, v143, v133, 1.0
	v_mul_f32_e32 v133, 0xbfb8aa3b, v218
	v_exp_f32_e32 v133, v133
	v_pk_mul_f32 v[124:125], v[124:125], v[170:171] op_sel_hi:[1,0]
	v_pk_mul_f32 v[126:127], v[126:127], v[170:171] op_sel_hi:[1,0]
	s_waitcnt lgkmcnt(0)
	v_pk_mul_f32 v[124:125], v[212:213], v[124:125]
	v_add_f32_e32 v133, 1.0, v133
	v_rcp_f32_e32 v220, v133
	v_mul_f32_e32 v133, 0xbfb8aa3b, v219
	v_exp_f32_e32 v133, v133
	v_pk_mul_f32 v[126:127], v[214:215], v[126:127]
	v_pk_mul_f32 v[120:121], v[120:121], v[170:171] op_sel_hi:[1,0]
	v_pk_mul_f32 v[122:123], v[122:123], v[170:171] op_sel_hi:[1,0]
	v_add_f32_e32 v133, 1.0, v133
	v_rcp_f32_e32 v221, v133
	v_mul_f32_e32 v133, 0xbfb8aa3b, v168
	v_exp_f32_e32 v133, v133
	v_pk_mul_f32 v[116:117], v[116:117], v[170:171] op_sel_hi:[1,0]
	v_pk_mul_f32 v[212:213], v[220:221], v[218:219]
	v_pk_mul_f32 v[118:119], v[118:119], v[170:171] op_sel_hi:[1,0]
	v_add_f32_e32 v133, 1.0, v133
	v_pk_mul_f32 v[124:125], v[212:213], v[124:125]
	v_rcp_f32_e32 v212, v133
	v_mul_f32_e32 v133, 0xbfb8aa3b, v169
	v_exp_f32_e32 v133, v133
	v_pk_mul_f32 v[112:113], v[112:113], v[170:171] op_sel_hi:[1,0]
	v_pk_mul_f32 v[114:115], v[114:115], v[170:171] op_sel_hi:[1,0]
	v_add_f32_e32 v133, 1.0, v133
	v_rcp_f32_e32 v213, v133
	v_mov_b32_e32 v133, v3
	v_pk_mul_f32 v[168:169], v[212:213], v[168:169]
	s_nop 0
	v_pk_mul_f32 v[126:127], v[168:169], v[126:127]
	v_cvt_pk_bf16_f32 v168, v124, v125
	v_lshl_add_u64 v[124:125], s[34:35], 0, v[216:217]
	v_lshl_add_u64 v[124:125], v[124:125], 0, s[8:9]
	v_cvt_pk_bf16_f32 v169, v126, v127
	v_lshl_add_u64 v[124:125], s[60:61], 1, v[124:125]
	s_waitcnt vmcnt(37)
	v_lshlrev_b32_e32 v126, 16, v160
	v_lshl_add_u64 v[124:125], v[124:125], 0, v[132:133]
	v_mul_f32_e32 v133, 0xbfb8aa3b, v126
	v_exp_f32_e32 v133, v133
	v_and_b32_e32 v127, 0xffff0000, v160
	global_store_dwordx2 v[124:125], v[168:169], off sc1
	ds_read_b128 v[212:215], v184 offset:64
	v_add_f32_e32 v133, 1.0, v133
	v_rcp_f32_e32 v168, v133
	v_mul_f32_e32 v133, 0xbfb8aa3b, v127
	v_exp_f32_e32 v133, v133
	s_waitcnt lgkmcnt(0)
	v_pk_mul_f32 v[120:121], v[212:213], v[120:121]
	v_pk_mul_f32 v[122:123], v[214:215], v[122:123]
	v_add_f32_e32 v133, 1.0, v133
	v_rcp_f32_e32 v169, v133
	s_nop 0
	v_pk_mul_f32 v[126:127], v[168:169], v[126:127]
	s_nop 0
	v_pk_mul_f32 v[120:121], v[126:127], v[120:121]
	v_lshlrev_b32_e32 v126, 16, v161
	v_mul_f32_e32 v133, 0xbfb8aa3b, v126
	v_exp_f32_e32 v133, v133
	v_and_b32_e32 v127, 0xffff0000, v161
	v_cvt_pk_bf16_f32 v120, v120, v121
	v_add_f32_e32 v133, 1.0, v133
	v_rcp_f32_e32 v160, v133
	v_mul_f32_e32 v133, 0xbfb8aa3b, v127
	v_exp_f32_e32 v133, v133
	s_nop 0
	v_add_f32_e32 v133, 1.0, v133
	v_rcp_f32_e32 v161, v133
	s_nop 0
	v_pk_mul_f32 v[126:127], v[160:161], v[126:127]
	s_nop 0
	v_pk_mul_f32 v[122:123], v[126:127], v[122:123]
	s_waitcnt vmcnt(37)
	v_lshlrev_b32_e32 v126, 16, v130
	v_cvt_pk_bf16_f32 v121, v122, v123
	global_store_dwordx2 v[124:125], v[120:121], off offset:32 sc1
	ds_read_b128 v[120:123], v184 offset:128
	v_and_b32_e32 v127, 0xffff0000, v130
	v_mul_f32_e32 v130, 0xbfb8aa3b, v126
	v_exp_f32_e32 v130, v130
	s_waitcnt lgkmcnt(0)
	v_pk_mul_f32 v[116:117], v[120:121], v[116:117]
	v_mul_f32_e32 v120, 0xbfb8aa3b, v127
	v_exp_f32_e32 v120, v120
	v_add_f32_e32 v130, 1.0, v130
	v_rcp_f32_e32 v160, v130
	v_pk_mul_f32 v[118:119], v[122:123], v[118:119]
	v_add_f32_e32 v120, 1.0, v120
	v_rcp_f32_e32 v161, v120
	s_nop 0
	v_pk_mul_f32 v[120:121], v[160:161], v[126:127]
	s_nop 0
	v_pk_mul_f32 v[116:117], v[120:121], v[116:117]
	v_lshlrev_b32_e32 v120, 16, v131
	v_and_b32_e32 v121, 0xffff0000, v131
	v_mul_f32_e32 v126, 0xbfb8aa3b, v120
	v_mul_f32_e32 v122, 0xbfb8aa3b, v121
	v_exp_f32_e32 v126, v126
	v_exp_f32_e32 v122, v122
	v_cvt_pk_bf16_f32 v116, v116, v117
	v_add_f32_e32 v126, 1.0, v126
	v_add_f32_e32 v122, 1.0, v122
	v_rcp_f32_e32 v126, v126
	v_rcp_f32_e32 v127, v122
	s_nop 0
	v_pk_mul_f32 v[120:121], v[126:127], v[120:121]
	s_nop 0
	v_pk_mul_f32 v[118:119], v[120:121], v[118:119]
	s_waitcnt vmcnt(37)
; #define GAS __attribute__((address_space(1)))
; #define LAS __attribute__((address_space(3)))
; #define MFMA16(a, b, c) __builtin_amdgcn_mfma_f32_16x16x32_bf16((a), (b), (c), 0, 0, 0)
; __device__ __forceinline__ float bflo(unsigned w) { return __uint_as_float(w << 16); }
; template <bool FULL> __device__ __forceinline__ void gla_unit(LAS unsigned char* lds, const MixBufs& B, int b, int h, int seg, int tid) {
;     ...
;     GLA_PREFETCH(0, 8 * seg); GLA_PREFETCH(1, 8 * seg + 1); GLA_PREFETCH(2, 8 * seg + 2);
; #pragma unroll
;     for (int ci = 0; ci < 8; ++ci) {
;         const int ch = 8 * seg + ci, st = ci % 3;
;         const size_t t0 = (size_t)b * T + (size_t)ch * CH;
;         const int okf = (ci & 1) ? G_KF2 : G_KF; LAS float* DLc = (ci & 1) ? (LAS float*)(lds + G_DL2) : DL;
;         const int ov = (!FULL && (ci & 1)) ? G_ST : G_V;
;         { const v4u ee = re[st]; const f32x4 e0 = (f32x4){bflo(ee.x), bfhi(ee.x), bflo(ee.y), bfhi(ee.y)}, e1 = (f32x4){bflo(ee.z), bfhi(ee.z), bflo(ee.w), bfhi(ee.w)};
;           f32x4 i0, i1;
; #pragma unroll
;           for (int e = 0; e < 4; ++e) { i0[e] = __builtin_amdgcn_rcpf(e0[e]); i1[e] = __builtin_amdgcn_rcpf(e1[e]); }
;           *(LAS v4u*)(lds + okf + lr * GP64 + lc * 16) = mul_bf8(rk[st], i0, i1);
;           if (FULL) { *(LAS v4u*)(lds + G_KB + lr * GP64 + lc * 16) = mul_bf8(rk[st], e0, e1);
;                       *(LAS v4u*)(lds + G_QF + lr * GP64 + lc * 16) = mul_bf8(rq[st], e0, e1); *(LAS v4u*)(lds + G_QB + lr * GP64 + lc * 16) = mul_bf8(rq[st], i0, i1); } }
;         *(LAS v4u*)(lds + ov + vr * GP128 + vc * 16) = rv0[st]; *(LAS v4u*)(lds + ov + (vr + 32) * GP128 + vc * 16) = rv1[st];
;         if (tid < 64) DLc[tid] = rdl[st];
;         if (FULL) {
; #pragma unroll
;             for (int j = 0; j < 4; ++j) *(LAS u32x2*)(lds + G_ST + (16 * (4 * vh + j) + c) * GP64 + (16 * kt + 4 * g) * 2) = f32_to_bf4(S[j]);
;     ...
;                 *(GAS u32x2*)(B.A_a + trow * 1024 + h * 128 + 16 * (4 * vh + j) + 4 * g) = f32_to_bf4(r); }
;         }
; #pragma unroll
;         for (int ks = 0; ks < 2; ++ks) { const bf16x8 kf = frag_tr(lds + okf, GP64, 32 * ks, 16 * kt, lane);
; #pragma unroll
;             for (int j = 0; j < 4; ++j) S[j] = MFMA16(kf, vfr[j][ks], S[j]); }
;         { const f32x4 dl = *(const LAS f32x4*)(DLc + 16 * kt + 4 * g);
; #pragma unroll
;           for (int j = 0; j < 4; ++j) S[j] *= dl; }
	v_lshlrev_b32_e32 v120, 16, v128
	v_cvt_pk_bf16_f32 v117, v118, v119
	global_store_dwordx2 v[124:125], v[116:117], off offset:64 sc1
	ds_read_b128 v[116:119], v184 offset:192
	v_and_b32_e32 v121, 0xffff0000, v128
	v_mul_f32_e32 v122, 0xbfb8aa3b, v120
	v_exp_f32_e32 v122, v122
	s_waitcnt lgkmcnt(0)
	v_pk_mul_f32 v[112:113], v[112:113], v[116:117]
	v_mul_f32_e32 v116, 0xbfb8aa3b, v121
	v_exp_f32_e32 v116, v116
	v_add_f32_e32 v122, 1.0, v122
	v_rcp_f32_e32 v122, v122
	v_pk_mul_f32 v[114:115], v[114:115], v[118:119]
	v_add_f32_e32 v116, 1.0, v116
	v_rcp_f32_e32 v123, v116
	s_nop 0
	v_pk_mul_f32 v[116:117], v[122:123], v[120:121]
	s_nop 0
	v_pk_mul_f32 v[112:113], v[116:117], v[112:113]
	v_lshlrev_b32_e32 v116, 16, v129
	v_and_b32_e32 v117, 0xffff0000, v129
	v_mul_f32_e32 v120, 0xbfb8aa3b, v116
	v_mul_f32_e32 v118, 0xbfb8aa3b, v117
	v_exp_f32_e32 v120, v120
	v_exp_f32_e32 v118, v118
	v_cvt_pk_bf16_f32 v112, v112, v113
	v_add_f32_e32 v120, 1.0, v120
	v_add_f32_e32 v118, 1.0, v118
	v_rcp_f32_e32 v120, v120
	v_rcp_f32_e32 v121, v118
	s_nop 0
	v_pk_mul_f32 v[116:117], v[120:121], v[116:117]
	s_nop 0
	v_pk_mul_f32 v[114:115], v[116:117], v[114:115]
	s_nop 0
	v_cvt_pk_bf16_f32 v113, v114, v115
	global_store_dwordx2 v[124:125], v[112:113], off offset:96 sc1
	ds_read_b64_tr_b16 v[112:113], v210 offset:18432
	ds_read_b64_tr_b16 v[114:115], v210 offset:19008
	s_waitcnt lgkmcnt(0)
	v_mfma_f32_16x16x32_bf16 v[64:67], v[112:115], v[100:103], v[64:67]
	v_mfma_f32_16x16x32_bf16 v[100:103], v[112:115], v[104:107], v[72:75]
	v_mfma_f32_16x16x32_bf16 v[104:107], v[112:115], v[108:111], v[76:79]
	ds_read_b64_tr_b16 v[108:109], v210 offset:23040
	ds_read_b64_tr_b16 v[110:111], v210 offset:23616
	v_mfma_f32_16x16x32_bf16 v[96:99], v[112:115], v[96:99], v[68:71]
	s_waitcnt lgkmcnt(0)
	v_mfma_f32_16x16x32_bf16 v[68:71], v[108:111], v[92:95], v[64:67]
	s_waitcnt vmcnt(36)
	v_lshlrev_b32_e32 v92, 16, v20
	v_and_b32_e32 v93, 0xffff0000, v20
	v_rcp_f32_e32 v94, v92
	v_rcp_f32_e32 v95, v93
	v_mfma_f32_16x16x32_bf16 v[76:79], v[108:111], v[84:87], v[100:103]
	v_lshlrev_b32_e32 v84, 16, v52
	v_and_b32_e32 v85, 0xffff0000, v52
	v_lshlrev_b32_e32 v86, 16, v53
	v_and_b32_e32 v87, 0xffff0000, v53
	v_pk_mul_f32 v[52:53], v[94:95], v[84:85]
	v_mfma_f32_16x16x32_bf16 v[72:75], v[108:111], v[88:91], v[96:99]
	v_cvt_pk_bf16_f32 v20, v52, v53
	v_pk_mul_f32 v[52:53], v[84:85], v[92:93]
	v_lshlrev_b32_e32 v84, 16, v21
	v_and_b32_e32 v85, 0xffff0000, v21
	v_rcp_f32_e32 v96, v84
	v_rcp_f32_e32 v97, v85
	v_lshlrev_b32_e32 v88, 16, v54
	v_and_b32_e32 v89, 0xffff0000, v54
	v_lshlrev_b32_e32 v90, 16, v55
	v_and_b32_e32 v91, 0xffff0000, v55
	v_pk_mul_f32 v[54:55], v[96:97], v[86:87]
	v_cvt_pk_bf16_f32 v52, v52, v53
	v_cvt_pk_bf16_f32 v21, v54, v55
	v_pk_mul_f32 v[54:55], v[86:87], v[84:85]
	v_lshlrev_b32_e32 v86, 16, v22
	v_and_b32_e32 v87, 0xffff0000, v22
	v_rcp_f32_e32 v98, v86
	v_rcp_f32_e32 v99, v87
	v_cvt_pk_bf16_f32 v53, v54, v55
	v_mfma_f32_16x16x32_bf16 v[64:67], v[108:111], v[80:83], v[104:107]
	ds_read_b128 v[80:83], v203
	v_pk_mul_f32 v[54:55], v[98:99], v[88:89]
	s_nop 0
	v_cvt_pk_bf16_f32 v22, v54, v55
	v_pk_mul_f32 v[54:55], v[88:89], v[86:87]
	v_lshlrev_b32_e32 v88, 16, v23
	v_and_b32_e32 v89, 0xffff0000, v23
	v_rcp_f32_e32 v100, v88
	v_rcp_f32_e32 v101, v89
	v_cvt_pk_bf16_f32 v54, v54, v55
	v_pk_mul_f32 v[102:103], v[100:101], v[90:91]
	s_nop 0
	v_cvt_pk_bf16_f32 v23, v102, v103
	ds_write_b128 v176, v[20:23]
	v_pk_mul_f32 v[20:21], v[90:91], v[88:89]
	s_nop 0
	v_cvt_pk_bf16_f32 v55, v20, v21
	v_lshlrev_b32_e32 v20, 16, v8
	v_and_b32_e32 v21, 0xffff0000, v8
	v_pk_mul_f32 v[22:23], v[20:21], v[92:93]
	ds_write_b128 v180, v[52:55] offset:27648
	v_cvt_pk_bf16_f32 v8, v22, v23
	v_lshlrev_b32_e32 v22, 16, v9
	v_and_b32_e32 v23, 0xffff0000, v9
	v_pk_mul_f32 v[52:53], v[22:23], v[84:85]
	s_nop 0
	v_cvt_pk_bf16_f32 v9, v52, v53
	v_lshlrev_b32_e32 v52, 16, v10
	v_and_b32_e32 v53, 0xffff0000, v10
	v_pk_mul_f32 v[54:55], v[52:53], v[86:87]
	s_nop 0
	v_cvt_pk_bf16_f32 v10, v54, v55
	v_lshlrev_b32_e32 v54, 16, v11
	v_and_b32_e32 v55, 0xffff0000, v11
	v_pk_mul_f32 v[84:85], v[54:55], v[88:89]
	s_nop 0
	v_cvt_pk_bf16_f32 v11, v84, v85
	ds_write_b128 v180, v[8:11]
	v_pk_mul_f32 v[8:9], v[94:95], v[20:21]
	v_pk_mul_f32 v[10:11], v[96:97], v[22:23]
	v_cvt_pk_bf16_f32 v8, v8, v9
	v_cvt_pk_bf16_f32 v9, v10, v11
	v_pk_mul_f32 v[10:11], v[98:99], v[52:53]
	v_pk_mul_f32 v[20:21], v[100:101], v[54:55]
	v_cvt_pk_bf16_f32 v10, v10, v11
	v_cvt_pk_bf16_f32 v11, v20, v21
	ds_write_b128 v180, v[8:11] offset:9216
	s_waitcnt vmcnt(35)
	ds_write_b128 v181, v[4:7] offset:36864
	s_waitcnt vmcnt(34)
	ds_write_b128 v181, v[12:15] offset:45568
	s_and_saveexec_b64 s[34:35], s[2:3]
	v_add_u32_e32 v4, 0x16c00, v178
	ds_write_b32 v4, v202
	s_or_b64 exec, exec, s[34:35]
	s_waitcnt lgkmcnt(6)
	v_pk_mul_f32 v[70:71], v[70:71], v[82:83]
	v_pk_mul_f32 v[68:69], v[68:69], v[80:81]
	v_pk_mul_f32 v[74:75], v[74:75], v[82:83]
	v_pk_mul_f32 v[72:73], v[72:73], v[80:81]
	v_cvt_pk_bf16_f32 v4, v68, v69
	v_cvt_pk_bf16_f32 v5, v70, v71
	v_pk_mul_f32 v[78:79], v[78:79], v[82:83]
	v_pk_mul_f32 v[76:77], v[76:77], v[80:81]
	ds_write_b64 v185, v[4:5] offset:63488
	v_cvt_pk_bf16_f32 v4, v72, v73
	v_cvt_pk_bf16_f32 v5, v74, v75
	s_or_b32 s69, s80, 6
	v_pk_mul_f32 v[82:83], v[66:67], v[82:83]
	v_pk_mul_f32 v[80:81], v[64:65], v[80:81]
	ds_write_b64 v186, v[4:5] offset:63488
	v_cvt_pk_bf16_f32 v4, v76, v77
	v_cvt_pk_bf16_f32 v5, v78, v79
	s_lshl_b32 s34, s69, 6
	ds_write_b64 v187, v[4:5] offset:63488
	v_cvt_pk_bf16_f32 v4, v80, v81
	v_cvt_pk_bf16_f32 v5, v82, v83
	s_or_b32 s34, s90, s34
	s_mov_b32 s35, s91
	ds_write_b64 v188, v[4:5] offset:63488
	v_lshl_add_u64 v[4:5], s[34:35], 0, v[138:139]
	v_mov_b64_e32 v[6:7], s[52:53]
	v_mad_u64_u32 v[8:9], s[58:59], v4, s33, v[6:7]
	v_mad_i32_i24 v9, v5, s33, v9
	v_lshlrev_b64 v[4:5], 9, v[4:5]
	s_mov_b32 s77, s9
	v_lshl_add_u64 v[4:5], s[94:95], 0, v[4:5]
	v_lshl_add_u64 v[8:9], v[8:9], 0, s[76:77]
	v_lshl_add_u64 v[4:5], v[4:5], 0, s[76:77]
	v_lshl_add_u64 v[8:9], v[8:9], 0, v[2:3]
	v_lshl_add_u64 v[4:5], v[4:5], 0, v[2:3]
	global_load_dwordx4 v[10:13], v[8:9], off nt
	global_load_dwordx4 v[64:67], v[8:9], off offset:512 nt
	global_load_dwordx4 v[52:55], v[4:5], off nt
	v_lshl_add_u64 v[4:5], s[34:35], 0, v[136:137]
	v_mad_u64_u32 v[6:7], s[58:59], v4, s33, v[6:7]
	v_mad_i32_i24 v7, v5, s33, v7
	v_lshl_add_u64 v[4:5], v[6:7], 0, s[8:9]
	v_mov_b32_e32 v143, v3
	v_lshl_add_u64 v[4:5], v[4:5], 0, v[142:143]
	global_load_dwordx4 v[6:9], v[4:5], off offset:1024 nt
	v_add_co_u32_e32 v4, vcc, 0x4c000, v4
	s_nop 1
	v_addc_co_u32_e32 v5, vcc, 0, v5, vcc
	global_load_dwordx4 v[20:23], v[4:5], off offset:1024 nt
	s_and_saveexec_b64 vcc, s[2:3]
	s_cbranch_execz .LBB0_767
	s_lshl_b32 s58, s69, 10
	s_mov_b32 s59, s9
	v_lshl_add_u64 v[4:5], v[140:141], 0, s[58:59]
	s_lshl_b32 s58, s78, 2
	v_lshl_add_u64 v[4:5], v[4:5], 0, s[58:59]
	v_lshl_add_u64 v[4:5], v[134:135], 2, v[4:5]
	global_load_dword v202, v[4:5], off

; #define GAS __attribute__((address_space(1)))
; #define LAS __attribute__((address_space(3)))
; __device__ __forceinline__ float fsigmoid(float x) { return __builtin_amdgcn_rcpf(1.f + __builtin_amdgcn_exp2f(-LOG2E * x)); }
; __device__ __forceinline__ f32x4 bf4_to_f32(u32x2 w) { return (f32x4){bflo(w.x), bfhi(w.x), bflo(w.y), bfhi(w.y)}; }
; __device__ __forceinline__ u32x2 f32_to_bf4(f32x4 v) { u32x2 w; w.x = cvtpk(v[0], v[1]); w.y = cvtpk(v[2], v[3]); return w; }
; template <bool FULL> __device__ __forceinline__ void gla_unit(LAS unsigned char* lds, const MixBufs& B, int b, int h, int seg, int tid) {
;     ...
;             const float rstd = 1.f / sqrtf((SSQ[16 * ti + c] + SSQ[64 + 16 * ti + c]) * (1.f / 128.f) + EPS);
; #pragma unroll
;             for (int j = 0; j < 4; ++j) { const f32x4 gg = bf4_to_f32(gv[j]), gnj = *(const LAS f32x4*)(GNL + 16 * (4 * vh + j) + 4 * g);
;                 f32x4 r;
; #pragma unroll
;                 for (int i = 0; i < 4; ++i) r[i] = o[j][i] * rstd * gnj[i] * (gg[i] * fsigmoid(gg[i]));
;                 *(GAS u32x2*)(B.A_a + trow * 1024 + h * 128 + 16 * (4 * vh + j) + 4 * g) = f32_to_bf4(r); }
.LBB0_785:
	s_or_b64 exec, exec, s[34:35]
	s_waitcnt lgkmcnt(0)
	s_barrier
	ds_read2st64_b32 v[4:5], v191 offset1:1
	s_or_b32 s34, s73, 0xc0
	v_or_b32_e32 v14, s34, v177
	s_waitcnt vmcnt(42)
	v_lshlrev_b32_e32 v216, 16, v164
	v_and_b32_e32 v217, 0xffff0000, v164
	s_waitcnt lgkmcnt(0)
	v_add_f32_e32 v4, v4, v5
	v_fmamk_f32 v4, v4, 0x3c000000, v182
	v_cmp_gt_f32_e32 vcc, s68, v4
	v_mul_f32_e32 v5, 0x4f800000, v4
	v_lshlrev_b32_e32 v164, 16, v165
	v_cndmask_b32_e32 v4, v4, v5, vcc
	v_sqrt_f32_e32 v5, v4
	v_and_b32_e32 v165, 0xffff0000, v165
	v_mov_b32_e32 v15, s91
	v_lshlrev_b64 v[14:15], 11, v[14:15]
	v_add_u32_e32 v133, -1, v5
	v_fma_f32 v143, -v133, v5, v4
	v_cmp_ge_f32_e64 s[34:35], 0, v143
	v_add_u32_e32 v143, 1, v5
	s_nop 0
	v_cndmask_b32_e64 v133, v5, v133, s[34:35]
	v_fma_f32 v5, -v143, v5, v4
	v_cmp_lt_f32_e64 s[34:35], 0, v5
	s_nop 1
	v_cndmask_b32_e64 v5, v133, v143, s[34:35]
	v_mul_f32_e32 v133, 0x37800000, v5
	v_cndmask_b32_e32 v5, v5, v133, vcc
	v_cmp_class_f32_e32 vcc, v4, v1
	s_nop 1
	v_cndmask_b32_e32 v4, v5, v4, vcc
	v_div_scale_f32 v5, s[34:35], v4, v4, 1.0
	v_rcp_f32_e32 v133, v5
	v_readlane_b32 s34, v240, 14
	v_readlane_b32 s35, v240, 15
	v_fma_f32 v143, -v5, v133, 1.0
	v_fmac_f32_e32 v133, v143, v133
	v_div_scale_f32 v143, vcc, 1.0, v4, 1.0
	v_mul_f32_e32 v211, v143, v133
	v_fma_f32 v212, -v5, v211, v143
	v_fmac_f32_e32 v211, v212, v133
	v_fma_f32 v5, -v5, v211, v143
	v_div_fmas_f32 v5, v5, v133, v211
	v_div_fixup_f32 v4, v5, v4, 1.0
	v_mul_f32_e32 v5, 0xbfb8aa3b, v216
	v_exp_f32_e32 v5, v5
	ds_read_b128 v[212:215], v184
	v_lshl_add_u64 v[14:15], s[34:35], 0, v[14:15]
	v_lshl_add_u64 v[14:15], v[14:15], 0, s[8:9]
	v_add_f32_e32 v5, 1.0, v5
	v_rcp_f32_e32 v218, v5
	v_pk_mul_f32 v[128:129], v[128:129], v[4:5] op_sel_hi:[1,0]
	v_mul_f32_e32 v5, 0xbfb8aa3b, v217
	v_exp_f32_e32 v5, v5
	s_waitcnt lgkmcnt(0)
	v_pk_mul_f32 v[128:129], v[212:213], v[128:129]
	v_lshl_add_u64 v[14:15], s[60:61], 1, v[14:15]
	v_mov_b32_e32 v133, v3
	v_add_f32_e32 v5, 1.0, v5
	v_rcp_f32_e32 v219, v5
	v_mul_f32_e32 v5, 0xbfb8aa3b, v164
	v_exp_f32_e32 v5, v5
	v_lshl_add_u64 v[14:15], v[14:15], 0, v[132:133]
	v_pk_mul_f32 v[212:213], v[218:219], v[216:217]
	v_add_f32_e32 v5, 1.0, v5
	v_pk_mul_f32 v[128:129], v[212:213], v[128:129]
	v_rcp_f32_e32 v212, v5
	v_pk_mul_f32 v[130:131], v[130:131], v[4:5] op_sel_hi:[1,0]
	v_mul_f32_e32 v5, 0xbfb8aa3b, v165
	v_exp_f32_e32 v5, v5
	v_pk_mul_f32 v[130:131], v[214:215], v[130:131]
	v_cvt_pk_bf16_f32 v128, v128, v129
	v_add_f32_e32 v5, 1.0, v5
	v_rcp_f32_e32 v213, v5
	s_nop 0
	v_pk_mul_f32 v[164:165], v[212:213], v[164:165]
	s_nop 0
	v_pk_mul_f32 v[130:131], v[164:165], v[130:131]
	s_waitcnt vmcnt(41)
	v_lshlrev_b32_e32 v164, 16, v154
	v_mul_f32_e32 v5, 0xbfb8aa3b, v164
	v_exp_f32_e32 v5, v5
	v_and_b32_e32 v165, 0xffff0000, v154
	v_cvt_pk_bf16_f32 v129, v130, v131
	global_store_dwordx2 v[14:15], v[128:129], off sc1
	v_add_f32_e32 v5, 1.0, v5
	v_rcp_f32_e32 v212, v5
	v_pk_mul_f32 v[124:125], v[124:125], v[4:5] op_sel_hi:[1,0]
	v_mul_f32_e32 v5, 0xbfb8aa3b, v165
	v_exp_f32_e32 v5, v5
	ds_read_b128 v[128:131], v184 offset:64
	v_add_f32_e32 v5, 1.0, v5
	v_rcp_f32_e32 v213, v5
	s_waitcnt lgkmcnt(0)
	v_pk_mul_f32 v[124:125], v[128:129], v[124:125]
	v_pk_mul_f32 v[128:129], v[212:213], v[164:165]
	s_nop 0
	v_pk_mul_f32 v[124:125], v[128:129], v[124:125]
	v_lshlrev_b32_e32 v128, 16, v155
	v_mul_f32_e32 v5, 0xbfb8aa3b, v128
	v_exp_f32_e32 v5, v5
	v_and_b32_e32 v129, 0xffff0000, v155
	v_cvt_pk_bf16_f32 v124, v124, v125
	v_add_f32_e32 v5, 1.0, v5
	v_rcp_f32_e32 v154, v5
	v_pk_mul_f32 v[126:127], v[126:127], v[4:5] op_sel_hi:[1,0]
	v_mul_f32_e32 v5, 0xbfb8aa3b, v129
	v_exp_f32_e32 v5, v5
	v_pk_mul_f32 v[126:127], v[130:131], v[126:127]
	v_add_f32_e32 v5, 1.0, v5
	v_rcp_f32_e32 v155, v5
	s_nop 0
	v_pk_mul_f32 v[128:129], v[154:155], v[128:129]
	s_nop 0
	v_pk_mul_f32 v[126:127], v[128:129], v[126:127]
	s_waitcnt vmcnt(41)
	v_lshlrev_b32_e32 v128, 16, v148
	v_mul_f32_e32 v5, 0xbfb8aa3b, v128
	v_exp_f32_e32 v5, v5
	v_and_b32_e32 v129, 0xffff0000, v148
	v_cvt_pk_bf16_f32 v125, v126, v127
	global_store_dwordx2 v[14:15], v[124:125], off offset:32 sc1
	v_add_f32_e32 v5, 1.0, v5
	v_rcp_f32_e32 v130, v5
	v_pk_mul_f32 v[120:121], v[120:121], v[4:5] op_sel_hi:[1,0]
	v_mul_f32_e32 v5, 0xbfb8aa3b, v129
	v_exp_f32_e32 v5, v5
	ds_read_b128 v[124:127], v184 offset:128
	v_add_f32_e32 v5, 1.0, v5
	v_rcp_f32_e32 v131, v5
	s_waitcnt lgkmcnt(0)
	v_pk_mul_f32 v[120:121], v[124:125], v[120:121]
	v_pk_mul_f32 v[124:125], v[130:131], v[128:129]
	s_nop 0
	v_pk_mul_f32 v[120:121], v[124:125], v[120:121]
	v_lshlrev_b32_e32 v124, 16, v149
	v_mul_f32_e32 v5, 0xbfb8aa3b, v124
	v_exp_f32_e32 v5, v5
	v_and_b32_e32 v125, 0xffff0000, v149
	v_cvt_pk_bf16_f32 v120, v120, v121
	v_add_f32_e32 v5, 1.0, v5
	v_rcp_f32_e32 v128, v5
	v_pk_mul_f32 v[122:123], v[122:123], v[4:5] op_sel_hi:[1,0]
	v_mul_f32_e32 v5, 0xbfb8aa3b, v125
	v_exp_f32_e32 v5, v5
	v_pk_mul_f32 v[122:123], v[126:127], v[122:123]
	v_add_f32_e32 v5, 1.0, v5
	v_rcp_f32_e32 v129, v5
	s_nop 0
	v_pk_mul_f32 v[124:125], v[128:129], v[124:125]
	s_nop 0
	v_pk_mul_f32 v[122:123], v[124:125], v[122:123]
	s_waitcnt vmcnt(41)
	v_lshlrev_b32_e32 v124, 16, v144
	v_mul_f32_e32 v5, 0xbfb8aa3b, v124
	v_exp_f32_e32 v5, v5
	v_and_b32_e32 v125, 0xffff0000, v144
	v_cvt_pk_bf16_f32 v121, v122, v123
	global_store_dwordx2 v[14:15], v[120:121], off offset:64 sc1
	v_add_f32_e32 v5, 1.0, v5
	v_rcp_f32_e32 v126, v5
	v_pk_mul_f32 v[116:117], v[116:117], v[4:5] op_sel_hi:[1,0]
	v_mul_f32_e32 v5, 0xbfb8aa3b, v125
	v_exp_f32_e32 v5, v5
	ds_read_b128 v[120:123], v184 offset:192
	v_add_f32_e32 v5, 1.0, v5
	v_rcp_f32_e32 v127, v5
	s_waitcnt lgkmcnt(0)
; #define GAS __attribute__((address_space(1)))
; #define LAS __attribute__((address_space(3)))
; #define MFMA16(a, b, c) __builtin_amdgcn_mfma_f32_16x16x32_bf16((a), (b), (c), 0, 0, 0)
; __device__ __forceinline__ float bflo(unsigned w) { return __uint_as_float(w << 16); }
; template <bool FULL> __device__ __forceinline__ void gla_unit(LAS unsigned char* lds, const MixBufs& B, int b, int h, int seg, int tid) {
;     ...
;     GLA_PREFETCH(0, 8 * seg); GLA_PREFETCH(1, 8 * seg + 1); GLA_PREFETCH(2, 8 * seg + 2);
; #pragma unroll
;     for (int ci = 0; ci < 8; ++ci) {
;         const int ch = 8 * seg + ci, st = ci % 3;
;         const size_t t0 = (size_t)b * T + (size_t)ch * CH;
;         const int okf = (ci & 1) ? G_KF2 : G_KF; LAS float* DLc = (ci & 1) ? (LAS float*)(lds + G_DL2) : DL;
;         const int ov = (!FULL && (ci & 1)) ? G_ST : G_V;
;         { const v4u ee = re[st]; const f32x4 e0 = (f32x4){bflo(ee.x), bfhi(ee.x), bflo(ee.y), bfhi(ee.y)}, e1 = (f32x4){bflo(ee.z), bfhi(ee.z), bflo(ee.w), bfhi(ee.w)};
;           f32x4 i0, i1;
; #pragma unroll
;           for (int e = 0; e < 4; ++e) { i0[e] = __builtin_amdgcn_rcpf(e0[e]); i1[e] = __builtin_amdgcn_rcpf(e1[e]); }
;           *(LAS v4u*)(lds + okf + lr * GP64 + lc * 16) = mul_bf8(rk[st], i0, i1);
;           if (FULL) { *(LAS v4u*)(lds + G_KB + lr * GP64 + lc * 16) = mul_bf8(rk[st], e0, e1);
;                       *(LAS v4u*)(lds + G_QF + lr * GP64 + lc * 16) = mul_bf8(rq[st], e0, e1); *(LAS v4u*)(lds + G_QB + lr * GP64 + lc * 16) = mul_bf8(rq[st], i0, i1); } }
;         *(LAS v4u*)(lds + ov + vr * GP128 + vc * 16) = rv0[st]; *(LAS v4u*)(lds + ov + (vr + 32) * GP128 + vc * 16) = rv1[st];
;         if (tid < 64) DLc[tid] = rdl[st];
;         if (FULL) {
; #pragma unroll
;             for (int j = 0; j < 4; ++j) *(LAS u32x2*)(lds + G_ST + (16 * (4 * vh + j) + c) * GP64 + (16 * kt + 4 * g) * 2) = f32_to_bf4(S[j]);
;     ...
;                 *(GAS u32x2*)(B.A_a + trow * 1024 + h * 128 + 16 * (4 * vh + j) + 4 * g) = f32_to_bf4(r); }
;         }
; #pragma unroll
;         for (int ks = 0; ks < 2; ++ks) { const bf16x8 kf = frag_tr(lds + okf, GP64, 32 * ks, 16 * kt, lane);
; #pragma unroll
;             for (int j = 0; j < 4; ++j) S[j] = MFMA16(kf, vfr[j][ks], S[j]); }
;         { const f32x4 dl = *(const LAS f32x4*)(DLc + 16 * kt + 4 * g);
; #pragma unroll
;           for (int j = 0; j < 4; ++j) S[j] *= dl; }
	v_pk_mul_f32 v[116:117], v[116:117], v[120:121]
	v_pk_mul_f32 v[120:121], v[126:127], v[124:125]
	s_nop 0
	v_pk_mul_f32 v[116:117], v[120:121], v[116:117]
	v_lshlrev_b32_e32 v120, 16, v145
	v_mul_f32_e32 v5, 0xbfb8aa3b, v120
	v_exp_f32_e32 v5, v5
	v_and_b32_e32 v121, 0xffff0000, v145
	v_cvt_pk_bf16_f32 v116, v116, v117
	v_add_f32_e32 v5, 1.0, v5
	v_rcp_f32_e32 v124, v5
	v_pk_mul_f32 v[4:5], v[118:119], v[4:5] op_sel_hi:[1,0]
	v_mul_f32_e32 v118, 0xbfb8aa3b, v121
	v_exp_f32_e32 v118, v118
	v_pk_mul_f32 v[4:5], v[4:5], v[122:123]
	v_add_f32_e32 v118, 1.0, v118
	v_rcp_f32_e32 v125, v118
	s_nop 0
	v_pk_mul_f32 v[118:119], v[124:125], v[120:121]
	s_nop 0
	v_pk_mul_f32 v[4:5], v[118:119], v[4:5]
	s_nop 0
	v_cvt_pk_bf16_f32 v117, v4, v5
	global_store_dwordx2 v[14:15], v[116:117], off offset:96 sc1
	ds_read_b64_tr_b16 v[116:117], v208
	ds_read_b64_tr_b16 v[118:119], v208 offset:576
	s_waitcnt lgkmcnt(0)
	v_mfma_f32_16x16x32_bf16 v[72:75], v[116:119], v[100:103], v[72:75]
	ds_read_b64_tr_b16 v[100:101], v208 offset:4608
	ds_read_b64_tr_b16 v[102:103], v208 offset:5184
	s_waitcnt vmcnt(37)
	v_lshlrev_b32_e32 v4, 16, v60
	v_and_b32_e32 v5, 0xffff0000, v60
	s_waitcnt lgkmcnt(0)
	v_mfma_f32_16x16x32_bf16 v[72:75], v[100:103], v[92:95], v[72:75]
	s_waitcnt vmcnt(36)
	v_lshlrev_b32_e32 v92, 16, v48
	v_and_b32_e32 v93, 0xffff0000, v48
	v_rcp_f32_e32 v94, v92
	v_rcp_f32_e32 v95, v93
	v_mfma_f32_16x16x32_bf16 v[68:71], v[116:119], v[104:107], v[68:71]
	v_lshlrev_b32_e32 v14, 16, v61
	v_and_b32_e32 v15, 0xffff0000, v61
	v_pk_mul_f32 v[60:61], v[94:95], v[4:5]
	v_pk_mul_f32 v[4:5], v[4:5], v[92:93]
	v_cvt_pk_bf16_f32 v48, v60, v61
	v_cvt_pk_bf16_f32 v60, v4, v5
	v_lshlrev_b32_e32 v4, 16, v49
	v_and_b32_e32 v5, 0xffff0000, v49
	v_mfma_f32_16x16x32_bf16 v[76:79], v[116:119], v[108:111], v[76:79]
	v_mfma_f32_16x16x32_bf16 v[68:71], v[100:103], v[96:99], v[68:71]
	v_rcp_f32_e32 v96, v4
	v_rcp_f32_e32 v97, v5
	v_mfma_f32_16x16x32_bf16 v[76:79], v[100:103], v[88:91], v[76:79]
	v_lshlrev_b32_e32 v88, 16, v62
	v_and_b32_e32 v89, 0xffff0000, v62
	v_lshlrev_b32_e32 v90, 16, v63
	v_and_b32_e32 v91, 0xffff0000, v63
	v_pk_mul_f32 v[62:63], v[96:97], v[14:15]
	v_pk_mul_f32 v[14:15], v[14:15], v[4:5]
	v_mfma_f32_16x16x32_bf16 v[80:83], v[116:119], v[112:115], v[80:83]
	v_cvt_pk_bf16_f32 v61, v14, v15
	v_lshlrev_b32_e32 v14, 16, v50
	v_and_b32_e32 v15, 0xffff0000, v50
	v_rcp_f32_e32 v98, v14
	v_rcp_f32_e32 v99, v15
	v_cvt_pk_bf16_f32 v49, v62, v63
	v_mfma_f32_16x16x32_bf16 v[80:83], v[100:103], v[84:87], v[80:83]
	ds_read_b128 v[84:87], v209
	v_pk_mul_f32 v[62:63], v[98:99], v[88:89]
	s_nop 0
	v_cvt_pk_bf16_f32 v50, v62, v63
	v_pk_mul_f32 v[62:63], v[88:89], v[14:15]
	v_lshlrev_b32_e32 v88, 16, v51
	v_and_b32_e32 v89, 0xffff0000, v51
	v_rcp_f32_e32 v100, v88
	v_rcp_f32_e32 v101, v89
	v_cvt_pk_bf16_f32 v62, v62, v63
	v_pk_mul_f32 v[102:103], v[100:101], v[90:91]
	s_nop 0
	v_cvt_pk_bf16_f32 v51, v102, v103
	ds_write_b128 v180, v[48:51] offset:18432
	v_pk_mul_f32 v[48:49], v[90:91], v[88:89]
	s_nop 0
	v_cvt_pk_bf16_f32 v63, v48, v49
	v_lshlrev_b32_e32 v48, 16, v36
	v_and_b32_e32 v49, 0xffff0000, v36
	v_pk_mul_f32 v[50:51], v[48:49], v[92:93]
	ds_write_b128 v180, v[60:63] offset:27648
	v_cvt_pk_bf16_f32 v36, v50, v51
	v_lshlrev_b32_e32 v50, 16, v37
	v_and_b32_e32 v51, 0xffff0000, v37
	v_pk_mul_f32 v[4:5], v[50:51], v[4:5]
	s_nop 0
	v_cvt_pk_bf16_f32 v37, v4, v5
	v_lshlrev_b32_e32 v4, 16, v38
	v_and_b32_e32 v5, 0xffff0000, v38
	v_pk_mul_f32 v[14:15], v[4:5], v[14:15]
	v_pk_mul_f32 v[4:5], v[98:99], v[4:5]
	v_cvt_pk_bf16_f32 v38, v14, v15
	v_lshlrev_b32_e32 v14, 16, v39
	v_and_b32_e32 v15, 0xffff0000, v39
	v_pk_mul_f32 v[60:61], v[14:15], v[88:89]
	s_nop 0
	v_cvt_pk_bf16_f32 v39, v60, v61
	ds_write_b128 v180, v[36:39]
	v_pk_mul_f32 v[36:37], v[94:95], v[48:49]
	v_pk_mul_f32 v[38:39], v[96:97], v[50:51]
	v_cvt_pk_bf16_f32 v36, v36, v37
	v_cvt_pk_bf16_f32 v37, v38, v39
	v_cvt_pk_bf16_f32 v38, v4, v5
	v_pk_mul_f32 v[4:5], v[100:101], v[14:15]
	s_nop 0
	v_cvt_pk_bf16_f32 v39, v4, v5
	ds_write_b128 v180, v[36:39] offset:9216
	s_waitcnt vmcnt(35)
	ds_write_b128 v181, v[32:35] offset:36864
	s_waitcnt vmcnt(34)
	ds_write_b128 v181, v[40:43] offset:45568
	s_and_saveexec_b64 s[34:35], s[2:3]
	v_add_u32_e32 v4, 0x14000, v178
	ds_write_b32 v4, v179
	s_or_b64 exec, exec, s[34:35]
	s_waitcnt lgkmcnt(6)
	v_pk_mul_f32 v[70:71], v[70:71], v[86:87]
	v_pk_mul_f32 v[68:69], v[68:69], v[84:85]
	v_pk_mul_f32 v[74:75], v[74:75], v[86:87]
	v_pk_mul_f32 v[72:73], v[72:73], v[84:85]
	v_cvt_pk_bf16_f32 v4, v68, v69
	v_cvt_pk_bf16_f32 v5, v70, v71
	v_pk_mul_f32 v[78:79], v[78:79], v[86:87]
	v_pk_mul_f32 v[76:77], v[76:77], v[84:85]
	ds_write_b64 v185, v[4:5] offset:63488
	v_cvt_pk_bf16_f32 v4, v72, v73
	v_cvt_pk_bf16_f32 v5, v74, v75
	s_or_b32 s69, s80, 7
	v_pk_mul_f32 v[82:83], v[82:83], v[86:87]
	v_pk_mul_f32 v[80:81], v[80:81], v[84:85]
	ds_write_b64 v186, v[4:5] offset:63488
	v_cvt_pk_bf16_f32 v4, v76, v77
	v_cvt_pk_bf16_f32 v5, v78, v79
	s_lshl_b32 s34, s69, 6
	ds_write_b64 v187, v[4:5] offset:63488
	v_cvt_pk_bf16_f32 v4, v80, v81
	v_cvt_pk_bf16_f32 v5, v82, v83
	s_or_b32 s90, s90, s34
	ds_write_b64 v188, v[4:5] offset:63488
	v_lshl_add_u64 v[4:5], s[90:91], 0, v[138:139]
	v_mov_b64_e32 v[14:15], s[52:53]
	v_mad_u64_u32 v[32:33], s[34:35], v4, s33, v[14:15]
	v_mad_i32_i24 v33, v5, s33, v33
	v_lshlrev_b64 v[4:5], 9, v[4:5]
	s_mov_b32 s77, s9
	v_lshl_add_u64 v[4:5], s[94:95], 0, v[4:5]
	v_lshl_add_u64 v[32:33], v[32:33], 0, s[76:77]
	v_lshl_add_u64 v[4:5], v[4:5], 0, s[76:77]
	v_lshl_add_u64 v[32:33], v[32:33], 0, v[2:3]
	v_lshl_add_u64 v[4:5], v[4:5], 0, v[2:3]
	global_load_dwordx4 v[36:39], v[32:33], off nt
	global_load_dwordx4 v[60:63], v[32:33], off offset:512 nt
	global_load_dwordx4 v[48:51], v[4:5], off nt
	v_lshl_add_u64 v[4:5], s[90:91], 0, v[136:137]
	v_mad_u64_u32 v[14:15], s[34:35], v4, s33, v[14:15]
	v_mad_i32_i24 v15, v5, s33, v15
	v_lshl_add_u64 v[4:5], v[14:15], 0, s[8:9]
	v_mov_b32_e32 v143, v3
	v_lshl_add_u64 v[4:5], v[4:5], 0, v[142:143]
	global_load_dwordx4 v[32:35], v[4:5], off offset:1024 nt
	v_add_co_u32_e32 v4, vcc, 0x4c000, v4
	s_nop 1
	v_addc_co_u32_e32 v5, vcc, 0, v5, vcc
	global_load_dwordx4 v[40:43], v[4:5], off offset:1024 nt
	s_and_saveexec_b64 s[34:35], s[2:3]
	s_cbranch_execz .LBB0_789
	s_lshl_b32 s58, s69, 10
	s_mov_b32 s59, s9
	v_lshl_add_u64 v[4:5], v[140:141], 0, s[58:59]
	s_lshl_b32 s58, s78, 2
	v_lshl_add_u64 v[4:5], v[4:5], 0, s[58:59]
	v_lshl_add_u64 v[4:5], v[134:135], 2, v[4:5]
	global_load_dword v179, v[4:5], off

; #define GAS __attribute__((address_space(1)))
; #define LAS __attribute__((address_space(3)))
; __device__ __forceinline__ float fsigmoid(float x) { return __builtin_amdgcn_rcpf(1.f + __builtin_amdgcn_exp2f(-LOG2E * x)); }
; __device__ __forceinline__ f32x4 bf4_to_f32(u32x2 w) { return (f32x4){bflo(w.x), bfhi(w.x), bflo(w.y), bfhi(w.y)}; }
; __device__ __forceinline__ u32x2 f32_to_bf4(f32x4 v) { u32x2 w; w.x = cvtpk(v[0], v[1]); w.y = cvtpk(v[2], v[3]); return w; }
; template <bool FULL> __device__ __forceinline__ void gla_unit(LAS unsigned char* lds, const MixBufs& B, int b, int h, int seg, int tid) {
;     ...
;             const float rstd = 1.f / sqrtf((SSQ[16 * ti + c] + SSQ[64 + 16 * ti + c]) * (1.f / 128.f) + EPS);
; #pragma unroll
;             for (int j = 0; j < 4; ++j) { const f32x4 gg = bf4_to_f32(gv[j]), gnj = *(const LAS f32x4*)(GNL + 16 * (4 * vh + j) + 4 * g);
;                 f32x4 r;
; #pragma unroll
;                 for (int i = 0; i < 4; ++i) r[i] = o[j][i] * rstd * gnj[i] * (gg[i] * fsigmoid(gg[i]));
;                 *(GAS u32x2*)(B.A_a + trow * 1024 + h * 128 + 16 * (4 * vh + j) + 4 * g) = f32_to_bf4(r); }
.LBB0_807:
	s_or_b64 exec, exec, s[34:35]
	s_waitcnt lgkmcnt(0)
	s_barrier
	ds_read2st64_b32 v[14:15], v191 offset1:1
	s_or_b32 s34, s73, 0x100
	v_or_b32_e32 v4, s34, v177
	v_mov_b32_e32 v5, s91
	v_lshlrev_b64 v[4:5], 11, v[4:5]
	s_waitcnt lgkmcnt(0)
	v_add_f32_e32 v2, v14, v15
	v_fmamk_f32 v2, v2, 0x3c000000, v182
	v_cmp_gt_f32_e32 vcc, s68, v2
	v_mul_f32_e32 v14, 0x4f800000, v2
	s_nop 0
	v_cndmask_b32_e32 v2, v2, v14, vcc
	v_sqrt_f32_e32 v14, v2
	s_nop 0
	v_add_u32_e32 v15, -1, v14
	v_fma_f32 v133, -v15, v14, v2
	v_cmp_ge_f32_e64 s[34:35], 0, v133
	v_add_u32_e32 v133, 1, v14
	s_nop 0
	v_cndmask_b32_e64 v15, v14, v15, s[34:35]
	v_fma_f32 v14, -v133, v14, v2
	v_cmp_lt_f32_e64 s[34:35], 0, v14
	s_nop 1
	v_cndmask_b32_e64 v14, v15, v133, s[34:35]
	v_mul_f32_e32 v15, 0x37800000, v14
	v_cndmask_b32_e32 v14, v14, v15, vcc
	v_cmp_class_f32_e32 vcc, v2, v1
	s_nop 1
	v_cndmask_b32_e32 v2, v14, v2, vcc
	v_div_scale_f32 v14, s[34:35], v2, v2, 1.0
	v_rcp_f32_e32 v15, v14
	v_readlane_b32 s34, v240, 14
	v_readlane_b32 s35, v240, 15
	v_fma_f32 v133, -v14, v15, 1.0
	v_fmac_f32_e32 v15, v133, v15
	v_div_scale_f32 v133, vcc, 1.0, v2, 1.0
	v_mul_f32_e32 v142, v133, v15
	v_fma_f32 v143, -v14, v142, v133
	v_fmac_f32_e32 v142, v143, v15
	v_fma_f32 v14, -v14, v142, v133
	v_div_fmas_f32 v14, v14, v15, v142
	v_div_fixup_f32 v2, v14, v2, 1.0
	s_waitcnt vmcnt(42)
	v_lshlrev_b32_e32 v14, 16, v166
	v_mul_f32_e32 v133, 0xbfb8aa3b, v14
	v_exp_f32_e32 v133, v133
	v_and_b32_e32 v15, 0xffff0000, v166
	ds_read_b128 v[142:145], v184
	v_pk_mul_f32 v[128:129], v[128:129], v[2:3] op_sel_hi:[1,0]
	v_add_f32_e32 v133, 1.0, v133
	v_rcp_f32_e32 v148, v133
	v_mul_f32_e32 v133, 0xbfb8aa3b, v15
	v_exp_f32_e32 v133, v133
	s_waitcnt lgkmcnt(0)
	v_pk_mul_f32 v[128:129], v[142:143], v[128:129]
	v_pk_mul_f32 v[130:131], v[130:131], v[2:3] op_sel_hi:[1,0]
	v_lshl_add_u64 v[4:5], s[34:35], 0, v[4:5]
	v_add_f32_e32 v133, 1.0, v133
	v_rcp_f32_e32 v149, v133
	v_pk_mul_f32 v[130:131], v[144:145], v[130:131]
	v_lshl_add_u64 v[4:5], v[4:5], 0, s[8:9]
	v_lshl_add_u64 v[4:5], s[60:61], 1, v[4:5]
	v_pk_mul_f32 v[14:15], v[148:149], v[14:15]
	v_pk_mul_f32 v[124:125], v[124:125], v[2:3] op_sel_hi:[1,0]
	v_pk_mul_f32 v[14:15], v[14:15], v[128:129]
	v_lshlrev_b32_e32 v128, 16, v167
	v_mul_f32_e32 v133, 0xbfb8aa3b, v128
	v_exp_f32_e32 v133, v133
	v_and_b32_e32 v129, 0xffff0000, v167
	v_cvt_pk_bf16_f32 v14, v14, v15
	v_pk_mul_f32 v[126:127], v[126:127], v[2:3] op_sel_hi:[1,0]
	v_add_f32_e32 v133, 1.0, v133
	v_rcp_f32_e32 v142, v133
	v_mul_f32_e32 v133, 0xbfb8aa3b, v129
	v_exp_f32_e32 v133, v133
	v_pk_mul_f32 v[120:121], v[120:121], v[2:3] op_sel_hi:[1,0]
	v_pk_mul_f32 v[122:123], v[122:123], v[2:3] op_sel_hi:[1,0]
	v_pk_mul_f32 v[116:117], v[116:117], v[2:3] op_sel_hi:[1,0]
	v_add_f32_e32 v133, 1.0, v133
	v_rcp_f32_e32 v143, v133
	v_mov_b32_e32 v133, v3
	v_lshl_add_u64 v[4:5], v[4:5], 0, v[132:133]
	v_pk_mul_f32 v[118:119], v[118:119], v[2:3] op_sel_hi:[1,0]
	v_pk_mul_f32 v[128:129], v[142:143], v[128:129]
	s_nop 0
	v_pk_mul_f32 v[128:129], v[128:129], v[130:131]
	s_nop 0
	v_cvt_pk_bf16_f32 v15, v128, v129
	ds_read_b128 v[128:131], v184 offset:64
	global_store_dwordx2 v[4:5], v[14:15], off sc1
	s_waitcnt vmcnt(42)
	v_lshlrev_b32_e32 v14, 16, v156
	v_and_b32_e32 v15, 0xffff0000, v156
	v_mul_f32_e32 v133, 0xbfb8aa3b, v14
	s_waitcnt lgkmcnt(0)
	v_pk_mul_f32 v[124:125], v[128:129], v[124:125]
	v_mul_f32_e32 v128, 0xbfb8aa3b, v15
	v_exp_f32_e32 v133, v133
	v_exp_f32_e32 v128, v128
	v_pk_mul_f32 v[126:127], v[130:131], v[126:127]
	v_add_f32_e32 v133, 1.0, v133
	v_add_f32_e32 v128, 1.0, v128
	v_rcp_f32_e32 v142, v133
	v_rcp_f32_e32 v143, v128
	s_nop 0
	v_pk_mul_f32 v[14:15], v[142:143], v[14:15]
	s_nop 0
	v_pk_mul_f32 v[14:15], v[14:15], v[124:125]
	v_lshlrev_b32_e32 v124, 16, v157
	v_and_b32_e32 v125, 0xffff0000, v157
	v_mul_f32_e32 v128, 0xbfb8aa3b, v124
	v_mul_f32_e32 v129, 0xbfb8aa3b, v125
	v_exp_f32_e32 v128, v128
	v_exp_f32_e32 v129, v129
	v_cvt_pk_bf16_f32 v14, v14, v15
	v_add_f32_e32 v128, 1.0, v128
	v_add_f32_e32 v129, 1.0, v129
	v_rcp_f32_e32 v128, v128
	v_rcp_f32_e32 v129, v129
	s_nop 0
	v_pk_mul_f32 v[124:125], v[128:129], v[124:125]
	s_nop 0
	v_pk_mul_f32 v[124:125], v[124:125], v[126:127]
	s_nop 0
	v_cvt_pk_bf16_f32 v15, v124, v125
	ds_read_b128 v[124:127], v184 offset:128
	global_store_dwordx2 v[4:5], v[14:15], off offset:32 sc1
	s_waitcnt vmcnt(42)
	v_lshlrev_b32_e32 v14, 16, v150
	v_and_b32_e32 v15, 0xffff0000, v150
	v_mul_f32_e32 v128, 0xbfb8aa3b, v14
	s_waitcnt lgkmcnt(0)
	v_pk_mul_f32 v[120:121], v[124:125], v[120:121]
	v_mul_f32_e32 v124, 0xbfb8aa3b, v15
	v_exp_f32_e32 v128, v128
	v_exp_f32_e32 v124, v124
	v_pk_mul_f32 v[122:123], v[126:127], v[122:123]
	v_add_f32_e32 v128, 1.0, v128
	v_add_f32_e32 v124, 1.0, v124
	v_rcp_f32_e32 v128, v128
	v_rcp_f32_e32 v129, v124
	s_nop 0
	v_pk_mul_f32 v[14:15], v[128:129], v[14:15]
	s_nop 0
	v_pk_mul_f32 v[14:15], v[14:15], v[120:121]
	v_lshlrev_b32_e32 v120, 16, v151
	v_and_b32_e32 v121, 0xffff0000, v151
	v_mul_f32_e32 v124, 0xbfb8aa3b, v120
	v_mul_f32_e32 v125, 0xbfb8aa3b, v121
	v_exp_f32_e32 v124, v124
	v_exp_f32_e32 v125, v125
	v_cvt_pk_bf16_f32 v14, v14, v15
	v_add_f32_e32 v124, 1.0, v124
	v_add_f32_e32 v125, 1.0, v125
	v_rcp_f32_e32 v124, v124
	v_rcp_f32_e32 v125, v125
	s_nop 0
	v_pk_mul_f32 v[120:121], v[124:125], v[120:121]
	s_nop 0
	v_pk_mul_f32 v[120:121], v[120:121], v[122:123]
	s_nop 0
	v_cvt_pk_bf16_f32 v15, v120, v121
	ds_read_b128 v[120:123], v184 offset:192
	global_store_dwordx2 v[4:5], v[14:15], off offset:64 sc1
	s_waitcnt vmcnt(42)
	v_lshlrev_b32_e32 v14, 16, v146
	v_and_b32_e32 v15, 0xffff0000, v146
	v_mul_f32_e32 v124, 0xbfb8aa3b, v14
	s_waitcnt lgkmcnt(0)
; template <bool FULL> __device__ __forceinline__ void gla_unit(LAS unsigned char* lds, const MixBufs& B, int b, int h, int seg, int tid) {
;     ...
;         { const v4u ee = re[st]; const f32x4 e0 = (f32x4){bflo(ee.x), bfhi(ee.x), bflo(ee.y), bfhi(ee.y)}, e1 = (f32x4){bflo(ee.z), bfhi(ee.z), bflo(ee.w), bfhi(ee.w)};
;           f32x4 i0, i1;
; #pragma unroll
;           for (int e = 0; e < 4; ++e) { i0[e] = __builtin_amdgcn_rcpf(e0[e]); i1[e] = __builtin_amdgcn_rcpf(e1[e]); }
;           *(LAS v4u*)(lds + okf + lr * GP64 + lc * 16) = mul_bf8(rk[st], i0, i1);
;           if (FULL) { *(LAS v4u*)(lds + G_KB + lr * GP64 + lc * 16) = mul_bf8(rk[st], e0, e1);
;                       *(LAS v4u*)(lds + G_QF + lr * GP64 + lc * 16) = mul_bf8(rq[st], e0, e1); *(LAS v4u*)(lds + G_QB + lr * GP64 + lc * 16) = mul_bf8(rq[st], i0, i1); } }
;         *(LAS v4u*)(lds + ov + vr * GP128 + vc * 16) = rv0[st]; *(LAS v4u*)(lds + ov + (vr + 32) * GP128 + vc * 16) = rv1[st];
;         if (tid < 64) DLc[tid] = rdl[st];
;         if (FULL) {
; #pragma unroll
;             for (int j = 0; j < 4; ++j) *(LAS u32x2*)(lds + G_ST + (16 * (4 * vh + j) + c) * GP64 + (16 * kt + 4 * g) * 2) = f32_to_bf4(S[j]);
;         }
;         const size_t trow = t0 + 16 * ti + c;
;         u32x2 gv[4];
;         if (FULL) {
; #pragma unroll
;             for (int j = 0; j < 4; ++j) gv[j] = gvp[st][j];
;         }
;         if (ci + 3 < 8) GLA_PREFETCH(st, ch + 3);
;         __syncthreads();
;         bf16x8 vfr[4][2];
; #pragma unroll
;         for (int j = 0; j < 4; ++j)
; #pragma unroll
;             for (int ks = 0; ks < 2; ++ks) vfr[j][ks] = frag_tr(lds + ov, GP128, 32 * ks, 16 * (4 * vh + j), lane);
;         if (FULL) {
; #pragma unroll
;             for (int jj = 0; jj < 2; ++jj) { const int sj = 2 * sh + jj;
;                 f32x4 af = (f32x4){0.f, 0.f, 0.f, 0.f}, ab = (f32x4){0.f, 0.f, 0.f, 0.f};
; #pragma unroll
;                 for (int ks = 0; ks < 2; ++ks) {
;                     if (ti >= sj) af = MFMA16(frag_row(lds + okf, GP64, 16 * sj, 32 * ks, lane), frag_row(lds + G_QF, GP64, 16 * ti, 32 * ks, lane), af);
;     ...
;                 *(GAS u32x2*)(B.A_a + trow * 1024 + h * 128 + 16 * (4 * vh + j) + 4 * g) = f32_to_bf4(r); }
;         }
; #pragma unroll
;         for (int ks = 0; ks < 2; ++ks) { const bf16x8 kf = frag_tr(lds + okf, GP64, 32 * ks, 16 * kt, lane);
; #pragma unroll
	v_pk_mul_f32 v[116:117], v[116:117], v[120:121]
	v_mul_f32_e32 v120, 0xbfb8aa3b, v15
	v_exp_f32_e32 v124, v124
	v_exp_f32_e32 v120, v120
	v_pk_mul_f32 v[118:119], v[118:119], v[122:123]
	v_add_f32_e32 v124, 1.0, v124
	v_add_f32_e32 v120, 1.0, v120
	v_rcp_f32_e32 v124, v124
	v_rcp_f32_e32 v125, v120
	s_nop 0
	v_pk_mul_f32 v[14:15], v[124:125], v[14:15]
	s_nop 0
	v_pk_mul_f32 v[14:15], v[14:15], v[116:117]
	v_lshlrev_b32_e32 v116, 16, v147
	v_and_b32_e32 v117, 0xffff0000, v147
	v_mul_f32_e32 v120, 0xbfb8aa3b, v116
	v_mul_f32_e32 v2, 0xbfb8aa3b, v117
	v_exp_f32_e32 v120, v120
	v_exp_f32_e32 v2, v2
	v_cvt_pk_bf16_f32 v14, v14, v15
	v_add_f32_e32 v120, 1.0, v120
	v_add_f32_e32 v2, 1.0, v2
	v_rcp_f32_e32 v120, v120
	v_rcp_f32_e32 v121, v2
	s_nop 0
	v_pk_mul_f32 v[116:117], v[120:121], v[116:117]
	s_nop 0
	v_pk_mul_f32 v[116:117], v[116:117], v[118:119]
	s_nop 0
	v_cvt_pk_bf16_f32 v15, v116, v117
	global_store_dwordx2 v[4:5], v[14:15], off offset:96 sc1
	ds_read_b64_tr_b16 v[116:117], v210 offset:18432
	ds_read_b64_tr_b16 v[118:119], v210 offset:19008
	s_waitcnt lgkmcnt(0)
	v_mfma_f32_16x16x32_bf16 v[68:71], v[116:119], v[104:107], v[68:71]
	ds_read_b64_tr_b16 v[104:105], v210 offset:23040
	ds_read_b64_tr_b16 v[106:107], v210 offset:23616
	s_waitcnt vmcnt(37)
	v_lshlrev_b32_e32 v4, 16, v56
	v_and_b32_e32 v5, 0xffff0000, v56
	v_mfma_f32_16x16x32_bf16 v[72:75], v[116:119], v[100:103], v[72:75]
	v_lshlrev_b32_e32 v14, 16, v57
	v_and_b32_e32 v15, 0xffff0000, v57
	v_mfma_f32_16x16x32_bf16 v[100:103], v[116:119], v[112:115], v[80:83]
	s_waitcnt lgkmcnt(0)
	v_mfma_f32_16x16x32_bf16 v[80:83], v[104:107], v[96:99], v[68:71]
	v_mfma_f32_16x16x32_bf16 v[68:71], v[104:107], v[92:95], v[72:75]
	s_waitcnt vmcnt(36)
	v_lshlrev_b32_e32 v92, 16, v44
	v_and_b32_e32 v93, 0xffff0000, v44
	v_rcp_f32_e32 v94, v92
	v_rcp_f32_e32 v95, v93
	v_mfma_f32_16x16x32_bf16 v[76:79], v[116:119], v[108:111], v[76:79]
	v_mul_f32_e64 v56, v94, v4
	v_mul_f32_e64 v57, v95, v5
	v_pk_mul_f32 v[4:5], v[4:5], v[92:93]
	v_cvt_pk_bf16_f32 v44, v56, v57
	v_cvt_pk_bf16_f32 v56, v4, v5
	v_lshlrev_b32_e32 v4, 16, v45
	v_and_b32_e32 v5, 0xffff0000, v45
	v_rcp_f32_e32 v96, v4
	v_rcp_f32_e32 v97, v5
	v_mfma_f32_16x16x32_bf16 v[72:75], v[104:107], v[88:91], v[76:79]
	v_lshlrev_b32_e32 v88, 16, v58
	v_and_b32_e32 v89, 0xffff0000, v58
	v_lshlrev_b32_e32 v90, 16, v59
	v_and_b32_e32 v91, 0xffff0000, v59
	v_pk_mul_f32 v[58:59], v[96:97], v[14:15]
	v_pk_mul_f32 v[14:15], v[14:15], v[4:5]
	v_cvt_pk_bf16_f32 v45, v58, v59
	v_cvt_pk_bf16_f32 v57, v14, v15
	v_lshlrev_b32_e32 v14, 16, v46
	v_and_b32_e32 v15, 0xffff0000, v46
	v_rcp_f32_e32 v98, v14
	v_rcp_f32_e32 v99, v15
	v_mfma_f32_16x16x32_bf16 v[76:79], v[104:107], v[84:87], v[100:103]
	ds_read_b128 v[84:87], v203
	v_pk_mul_f32 v[58:59], v[98:99], v[88:89]
	s_nop 0
	v_cvt_pk_bf16_f32 v46, v58, v59
	v_pk_mul_f32 v[58:59], v[88:89], v[14:15]
	v_lshlrev_b32_e32 v88, 16, v47
	v_and_b32_e32 v89, 0xffff0000, v47
	v_rcp_f32_e32 v100, v88
	v_rcp_f32_e32 v101, v89
	v_cvt_pk_bf16_f32 v58, v58, v59
	v_pk_mul_f32 v[102:103], v[100:101], v[90:91]
	s_nop 0
	v_cvt_pk_bf16_f32 v47, v102, v103
	ds_write_b128 v176, v[44:47]
	v_pk_mul_f32 v[44:45], v[90:91], v[88:89]
	s_nop 0
	v_cvt_pk_bf16_f32 v59, v44, v45
	v_lshlrev_b32_e32 v44, 16, v24
	v_and_b32_e32 v45, 0xffff0000, v24
	v_pk_mul_f32 v[46:47], v[44:45], v[92:93]
	ds_write_b128 v180, v[56:59] offset:27648
	v_cvt_pk_bf16_f32 v24, v46, v47
	v_lshlrev_b32_e32 v46, 16, v25
	v_and_b32_e32 v47, 0xffff0000, v25
	v_pk_mul_f32 v[4:5], v[46:47], v[4:5]
	s_nop 0
	v_cvt_pk_bf16_f32 v25, v4, v5
	v_lshlrev_b32_e32 v4, 16, v26
	v_and_b32_e32 v5, 0xffff0000, v26
	v_pk_mul_f32 v[14:15], v[4:5], v[14:15]
	v_pk_mul_f32 v[4:5], v[98:99], v[4:5]
	v_cvt_pk_bf16_f32 v26, v14, v15
	v_lshlrev_b32_e32 v14, 16, v27
	v_and_b32_e32 v15, 0xffff0000, v27
	v_pk_mul_f32 v[56:57], v[14:15], v[88:89]
	s_nop 0
	v_cvt_pk_bf16_f32 v27, v56, v57
	ds_write_b128 v180, v[24:27]
	v_pk_mul_f32 v[24:25], v[94:95], v[44:45]
	v_pk_mul_f32 v[26:27], v[96:97], v[46:47]
	v_cvt_pk_bf16_f32 v24, v24, v25
	v_cvt_pk_bf16_f32 v25, v26, v27
	v_cvt_pk_bf16_f32 v26, v4, v5
	v_pk_mul_f32 v[4:5], v[100:101], v[14:15]
	s_nop 0
	v_cvt_pk_bf16_f32 v27, v4, v5
	ds_write_b128 v180, v[24:27] offset:9216
	s_waitcnt vmcnt(35)
	ds_write_b128 v181, v[16:19] offset:36864
	s_waitcnt vmcnt(34)
	ds_write_b128 v181, v[28:31] offset:45568
	s_and_saveexec_b64 s[34:35], s[2:3]
	v_add_u32_e32 v2, 0x16c00, v178
	ds_write_b32 v2, v207
	s_or_b64 exec, exec, s[34:35]
	s_waitcnt lgkmcnt(6)
	v_pk_mul_f32 v[58:59], v[82:83], v[86:87]
	v_pk_mul_f32 v[56:57], v[80:81], v[84:85]
	v_pk_mul_f32 v[70:71], v[70:71], v[86:87]
	v_pk_mul_f32 v[68:69], v[68:69], v[84:85]
	v_cvt_pk_bf16_f32 v4, v56, v57
	v_cvt_pk_bf16_f32 v5, v58, v59
	v_pk_mul_f32 v[74:75], v[74:75], v[86:87]
	v_pk_mul_f32 v[72:73], v[72:73], v[84:85]
	ds_write_b64 v185, v[4:5] offset:63488
	v_cvt_pk_bf16_f32 v4, v68, v69
	v_cvt_pk_bf16_f32 v5, v70, v71
	v_pk_mul_f32 v[78:79], v[78:79], v[86:87]
	v_pk_mul_f32 v[76:77], v[76:77], v[84:85]
	ds_write_b64 v186, v[4:5] offset:63488
	v_cvt_pk_bf16_f32 v4, v72, v73
	v_cvt_pk_bf16_f32 v5, v74, v75
	ds_write_b64 v187, v[4:5] offset:63488
	v_cvt_pk_bf16_f32 v4, v76, v77
	v_cvt_pk_bf16_f32 v5, v78, v79
	ds_write_b64 v188, v[4:5] offset:63488
	s_waitcnt lgkmcnt(0)
	s_barrier
	ds_read_b64_tr_b16 v[84:85], v206 offset:36864
	ds_read_b64_tr_b16 v[80:81], v206 offset:36896
	ds_read_b64_tr_b16 v[88:89], v206 offset:36928
	ds_read_b64_tr_b16 v[92:93], v206 offset:36960
	ds_read_b64_tr_b16 v[86:87], v206 offset:37952
	ds_read_b64_tr_b16 v[82:83], v206 offset:37984
	ds_read_b64_tr_b16 v[90:91], v206 offset:38016
	ds_read_b64_tr_b16 v[94:95], v206 offset:38048
	ds_read_b64_tr_b16 v[44:45], v206 offset:45568
	ds_read_b64_tr_b16 v[28:29], v206 offset:45600
	ds_read_b64_tr_b16 v[24:25], v206 offset:45632
	ds_read_b64_tr_b16 v[14:15], v206 offset:45664
	ds_read_b64_tr_b16 v[46:47], v206 offset:46656
	ds_read_b64_tr_b16 v[30:31], v206 offset:46688
	ds_read_b64_tr_b16 v[26:27], v206 offset:46720
	ds_read_b64_tr_b16 v[16:17], v206 offset:46752
	s_and_b64 vcc, exec, s[74:75]
	s_cbranch_vccnz .LBB0_812
	ds_read_b128 v[96:99], v205
	ds_read_b128 v[100:103], v189
	s_waitcnt lgkmcnt(0)
	v_mfma_f32_16x16x32_bf16 v[96:99], v[96:99], v[100:103], 0
	s_and_b64 vcc, exec, s[10:11]
	s_cbranch_vccz .LBB0_813

; #define GAS __attribute__((address_space(1)))
; #define LAS __attribute__((address_space(3)))
; __device__ __forceinline__ float fsigmoid(float x) { return __builtin_amdgcn_rcpf(1.f + __builtin_amdgcn_exp2f(-LOG2E * x)); }
; __device__ __forceinline__ f32x4 bf4_to_f32(u32x2 w) { return (f32x4){bflo(w.x), bfhi(w.x), bflo(w.y), bfhi(w.y)}; }
; __device__ __forceinline__ u32x2 f32_to_bf4(f32x4 v) { u32x2 w; w.x = cvtpk(v[0], v[1]); w.y = cvtpk(v[2], v[3]); return w; }
; template <bool FULL> __device__ __forceinline__ void gla_unit(LAS unsigned char* lds, const MixBufs& B, int b, int h, int seg, int tid) {
;     ...
;             const float rstd = 1.f / sqrtf((SSQ[16 * ti + c] + SSQ[64 + 16 * ti + c]) * (1.f / 128.f) + EPS);
; #pragma unroll
;             for (int j = 0; j < 4; ++j) { const f32x4 gg = bf4_to_f32(gv[j]), gnj = *(const LAS f32x4*)(GNL + 16 * (4 * vh + j) + 4 * g);
;                 f32x4 r;
; #pragma unroll
;                 for (int i = 0; i < 4; ++i) r[i] = o[j][i] * rstd * gnj[i] * (gg[i] * fsigmoid(gg[i]));
;                 *(GAS u32x2*)(B.A_a + trow * 1024 + h * 128 + 16 * (4 * vh + j) + 4 * g) = f32_to_bf4(r); }
.LBB0_827:
	s_or_b64 exec, exec, s[34:35]
	s_waitcnt lgkmcnt(0)
	s_barrier
	ds_read2st64_b32 v[18:19], v191 offset1:1
	s_or_b32 s34, s73, 0x140
	v_or_b32_e32 v4, s34, v177
	v_mov_b32_e32 v5, s91
	v_lshlrev_b64 v[4:5], 11, v[4:5]
	s_waitcnt lgkmcnt(0)
	v_add_f32_e32 v2, v18, v19
	v_fmamk_f32 v2, v2, 0x3c000000, v182
	v_cmp_gt_f32_e32 vcc, s68, v2
	v_mul_f32_e32 v18, 0x4f800000, v2
	v_mov_b32_e32 v133, v3
	v_cndmask_b32_e32 v2, v2, v18, vcc
	v_sqrt_f32_e32 v18, v2
	s_nop 0
	v_add_u32_e32 v19, -1, v18
	v_fma_f32 v112, -v19, v18, v2
	v_cmp_ge_f32_e64 s[34:35], 0, v112
	v_add_u32_e32 v112, 1, v18
	s_nop 0
	v_cndmask_b32_e64 v19, v18, v19, s[34:35]
	v_fma_f32 v18, -v112, v18, v2
	v_cmp_lt_f32_e64 s[34:35], 0, v18
	s_nop 1
	v_cndmask_b32_e64 v18, v19, v112, s[34:35]
	v_mul_f32_e32 v19, 0x37800000, v18
	v_cndmask_b32_e32 v18, v18, v19, vcc
	v_cmp_class_f32_e32 vcc, v2, v1
	s_nop 1
	v_cndmask_b32_e32 v2, v18, v2, vcc
	v_div_scale_f32 v18, s[34:35], v2, v2, 1.0
	v_rcp_f32_e32 v19, v18
	v_readlane_b32 s34, v240, 14
	v_readlane_b32 s35, v240, 15
	v_fma_f32 v112, -v18, v19, 1.0
	v_fmac_f32_e32 v19, v112, v19
	v_div_scale_f32 v112, vcc, 1.0, v2, 1.0
	v_mul_f32_e32 v113, v112, v19
	v_fma_f32 v114, -v18, v113, v112
	v_fmac_f32_e32 v113, v114, v19
	v_fma_f32 v18, -v18, v113, v112
	v_div_fmas_f32 v18, v18, v19, v113
	ds_read_b128 v[112:115], v184
	v_div_fixup_f32 v2, v18, v2, 1.0
	s_waitcnt vmcnt(33)
	v_lshlrev_b32_e32 v18, 16, v172
	v_and_b32_e32 v19, 0xffff0000, v172
	v_pk_mul_f32 v[108:109], v[108:109], v[2:3] op_sel_hi:[1,0]
	v_mul_f32_e32 v116, 0xbfb8aa3b, v18
	s_waitcnt lgkmcnt(0)
	v_pk_mul_f32 v[108:109], v[112:113], v[108:109]
	v_mul_f32_e32 v112, 0xbfb8aa3b, v19
	v_exp_f32_e32 v116, v116
	v_exp_f32_e32 v112, v112
	v_pk_mul_f32 v[110:111], v[110:111], v[2:3] op_sel_hi:[1,0]
	v_lshl_add_u64 v[4:5], s[34:35], 0, v[4:5]
	v_add_f32_e32 v116, 1.0, v116
	v_add_f32_e32 v112, 1.0, v112
	v_rcp_f32_e32 v116, v116
	v_rcp_f32_e32 v117, v112
	v_pk_mul_f32 v[110:111], v[114:115], v[110:111]
	v_lshl_add_u64 v[4:5], v[4:5], 0, s[8:9]
	v_lshl_add_u64 v[4:5], s[60:61], 1, v[4:5]
	v_pk_mul_f32 v[18:19], v[116:117], v[18:19]
	v_lshl_add_u64 v[4:5], v[4:5], 0, v[132:133]
	v_pk_mul_f32 v[18:19], v[18:19], v[108:109]
	v_lshlrev_b32_e32 v108, 16, v173
	v_and_b32_e32 v109, 0xffff0000, v173
	v_mul_f32_e32 v112, 0xbfb8aa3b, v108
	v_mul_f32_e32 v113, 0xbfb8aa3b, v109
	v_exp_f32_e32 v112, v112
	v_exp_f32_e32 v113, v113
	v_cvt_pk_bf16_f32 v18, v18, v19
	v_pk_mul_f32 v[104:105], v[104:105], v[2:3] op_sel_hi:[1,0]
	v_add_f32_e32 v112, 1.0, v112
	v_add_f32_e32 v113, 1.0, v113
	v_rcp_f32_e32 v112, v112
	v_rcp_f32_e32 v113, v113
	v_pk_mul_f32 v[106:107], v[106:107], v[2:3] op_sel_hi:[1,0]
	v_pk_mul_f32 v[100:101], v[100:101], v[2:3] op_sel_hi:[1,0]
	v_pk_mul_f32 v[102:103], v[102:103], v[2:3] op_sel_hi:[1,0]
	v_pk_mul_f32 v[108:109], v[112:113], v[108:109]
	v_pk_mul_f32 v[96:97], v[96:97], v[2:3] op_sel_hi:[1,0]
	v_pk_mul_f32 v[108:109], v[108:109], v[110:111]
	v_pk_mul_f32 v[98:99], v[98:99], v[2:3] op_sel_hi:[1,0]
	v_cvt_pk_bf16_f32 v19, v108, v109
	ds_read_b128 v[108:111], v184 offset:64
	global_store_dwordx2 v[4:5], v[18:19], off sc1
	s_waitcnt vmcnt(33)
	v_lshlrev_b32_e32 v18, 16, v162
	v_and_b32_e32 v19, 0xffff0000, v162
	v_mul_f32_e32 v112, 0xbfb8aa3b, v18
	s_waitcnt lgkmcnt(0)
	v_pk_mul_f32 v[104:105], v[108:109], v[104:105]
	v_mul_f32_e32 v108, 0xbfb8aa3b, v19
	v_exp_f32_e32 v112, v112
	v_exp_f32_e32 v108, v108
	v_pk_mul_f32 v[106:107], v[110:111], v[106:107]
	v_add_f32_e32 v112, 1.0, v112
	v_add_f32_e32 v108, 1.0, v108
	v_rcp_f32_e32 v112, v112
	v_rcp_f32_e32 v113, v108
	s_nop 0
	v_pk_mul_f32 v[18:19], v[112:113], v[18:19]
	s_nop 0
	v_pk_mul_f32 v[18:19], v[18:19], v[104:105]
	v_lshlrev_b32_e32 v104, 16, v163
	v_and_b32_e32 v105, 0xffff0000, v163
	v_mul_f32_e32 v108, 0xbfb8aa3b, v104
	v_mul_f32_e32 v109, 0xbfb8aa3b, v105
	v_exp_f32_e32 v108, v108
	v_exp_f32_e32 v109, v109
	v_cvt_pk_bf16_f32 v18, v18, v19
	v_add_f32_e32 v108, 1.0, v108
	v_add_f32_e32 v109, 1.0, v109
	v_rcp_f32_e32 v108, v108
	v_rcp_f32_e32 v109, v109
	s_nop 0
	v_pk_mul_f32 v[104:105], v[108:109], v[104:105]
	s_nop 0
	v_pk_mul_f32 v[104:105], v[104:105], v[106:107]
	s_nop 0
	v_cvt_pk_bf16_f32 v19, v104, v105
	ds_read_b128 v[104:107], v184 offset:128
	global_store_dwordx2 v[4:5], v[18:19], off offset:32 sc1
	s_waitcnt vmcnt(33)
	v_lshlrev_b32_e32 v18, 16, v158
	v_and_b32_e32 v19, 0xffff0000, v158
	v_mul_f32_e32 v108, 0xbfb8aa3b, v18
	s_waitcnt lgkmcnt(0)
	v_pk_mul_f32 v[100:101], v[104:105], v[100:101]
	v_mul_f32_e32 v104, 0xbfb8aa3b, v19
	v_exp_f32_e32 v108, v108
	v_exp_f32_e32 v104, v104
	v_pk_mul_f32 v[102:103], v[106:107], v[102:103]
	v_add_f32_e32 v108, 1.0, v108
	v_add_f32_e32 v104, 1.0, v104
	v_rcp_f32_e32 v108, v108
	v_rcp_f32_e32 v109, v104
	s_nop 0
	v_pk_mul_f32 v[18:19], v[108:109], v[18:19]
	s_nop 0
	v_pk_mul_f32 v[18:19], v[18:19], v[100:101]
	v_lshlrev_b32_e32 v100, 16, v159
	v_and_b32_e32 v101, 0xffff0000, v159
	v_mul_f32_e32 v104, 0xbfb8aa3b, v100
	v_mul_f32_e32 v105, 0xbfb8aa3b, v101
	v_exp_f32_e32 v104, v104
	v_exp_f32_e32 v105, v105
	v_cvt_pk_bf16_f32 v18, v18, v19
	v_add_f32_e32 v104, 1.0, v104
	v_add_f32_e32 v105, 1.0, v105
	v_rcp_f32_e32 v104, v104
	v_rcp_f32_e32 v105, v105
	s_nop 0
	v_pk_mul_f32 v[100:101], v[104:105], v[100:101]
	s_nop 0
	v_pk_mul_f32 v[100:101], v[100:101], v[102:103]
	s_nop 0
	v_cvt_pk_bf16_f32 v19, v100, v101
	ds_read_b128 v[100:103], v184 offset:192
	global_store_dwordx2 v[4:5], v[18:19], off offset:64 sc1
	s_waitcnt vmcnt(33)
	v_lshlrev_b32_e32 v18, 16, v152
	v_and_b32_e32 v19, 0xffff0000, v152
	v_mul_f32_e32 v104, 0xbfb8aa3b, v18
	s_waitcnt lgkmcnt(0)
; template <bool FULL> __device__ __forceinline__ void gla_unit(LAS unsigned char* lds, const MixBufs& B, int b, int h, int seg, int tid) {
;     ...
;         { const v4u ee = re[st]; const f32x4 e0 = (f32x4){bflo(ee.x), bfhi(ee.x), bflo(ee.y), bfhi(ee.y)}, e1 = (f32x4){bflo(ee.z), bfhi(ee.z), bflo(ee.w), bfhi(ee.w)};
;           f32x4 i0, i1;
; #pragma unroll
;           for (int e = 0; e < 4; ++e) { i0[e] = __builtin_amdgcn_rcpf(e0[e]); i1[e] = __builtin_amdgcn_rcpf(e1[e]); }
;           *(LAS v4u*)(lds + okf + lr * GP64 + lc * 16) = mul_bf8(rk[st], i0, i1);
;           if (FULL) { *(LAS v4u*)(lds + G_KB + lr * GP64 + lc * 16) = mul_bf8(rk[st], e0, e1);
;                       *(LAS v4u*)(lds + G_QF + lr * GP64 + lc * 16) = mul_bf8(rq[st], e0, e1); *(LAS v4u*)(lds + G_QB + lr * GP64 + lc * 16) = mul_bf8(rq[st], i0, i1); } }
;         *(LAS v4u*)(lds + ov + vr * GP128 + vc * 16) = rv0[st]; *(LAS v4u*)(lds + ov + (vr + 32) * GP128 + vc * 16) = rv1[st];
;         if (tid < 64) DLc[tid] = rdl[st];
;         if (FULL) {
; #pragma unroll
;             for (int j = 0; j < 4; ++j) *(LAS u32x2*)(lds + G_ST + (16 * (4 * vh + j) + c) * GP64 + (16 * kt + 4 * g) * 2) = f32_to_bf4(S[j]);
;         }
;         const size_t trow = t0 + 16 * ti + c;
;         u32x2 gv[4];
;         if (FULL) {
; #pragma unroll
;             for (int j = 0; j < 4; ++j) gv[j] = gvp[st][j];
;         }
;         if (ci + 3 < 8) GLA_PREFETCH(st, ch + 3);
;         __syncthreads();
;         bf16x8 vfr[4][2];
; #pragma unroll
;         for (int j = 0; j < 4; ++j)
; #pragma unroll
;             for (int ks = 0; ks < 2; ++ks) vfr[j][ks] = frag_tr(lds + ov, GP128, 32 * ks, 16 * (4 * vh + j), lane);
;         if (FULL) {
; #pragma unroll
;             for (int jj = 0; jj < 2; ++jj) { const int sj = 2 * sh + jj;
;                 f32x4 af = (f32x4){0.f, 0.f, 0.f, 0.f}, ab = (f32x4){0.f, 0.f, 0.f, 0.f};
; #pragma unroll
;                 for (int ks = 0; ks < 2; ++ks) {
;                     if (ti >= sj) af = MFMA16(frag_row(lds + okf, GP64, 16 * sj, 32 * ks, lane), frag_row(lds + G_QF, GP64, 16 * ti, 32 * ks, lane), af);
;     ...
;                 *(GAS u32x2*)(B.A_a + trow * 1024 + h * 128 + 16 * (4 * vh + j) + 4 * g) = f32_to_bf4(r); }
;         }
; #pragma unroll
;         for (int ks = 0; ks < 2; ++ks) { const bf16x8 kf = frag_tr(lds + okf, GP64, 32 * ks, 16 * kt, lane);
; #pragma unroll
	v_pk_mul_f32 v[96:97], v[96:97], v[100:101]
	v_mul_f32_e32 v100, 0xbfb8aa3b, v19
	v_exp_f32_e32 v104, v104
	v_exp_f32_e32 v100, v100
	v_pk_mul_f32 v[98:99], v[98:99], v[102:103]
	v_add_f32_e32 v104, 1.0, v104
	v_add_f32_e32 v100, 1.0, v100
	v_rcp_f32_e32 v104, v104
	v_rcp_f32_e32 v105, v100
	s_nop 0
	v_pk_mul_f32 v[18:19], v[104:105], v[18:19]
	s_nop 0
	v_pk_mul_f32 v[18:19], v[18:19], v[96:97]
	v_lshlrev_b32_e32 v96, 16, v153
	v_and_b32_e32 v97, 0xffff0000, v153
	v_mul_f32_e32 v100, 0xbfb8aa3b, v96
	v_mul_f32_e32 v2, 0xbfb8aa3b, v97
	v_exp_f32_e32 v100, v100
	v_exp_f32_e32 v2, v2
	v_cvt_pk_bf16_f32 v18, v18, v19
	v_add_f32_e32 v100, 1.0, v100
	v_add_f32_e32 v2, 1.0, v2
	v_rcp_f32_e32 v100, v100
	v_rcp_f32_e32 v101, v2
	s_nop 0
	v_pk_mul_f32 v[96:97], v[100:101], v[96:97]
	s_nop 0
	v_pk_mul_f32 v[96:97], v[96:97], v[98:99]
	s_nop 0
	v_cvt_pk_bf16_f32 v19, v96, v97
	global_store_dwordx2 v[4:5], v[18:19], off offset:96 sc1
	ds_read_b64_tr_b16 v[96:97], v208
	ds_read_b64_tr_b16 v[98:99], v208 offset:576
	s_waitcnt lgkmcnt(0)
	v_mfma_f32_16x16x32_bf16 v[68:71], v[96:99], v[80:83], v[68:71]
	ds_read_b64_tr_b16 v[80:81], v208 offset:4608
	ds_read_b64_tr_b16 v[82:83], v208 offset:5184
	s_waitcnt vmcnt(28)
	v_lshlrev_b32_e32 v4, 16, v64
	v_and_b32_e32 v5, 0xffff0000, v64
	v_mfma_f32_16x16x32_bf16 v[56:59], v[96:99], v[84:87], v[56:59]
	v_lshlrev_b32_e32 v18, 16, v65
	v_and_b32_e32 v19, 0xffff0000, v65
	v_lshlrev_b32_e32 v64, 16, v67
	v_mfma_f32_16x16x32_bf16 v[76:79], v[96:99], v[92:95], v[76:79]
	v_and_b32_e32 v65, 0xffff0000, v67
	s_waitcnt vmcnt(27)
	v_and_b32_e32 v67, 0xffff0000, v52
	s_waitcnt lgkmcnt(0)
	v_mfma_f32_16x16x32_bf16 v[44:47], v[80:83], v[44:47], v[56:59]
	v_mfma_f32_16x16x32_bf16 v[56:59], v[80:83], v[28:31], v[68:71]
	v_lshlrev_b32_e32 v30, 16, v66
	v_and_b32_e32 v31, 0xffff0000, v66
	v_lshlrev_b32_e32 v66, 16, v52
	v_mfma_f32_16x16x32_bf16 v[72:75], v[96:99], v[88:91], v[72:75]
	v_mfma_f32_16x16x32_bf16 v[14:17], v[80:83], v[14:17], v[76:79]
	s_nop 2
	v_rcp_f32_e32 v76, v66
	v_rcp_f32_e32 v77, v67
	v_mfma_f32_16x16x32_bf16 v[68:71], v[80:83], v[24:27], v[72:75]
	v_mul_f32_e64 v24, v76, v4
	v_mul_f32_e64 v25, v77, v5
	v_pk_mul_f32 v[4:5], v[4:5], v[66:67]
	v_cvt_pk_bf16_f32 v24, v24, v25
	v_cvt_pk_bf16_f32 v28, v4, v5
	v_lshlrev_b32_e32 v4, 16, v53
	v_and_b32_e32 v5, 0xffff0000, v53
	v_rcp_f32_e32 v52, v4
	v_rcp_f32_e32 v53, v5
	ds_read_b128 v[72:75], v209
	v_pk_mul_f32 v[26:27], v[52:53], v[18:19]
	v_pk_mul_f32 v[18:19], v[18:19], v[4:5]
	v_cvt_pk_bf16_f32 v25, v26, v27
	v_cvt_pk_bf16_f32 v29, v18, v19
	v_lshlrev_b32_e32 v18, 16, v54
	v_and_b32_e32 v19, 0xffff0000, v54
	v_lshlrev_b32_e32 v54, 16, v55
	v_and_b32_e32 v55, 0xffff0000, v55
	v_rcp_f32_e32 v78, v18
	v_rcp_f32_e32 v79, v19
	v_rcp_f32_e32 v80, v54
	v_rcp_f32_e32 v81, v55
	v_pk_mul_f32 v[26:27], v[78:79], v[30:31]
	s_nop 0
	v_cvt_pk_bf16_f32 v26, v26, v27
	v_pk_mul_f32 v[82:83], v[80:81], v[64:65]
	v_pk_mul_f32 v[30:31], v[30:31], v[18:19]
	v_cvt_pk_bf16_f32 v27, v82, v83
	ds_write_b128 v180, v[24:27] offset:18432
	v_pk_mul_f32 v[24:25], v[64:65], v[54:55]
	v_cvt_pk_bf16_f32 v30, v30, v31
	v_cvt_pk_bf16_f32 v31, v24, v25
	v_lshlrev_b32_e32 v24, 16, v10
	v_and_b32_e32 v25, 0xffff0000, v10
	v_pk_mul_f32 v[26:27], v[24:25], v[66:67]
	ds_write_b128 v180, v[28:31] offset:27648
	v_cvt_pk_bf16_f32 v10, v26, v27
	v_lshlrev_b32_e32 v26, 16, v11
	v_and_b32_e32 v27, 0xffff0000, v11
	v_pk_mul_f32 v[4:5], v[26:27], v[4:5]
	s_nop 0
	v_cvt_pk_bf16_f32 v11, v4, v5
	v_lshlrev_b32_e32 v4, 16, v12
	v_and_b32_e32 v5, 0xffff0000, v12
	v_pk_mul_f32 v[18:19], v[4:5], v[18:19]
	v_pk_mul_f32 v[4:5], v[78:79], v[4:5]
	v_cvt_pk_bf16_f32 v12, v18, v19
	v_lshlrev_b32_e32 v18, 16, v13
	v_and_b32_e32 v19, 0xffff0000, v13
	v_pk_mul_f32 v[28:29], v[18:19], v[54:55]
	s_nop 0
	v_cvt_pk_bf16_f32 v13, v28, v29
	ds_write_b128 v180, v[10:13]
	v_pk_mul_f32 v[10:11], v[76:77], v[24:25]
	v_pk_mul_f32 v[12:13], v[52:53], v[26:27]
	v_cvt_pk_bf16_f32 v10, v10, v11
	v_cvt_pk_bf16_f32 v11, v12, v13
	v_cvt_pk_bf16_f32 v12, v4, v5
	v_pk_mul_f32 v[4:5], v[80:81], v[18:19]
	s_nop 0
	v_cvt_pk_bf16_f32 v13, v4, v5
	ds_write_b128 v180, v[10:13] offset:9216
	s_waitcnt vmcnt(26)
	ds_write_b128 v181, v[6:9] offset:36864
	s_waitcnt vmcnt(25)
	ds_write_b128 v181, v[20:23] offset:45568
	s_and_saveexec_b64 s[34:35], s[2:3]
	v_add_u32_e32 v2, 0x14000, v178
	ds_write_b32 v2, v202
	s_or_b64 exec, exec, s[34:35]
	s_waitcnt lgkmcnt(6)
	v_pk_mul_f32 v[8:9], v[46:47], v[74:75]
	v_pk_mul_f32 v[6:7], v[44:45], v[72:73]
	v_pk_mul_f32 v[28:29], v[58:59], v[74:75]
	v_pk_mul_f32 v[26:27], v[56:57], v[72:73]
	v_cvt_pk_bf16_f32 v4, v6, v7
	v_cvt_pk_bf16_f32 v5, v8, v9
	v_pk_mul_f32 v[46:47], v[70:71], v[74:75]
	v_pk_mul_f32 v[44:45], v[68:69], v[72:73]
	ds_write_b64 v185, v[4:5] offset:63488
	v_cvt_pk_bf16_f32 v4, v26, v27
	v_cvt_pk_bf16_f32 v5, v28, v29
	v_pk_mul_f32 v[54:55], v[16:17], v[74:75]
	v_pk_mul_f32 v[52:53], v[14:15], v[72:73]
	ds_write_b64 v186, v[4:5] offset:63488
	v_cvt_pk_bf16_f32 v4, v44, v45
	v_cvt_pk_bf16_f32 v5, v46, v47
	ds_write_b64 v187, v[4:5] offset:63488
	v_cvt_pk_bf16_f32 v4, v52, v53
	v_cvt_pk_bf16_f32 v5, v54, v55
	ds_write_b64 v188, v[4:5] offset:63488
	s_waitcnt lgkmcnt(0)
	s_barrier
	ds_read_b64_tr_b16 v[64:65], v206 offset:36864
	ds_read_b64_tr_b16 v[56:57], v206 offset:36896
	ds_read_b64_tr_b16 v[68:69], v206 offset:36928
	ds_read_b64_tr_b16 v[72:73], v206 offset:36960
	ds_read_b64_tr_b16 v[66:67], v206 offset:37952
	ds_read_b64_tr_b16 v[58:59], v206 offset:37984
	ds_read_b64_tr_b16 v[70:71], v206 offset:38016
	ds_read_b64_tr_b16 v[74:75], v206 offset:38048
	ds_read_b64_tr_b16 v[22:23], v206 offset:45568
	ds_read_b64_tr_b16 v[18:19], v206 offset:45600
	ds_read_b64_tr_b16 v[14:15], v206 offset:45632
	ds_read_b64_tr_b16 v[10:11], v206 offset:45664
	ds_read_b64_tr_b16 v[24:25], v206 offset:46656
	ds_read_b64_tr_b16 v[20:21], v206 offset:46688
	ds_read_b64_tr_b16 v[16:17], v206 offset:46720
	ds_read_b64_tr_b16 v[12:13], v206 offset:46752
	s_and_b64 vcc, exec, s[74:75]
	s_cbranch_vccnz .LBB0_832
	ds_read_b128 v[76:79], v192 offset:18432
	ds_read_b128 v[80:83], v189
	s_waitcnt lgkmcnt(0)
	v_mfma_f32_16x16x32_bf16 v[76:79], v[76:79], v[80:83], 0
	s_and_b64 vcc, exec, s[10:11]
	s_cbranch_vccz .LBB0_833

; #define GAS __attribute__((address_space(1)))
; #define LAS __attribute__((address_space(3)))
; __device__ __forceinline__ float fsigmoid(float x) { return __builtin_amdgcn_rcpf(1.f + __builtin_amdgcn_exp2f(-LOG2E * x)); }
; __device__ __forceinline__ f32x4 bf4_to_f32(u32x2 w) { return (f32x4){bflo(w.x), bfhi(w.x), bflo(w.y), bfhi(w.y)}; }
; __device__ __forceinline__ u32x2 f32_to_bf4(f32x4 v) { u32x2 w; w.x = cvtpk(v[0], v[1]); w.y = cvtpk(v[2], v[3]); return w; }
; template <bool FULL> __device__ __forceinline__ void gla_unit(LAS unsigned char* lds, const MixBufs& B, int b, int h, int seg, int tid) {
;     ...
;             const float rstd = 1.f / sqrtf((SSQ[16 * ti + c] + SSQ[64 + 16 * ti + c]) * (1.f / 128.f) + EPS);
; #pragma unroll
;             for (int j = 0; j < 4; ++j) { const f32x4 gg = bf4_to_f32(gv[j]), gnj = *(const LAS f32x4*)(GNL + 16 * (4 * vh + j) + 4 * g);
;                 f32x4 r;
; #pragma unroll
;                 for (int i = 0; i < 4; ++i) r[i] = o[j][i] * rstd * gnj[i] * (gg[i] * fsigmoid(gg[i]));
;                 *(GAS u32x2*)(B.A_a + trow * 1024 + h * 128 + 16 * (4 * vh + j) + 4 * g) = f32_to_bf4(r); }
.LBB0_847:
	s_or_b64 exec, exec, s[34:35]
	s_waitcnt lgkmcnt(0)
	s_barrier
	ds_read2st64_b32 v[30:31], v191 offset1:1
	s_or_b32 s34, s73, 0x180
	v_or_b32_e32 v4, s34, v177
	v_mov_b32_e32 v5, s91
	v_lshlrev_b64 v[4:5], 11, v[4:5]
	s_waitcnt lgkmcnt(0)
	v_add_f32_e32 v2, v30, v31
	v_fmamk_f32 v2, v2, 0x3c000000, v182
	v_cmp_gt_f32_e32 vcc, s68, v2
	v_mul_f32_e32 v30, 0x4f800000, v2
	v_mov_b32_e32 v133, v3
	v_cndmask_b32_e32 v2, v2, v30, vcc
	v_sqrt_f32_e32 v30, v2
	s_nop 0
	v_add_u32_e32 v31, -1, v30
	v_fma_f32 v92, -v31, v30, v2
	v_cmp_ge_f32_e64 s[34:35], 0, v92
	v_add_u32_e32 v92, 1, v30
	s_nop 0
	v_cndmask_b32_e64 v31, v30, v31, s[34:35]
	v_fma_f32 v30, -v92, v30, v2
	v_cmp_lt_f32_e64 s[34:35], 0, v30
	s_nop 1
	v_cndmask_b32_e64 v30, v31, v92, s[34:35]
	v_mul_f32_e32 v31, 0x37800000, v30
	v_cndmask_b32_e32 v30, v30, v31, vcc
	v_cmp_class_f32_e32 vcc, v2, v1
	s_nop 1
	v_cndmask_b32_e32 v2, v30, v2, vcc
	v_div_scale_f32 v30, s[34:35], v2, v2, 1.0
	v_rcp_f32_e32 v31, v30
	v_readlane_b32 s34, v240, 14
	v_readlane_b32 s35, v240, 15
	v_fma_f32 v92, -v30, v31, 1.0
	v_fmac_f32_e32 v31, v92, v31
	v_div_scale_f32 v92, vcc, 1.0, v2, 1.0
	v_mul_f32_e32 v93, v92, v31
	v_fma_f32 v94, -v30, v93, v92
	v_fmac_f32_e32 v93, v94, v31
	v_fma_f32 v30, -v30, v93, v92
	v_div_fmas_f32 v30, v30, v31, v93
	ds_read_b128 v[92:95], v184
	v_div_fixup_f32 v2, v30, v2, 1.0
	s_waitcnt vmcnt(24)
	v_lshlrev_b32_e32 v30, 16, v174
	v_and_b32_e32 v31, 0xffff0000, v174
	v_pk_mul_f32 v[88:89], v[88:89], v[2:3] op_sel_hi:[1,0]
	v_mul_f32_e32 v96, 0xbfb8aa3b, v30
	s_waitcnt lgkmcnt(0)
	v_pk_mul_f32 v[88:89], v[92:93], v[88:89]
	v_mul_f32_e32 v92, 0xbfb8aa3b, v31
	v_exp_f32_e32 v96, v96
	v_exp_f32_e32 v92, v92
	v_pk_mul_f32 v[90:91], v[90:91], v[2:3] op_sel_hi:[1,0]
	v_lshl_add_u64 v[4:5], s[34:35], 0, v[4:5]
	v_add_f32_e32 v96, 1.0, v96
	v_add_f32_e32 v92, 1.0, v92
	v_rcp_f32_e32 v96, v96
	v_rcp_f32_e32 v97, v92
	v_pk_mul_f32 v[90:91], v[94:95], v[90:91]
	v_lshl_add_u64 v[4:5], v[4:5], 0, s[8:9]
	v_lshl_add_u64 v[4:5], s[60:61], 1, v[4:5]
	v_pk_mul_f32 v[30:31], v[96:97], v[30:31]
	v_lshl_add_u64 v[4:5], v[4:5], 0, v[132:133]
	v_pk_mul_f32 v[30:31], v[30:31], v[88:89]
	v_lshlrev_b32_e32 v88, 16, v175
	v_and_b32_e32 v89, 0xffff0000, v175
	v_mul_f32_e32 v92, 0xbfb8aa3b, v88
	v_mul_f32_e32 v93, 0xbfb8aa3b, v89
	v_exp_f32_e32 v92, v92
	v_exp_f32_e32 v93, v93
	v_cvt_pk_bf16_f32 v30, v30, v31
	v_pk_mul_f32 v[84:85], v[84:85], v[2:3] op_sel_hi:[1,0]
	v_add_f32_e32 v92, 1.0, v92
	v_add_f32_e32 v93, 1.0, v93
	v_rcp_f32_e32 v92, v92
	v_rcp_f32_e32 v93, v93
	v_pk_mul_f32 v[86:87], v[86:87], v[2:3] op_sel_hi:[1,0]
	v_pk_mul_f32 v[80:81], v[80:81], v[2:3] op_sel_hi:[1,0]
	v_pk_mul_f32 v[82:83], v[82:83], v[2:3] op_sel_hi:[1,0]
	v_pk_mul_f32 v[88:89], v[92:93], v[88:89]
	v_pk_mul_f32 v[76:77], v[76:77], v[2:3] op_sel_hi:[1,0]
	v_pk_mul_f32 v[88:89], v[88:89], v[90:91]
	v_pk_mul_f32 v[78:79], v[78:79], v[2:3] op_sel_hi:[1,0]
	v_cvt_pk_bf16_f32 v31, v88, v89
	ds_read_b128 v[88:91], v184 offset:64
	global_store_dwordx2 v[4:5], v[30:31], off sc1
	s_waitcnt vmcnt(24)
	v_lshlrev_b32_e32 v30, 16, v170
	v_and_b32_e32 v31, 0xffff0000, v170
	v_mul_f32_e32 v92, 0xbfb8aa3b, v30
	s_waitcnt lgkmcnt(0)
	v_pk_mul_f32 v[84:85], v[88:89], v[84:85]
	v_mul_f32_e32 v88, 0xbfb8aa3b, v31
	v_exp_f32_e32 v92, v92
	v_exp_f32_e32 v88, v88
	v_pk_mul_f32 v[86:87], v[90:91], v[86:87]
	v_add_f32_e32 v92, 1.0, v92
	v_add_f32_e32 v88, 1.0, v88
	v_rcp_f32_e32 v92, v92
	v_rcp_f32_e32 v93, v88
	s_nop 0
	v_pk_mul_f32 v[30:31], v[92:93], v[30:31]
	s_nop 0
	v_pk_mul_f32 v[30:31], v[30:31], v[84:85]
	v_lshlrev_b32_e32 v84, 16, v171
	v_and_b32_e32 v85, 0xffff0000, v171
	v_mul_f32_e32 v88, 0xbfb8aa3b, v84
	v_mul_f32_e32 v89, 0xbfb8aa3b, v85
	v_exp_f32_e32 v88, v88
	v_exp_f32_e32 v89, v89
	v_cvt_pk_bf16_f32 v30, v30, v31
	v_add_f32_e32 v88, 1.0, v88
	v_add_f32_e32 v89, 1.0, v89
	v_rcp_f32_e32 v88, v88
	v_rcp_f32_e32 v89, v89
	s_nop 0
	v_pk_mul_f32 v[84:85], v[88:89], v[84:85]
	s_nop 0
	v_pk_mul_f32 v[84:85], v[84:85], v[86:87]
	s_nop 0
	v_cvt_pk_bf16_f32 v31, v84, v85
	ds_read_b128 v[84:87], v184 offset:128
	global_store_dwordx2 v[4:5], v[30:31], off offset:32 sc1
	s_waitcnt vmcnt(24)
	v_lshlrev_b32_e32 v30, 16, v168
	v_and_b32_e32 v31, 0xffff0000, v168
	v_mul_f32_e32 v88, 0xbfb8aa3b, v30
	s_waitcnt lgkmcnt(0)
	v_pk_mul_f32 v[80:81], v[84:85], v[80:81]
	v_mul_f32_e32 v84, 0xbfb8aa3b, v31
	v_exp_f32_e32 v88, v88
	v_exp_f32_e32 v84, v84
	v_pk_mul_f32 v[82:83], v[86:87], v[82:83]
	v_add_f32_e32 v88, 1.0, v88
	v_add_f32_e32 v84, 1.0, v84
	v_rcp_f32_e32 v88, v88
	v_rcp_f32_e32 v89, v84
	s_nop 0
	v_pk_mul_f32 v[30:31], v[88:89], v[30:31]
	s_nop 0
	v_pk_mul_f32 v[30:31], v[30:31], v[80:81]
	v_lshlrev_b32_e32 v80, 16, v169
	v_and_b32_e32 v81, 0xffff0000, v169
	v_mul_f32_e32 v84, 0xbfb8aa3b, v80
	v_mul_f32_e32 v85, 0xbfb8aa3b, v81
	v_exp_f32_e32 v84, v84
	v_exp_f32_e32 v85, v85
	v_cvt_pk_bf16_f32 v30, v30, v31
	v_add_f32_e32 v84, 1.0, v84
	v_add_f32_e32 v85, 1.0, v85
	v_rcp_f32_e32 v84, v84
	v_rcp_f32_e32 v85, v85
	s_nop 0
	v_pk_mul_f32 v[80:81], v[84:85], v[80:81]
	s_nop 0
	v_pk_mul_f32 v[80:81], v[80:81], v[82:83]
	s_nop 0
	v_cvt_pk_bf16_f32 v31, v80, v81
	ds_read_b128 v[80:83], v184 offset:192
	global_store_dwordx2 v[4:5], v[30:31], off offset:64 sc1
	s_waitcnt vmcnt(24)
	v_lshlrev_b32_e32 v30, 16, v160
	v_and_b32_e32 v31, 0xffff0000, v160
	v_mul_f32_e32 v84, 0xbfb8aa3b, v30
	s_waitcnt lgkmcnt(0)
; template <bool FULL> __device__ __forceinline__ void gla_unit(LAS unsigned char* lds, const MixBufs& B, int b, int h, int seg, int tid) {
;     ...
;         { const v4u ee = re[st]; const f32x4 e0 = (f32x4){bflo(ee.x), bfhi(ee.x), bflo(ee.y), bfhi(ee.y)}, e1 = (f32x4){bflo(ee.z), bfhi(ee.z), bflo(ee.w), bfhi(ee.w)};
;           f32x4 i0, i1;
; #pragma unroll
;           for (int e = 0; e < 4; ++e) { i0[e] = __builtin_amdgcn_rcpf(e0[e]); i1[e] = __builtin_amdgcn_rcpf(e1[e]); }
;           *(LAS v4u*)(lds + okf + lr * GP64 + lc * 16) = mul_bf8(rk[st], i0, i1);
;           if (FULL) { *(LAS v4u*)(lds + G_KB + lr * GP64 + lc * 16) = mul_bf8(rk[st], e0, e1);
;                       *(LAS v4u*)(lds + G_QF + lr * GP64 + lc * 16) = mul_bf8(rq[st], e0, e1); *(LAS v4u*)(lds + G_QB + lr * GP64 + lc * 16) = mul_bf8(rq[st], i0, i1); } }
;         *(LAS v4u*)(lds + ov + vr * GP128 + vc * 16) = rv0[st]; *(LAS v4u*)(lds + ov + (vr + 32) * GP128 + vc * 16) = rv1[st];
;         if (tid < 64) DLc[tid] = rdl[st];
;         if (FULL) {
; #pragma unroll
;             for (int j = 0; j < 4; ++j) *(LAS u32x2*)(lds + G_ST + (16 * (4 * vh + j) + c) * GP64 + (16 * kt + 4 * g) * 2) = f32_to_bf4(S[j]);
;         }
;         const size_t trow = t0 + 16 * ti + c;
;         u32x2 gv[4];
;         if (FULL) {
; #pragma unroll
;             for (int j = 0; j < 4; ++j) gv[j] = gvp[st][j];
;         }
;         if (ci + 3 < 8) GLA_PREFETCH(st, ch + 3);
;         __syncthreads();
;         bf16x8 vfr[4][2];
; #pragma unroll
;         for (int j = 0; j < 4; ++j)
; #pragma unroll
;             for (int ks = 0; ks < 2; ++ks) vfr[j][ks] = frag_tr(lds + ov, GP128, 32 * ks, 16 * (4 * vh + j), lane);
;         if (FULL) {
; #pragma unroll
;             for (int jj = 0; jj < 2; ++jj) { const int sj = 2 * sh + jj;
;                 f32x4 af = (f32x4){0.f, 0.f, 0.f, 0.f}, ab = (f32x4){0.f, 0.f, 0.f, 0.f};
; #pragma unroll
;                 for (int ks = 0; ks < 2; ++ks) {
;                     if (ti >= sj) af = MFMA16(frag_row(lds + okf, GP64, 16 * sj, 32 * ks, lane), frag_row(lds + G_QF, GP64, 16 * ti, 32 * ks, lane), af);
;     ...
;                 *(GAS u32x2*)(B.A_a + trow * 1024 + h * 128 + 16 * (4 * vh + j) + 4 * g) = f32_to_bf4(r); }
;         }
; #pragma unroll
;         for (int ks = 0; ks < 2; ++ks) { const bf16x8 kf = frag_tr(lds + okf, GP64, 32 * ks, 16 * kt, lane);
; #pragma unroll
	v_pk_mul_f32 v[76:77], v[76:77], v[80:81]
	v_mul_f32_e32 v80, 0xbfb8aa3b, v31
	v_exp_f32_e32 v84, v84
	v_exp_f32_e32 v80, v80
	v_pk_mul_f32 v[78:79], v[78:79], v[82:83]
	v_add_f32_e32 v84, 1.0, v84
	v_add_f32_e32 v80, 1.0, v80
	v_rcp_f32_e32 v84, v84
	v_rcp_f32_e32 v85, v80
	s_nop 0
	v_pk_mul_f32 v[30:31], v[84:85], v[30:31]
	s_nop 0
	v_pk_mul_f32 v[30:31], v[30:31], v[76:77]
	v_lshlrev_b32_e32 v76, 16, v161
	v_and_b32_e32 v77, 0xffff0000, v161
	v_mul_f32_e32 v80, 0xbfb8aa3b, v76
	v_mul_f32_e32 v2, 0xbfb8aa3b, v77
	v_exp_f32_e32 v80, v80
	v_exp_f32_e32 v2, v2
	v_cvt_pk_bf16_f32 v30, v30, v31
	v_add_f32_e32 v80, 1.0, v80
	v_add_f32_e32 v2, 1.0, v2
	v_rcp_f32_e32 v80, v80
	v_rcp_f32_e32 v81, v2
	s_nop 0
	v_pk_mul_f32 v[76:77], v[80:81], v[76:77]
	s_nop 0
	v_pk_mul_f32 v[76:77], v[76:77], v[78:79]
	s_nop 0
	v_cvt_pk_bf16_f32 v31, v76, v77
	global_store_dwordx2 v[4:5], v[30:31], off offset:96 sc1
	ds_read_b64_tr_b16 v[76:77], v210 offset:18432
	ds_read_b64_tr_b16 v[78:79], v210 offset:19008
	s_waitcnt lgkmcnt(0)
	v_mfma_f32_16x16x32_bf16 v[26:29], v[76:79], v[56:59], v[26:29]
	ds_read_b64_tr_b16 v[56:57], v210 offset:23040
	ds_read_b64_tr_b16 v[58:59], v210 offset:23616
	s_waitcnt vmcnt(19)
	v_lshlrev_b32_e32 v30, 16, v62
	v_and_b32_e32 v31, 0xffff0000, v62
	v_mfma_f32_16x16x32_bf16 v[4:7], v[76:79], v[64:67], v[6:9]
	v_mfma_f32_16x16x32_bf16 v[52:55], v[76:79], v[72:75], v[52:55]
	v_mfma_f32_16x16x32_bf16 v[44:47], v[76:79], v[68:71], v[44:47]
	s_waitcnt lgkmcnt(0)
	v_mfma_f32_16x16x32_bf16 v[22:25], v[56:59], v[22:25], v[4:7]
	v_mfma_f32_16x16x32_bf16 v[4:7], v[56:59], v[10:13], v[52:55]
	v_lshlrev_b32_e32 v12, 16, v60
	v_and_b32_e32 v13, 0xffff0000, v60
	ds_read_b128 v[8:11], v203
	s_waitcnt vmcnt(18)
	v_lshlrev_b32_e32 v54, 16, v48
	v_and_b32_e32 v55, 0xffff0000, v48
	v_mfma_f32_16x16x32_bf16 v[18:21], v[56:59], v[18:21], v[26:29]
	v_lshlrev_b32_e32 v52, 16, v63
	v_and_b32_e32 v53, 0xffff0000, v63
	v_mfma_f32_16x16x32_bf16 v[14:17], v[56:59], v[14:17], v[44:47]
	v_rcp_f32_e32 v56, v54
	v_rcp_f32_e32 v57, v55
	v_lshlrev_b32_e32 v58, 16, v50
	v_and_b32_e32 v59, 0xffff0000, v50
	v_lshlrev_b32_e32 v28, 16, v61
	v_pk_mul_f32 v[26:27], v[56:57], v[12:13]
	v_pk_mul_f32 v[12:13], v[12:13], v[54:55]
	v_and_b32_e32 v29, 0xffff0000, v61
	v_cvt_pk_bf16_f32 v44, v12, v13
	v_lshlrev_b32_e32 v12, 16, v49
	v_and_b32_e32 v13, 0xffff0000, v49
	v_rcp_f32_e32 v48, v12
	v_rcp_f32_e32 v49, v13
	v_rcp_f32_e32 v60, v58
	v_rcp_f32_e32 v61, v59
	v_cvt_pk_bf16_f32 v26, v26, v27
	v_pk_mul_f32 v[46:47], v[48:49], v[28:29]
	v_pk_mul_f32 v[28:29], v[28:29], v[12:13]
	v_cvt_pk_bf16_f32 v27, v46, v47
	v_cvt_pk_bf16_f32 v45, v28, v29
	v_pk_mul_f32 v[28:29], v[60:61], v[30:31]
	v_pk_mul_f32 v[30:31], v[30:31], v[58:59]
	v_cvt_pk_bf16_f32 v28, v28, v29
	v_cvt_pk_bf16_f32 v46, v30, v31
	v_lshlrev_b32_e32 v30, 16, v51
	v_and_b32_e32 v31, 0xffff0000, v51
	v_rcp_f32_e32 v50, v30
	v_rcp_f32_e32 v51, v31
	s_nop 0
	v_pk_mul_f32 v[62:63], v[50:51], v[52:53]
	s_nop 0
	v_cvt_pk_bf16_f32 v29, v62, v63
	ds_write_b128 v176, v[26:29]
	v_pk_mul_f32 v[26:27], v[52:53], v[30:31]
	s_nop 0
	v_cvt_pk_bf16_f32 v47, v26, v27
	ds_write_b128 v180, v[44:47] offset:27648
	v_lshlrev_b32_e32 v44, 16, v36
	v_and_b32_e32 v45, 0xffff0000, v36
	v_lshlrev_b32_e32 v36, 16, v37
	v_and_b32_e32 v37, 0xffff0000, v37
	v_pk_mul_f32 v[26:27], v[44:45], v[54:55]
	v_pk_mul_f32 v[12:13], v[36:37], v[12:13]
	v_cvt_pk_bf16_f32 v26, v26, v27
	v_cvt_pk_bf16_f32 v27, v12, v13
	v_lshlrev_b32_e32 v12, 16, v38
	v_and_b32_e32 v13, 0xffff0000, v38
	v_lshlrev_b32_e32 v38, 16, v39
	v_and_b32_e32 v39, 0xffff0000, v39
	v_pk_mul_f32 v[28:29], v[12:13], v[58:59]
	v_pk_mul_f32 v[30:31], v[38:39], v[30:31]
	v_cvt_pk_bf16_f32 v28, v28, v29
	v_cvt_pk_bf16_f32 v29, v30, v31
	ds_write_b128 v180, v[26:29]
	v_pk_mul_f32 v[26:27], v[56:57], v[44:45]
	v_pk_mul_f32 v[28:29], v[48:49], v[36:37]
	v_pk_mul_f32 v[12:13], v[60:61], v[12:13]
	v_cvt_pk_bf16_f32 v26, v26, v27
	v_cvt_pk_bf16_f32 v27, v28, v29
	v_cvt_pk_bf16_f32 v28, v12, v13
	v_pk_mul_f32 v[12:13], v[50:51], v[38:39]
	s_nop 0
	v_cvt_pk_bf16_f32 v29, v12, v13
	ds_write_b128 v180, v[26:29] offset:9216
	s_waitcnt vmcnt(17)
	ds_write_b128 v181, v[32:35] offset:36864
	s_waitcnt vmcnt(16)
	ds_write_b128 v181, v[40:43] offset:45568
	s_and_saveexec_b64 s[34:35], s[2:3]
	v_add_u32_e32 v2, 0x16c00, v178
	ds_write_b32 v2, v179
	s_or_b64 exec, exec, s[34:35]
	s_waitcnt lgkmcnt(6)
	v_pk_mul_f32 v[12:13], v[24:25], v[10:11]
	v_pk_mul_f32 v[22:23], v[22:23], v[8:9]
	v_pk_mul_f32 v[20:21], v[20:21], v[10:11]
	v_pk_mul_f32 v[18:19], v[18:19], v[8:9]
	v_pk_mul_f32 v[14:15], v[14:15], v[8:9]
	v_pk_mul_f32 v[4:5], v[4:5], v[8:9]
	v_cvt_pk_bf16_f32 v8, v22, v23
	v_cvt_pk_bf16_f32 v9, v12, v13
	v_pk_mul_f32 v[16:17], v[16:17], v[10:11]
	v_pk_mul_f32 v[6:7], v[6:7], v[10:11]
	ds_write_b64 v185, v[8:9] offset:63488
	v_cvt_pk_bf16_f32 v8, v18, v19
	v_cvt_pk_bf16_f32 v9, v20, v21
	ds_write_b64 v186, v[8:9] offset:63488
	v_cvt_pk_bf16_f32 v8, v14, v15
	v_cvt_pk_bf16_f32 v9, v16, v17
	v_cvt_pk_bf16_f32 v4, v4, v5
	v_cvt_pk_bf16_f32 v5, v6, v7
	ds_write_b64 v187, v[8:9] offset:63488
	ds_write_b64 v188, v[4:5] offset:63488
	s_waitcnt lgkmcnt(0)
	s_barrier
	ds_read_b64_tr_b16 v[26:27], v206 offset:36864
	ds_read_b64_tr_b16 v[22:23], v206 offset:36896
	ds_read_b64_tr_b16 v[30:31], v206 offset:36928
	ds_read_b64_tr_b16 v[34:35], v206 offset:36960
	ds_read_b64_tr_b16 v[28:29], v206 offset:37952
	ds_read_b64_tr_b16 v[24:25], v206 offset:37984
	ds_read_b64_tr_b16 v[32:33], v206 offset:38016
	ds_read_b64_tr_b16 v[36:37], v206 offset:38048
	ds_read_b64_tr_b16 v[18:19], v206 offset:45568
	ds_read_b64_tr_b16 v[14:15], v206 offset:45600
	ds_read_b64_tr_b16 v[10:11], v206 offset:45632
	ds_read_b64_tr_b16 v[6:7], v206 offset:45664
	ds_read_b64_tr_b16 v[20:21], v206 offset:46656
	ds_read_b64_tr_b16 v[16:17], v206 offset:46688
	ds_read_b64_tr_b16 v[12:13], v206 offset:46720
	ds_read_b64_tr_b16 v[8:9], v206 offset:46752
	s_and_b64 vcc, exec, s[74:75]
	s_cbranch_vccnz .LBB0_852
	ds_read_b128 v[38:41], v205
	ds_read_b128 v[42:45], v189
	s_waitcnt lgkmcnt(0)
	v_mfma_f32_16x16x32_bf16 v[38:41], v[38:41], v[42:45], 0
	s_and_b64 vcc, exec, s[10:11]
	s_cbranch_vccz .LBB0_853

; #define GAS __attribute__((address_space(1)))
; #define LAS __attribute__((address_space(3)))
; __device__ __forceinline__ float fsigmoid(float x) { return __builtin_amdgcn_rcpf(1.f + __builtin_amdgcn_exp2f(-LOG2E * x)); }
; __device__ __forceinline__ f32x4 bf4_to_f32(u32x2 w) { return (f32x4){bflo(w.x), bfhi(w.x), bflo(w.y), bfhi(w.y)}; }
; __device__ __forceinline__ u32x2 f32_to_bf4(f32x4 v) { u32x2 w; w.x = cvtpk(v[0], v[1]); w.y = cvtpk(v[2], v[3]); return w; }
; template <bool FULL> __device__ __forceinline__ void gla_unit(LAS unsigned char* lds, const MixBufs& B, int b, int h, int seg, int tid) {
;     ...
;             const float rstd = 1.f / sqrtf((SSQ[16 * ti + c] + SSQ[64 + 16 * ti + c]) * (1.f / 128.f) + EPS);
; #pragma unroll
;             for (int j = 0; j < 4; ++j) { const f32x4 gg = bf4_to_f32(gv[j]), gnj = *(const LAS f32x4*)(GNL + 16 * (4 * vh + j) + 4 * g);
;                 f32x4 r;
; #pragma unroll
;                 for (int i = 0; i < 4; ++i) r[i] = o[j][i] * rstd * gnj[i] * (gg[i] * fsigmoid(gg[i]));
;                 *(GAS u32x2*)(B.A_a + trow * 1024 + h * 128 + 16 * (4 * vh + j) + 4 * g) = f32_to_bf4(r); }
;     ...
;     __syncthreads();
.LBB0_867:
	s_or_b64 exec, exec, s[2:3]
	s_waitcnt lgkmcnt(0)
	s_barrier
	ds_read2st64_b32 v[22:23], v191 offset1:1
	s_or_b32 s2, s73, 0x1c0
	v_or_b32_e32 v20, s2, v177
	v_mov_b32_e32 v21, s91
	s_waitcnt vmcnt(15)
	v_and_b32_e32 v27, 0xffff0000, v140
	s_waitcnt lgkmcnt(0)
	v_add_f32_e32 v2, v22, v23
	v_fmamk_f32 v2, v2, 0x3c000000, v182
	v_cmp_gt_f32_e32 vcc, s68, v2
	v_mul_f32_e32 v22, 0x4f800000, v2
	v_mov_b32_e32 v133, v3
	v_cndmask_b32_e32 v2, v2, v22, vcc
	v_sqrt_f32_e32 v22, v2
	s_mov_b64 s[16:17], -1
	v_add_u32_e32 v23, -1, v22
	v_fma_f32 v24, -v23, v22, v2
	v_cmp_ge_f32_e64 s[2:3], 0, v24
	v_add_u32_e32 v24, 1, v22
	s_nop 0
	v_cndmask_b32_e64 v23, v22, v23, s[2:3]
	v_fma_f32 v22, -v24, v22, v2
	v_cmp_lt_f32_e64 s[2:3], 0, v22
	s_nop 1
	v_cndmask_b32_e64 v22, v23, v24, s[2:3]
	v_mul_f32_e32 v23, 0x37800000, v22
	v_cndmask_b32_e32 v22, v22, v23, vcc
	v_cmp_class_f32_e32 vcc, v2, v1
	s_nop 1
	v_cndmask_b32_e32 v2, v22, v2, vcc
	v_div_scale_f32 v22, s[2:3], v2, v2, 1.0
	v_rcp_f32_e32 v23, v22
	v_readlane_b32 s2, v240, 14
	v_readlane_b32 s3, v240, 15
	v_fma_f32 v24, -v22, v23, 1.0
	v_fmac_f32_e32 v23, v24, v23
	v_div_scale_f32 v24, vcc, 1.0, v2, 1.0
	v_mul_f32_e32 v25, v24, v23
	v_fma_f32 v26, -v22, v25, v24
	v_fmac_f32_e32 v25, v26, v23
	v_fma_f32 v22, -v22, v25, v24
	v_div_fmas_f32 v22, v22, v23, v25
	v_div_fixup_f32 v2, v22, v2, 1.0
	v_lshlrev_b64 v[24:25], 11, v[20:21]
	ds_read_b128 v[20:23], v184
	v_lshlrev_b32_e32 v26, 16, v140
	v_pk_mul_f32 v[16:17], v[16:17], v[2:3] op_sel_hi:[1,0]
	v_mul_f32_e32 v28, 0xbfb8aa3b, v26
	v_exp_f32_e32 v28, v28
	s_waitcnt lgkmcnt(0)
	v_pk_mul_f32 v[16:17], v[20:21], v[16:17]
	v_mul_f32_e32 v20, 0xbfb8aa3b, v27
	v_exp_f32_e32 v20, v20
	v_add_f32_e32 v28, 1.0, v28
	v_rcp_f32_e32 v28, v28
	v_pk_mul_f32 v[18:19], v[18:19], v[2:3] op_sel_hi:[1,0]
	v_add_f32_e32 v20, 1.0, v20
	v_rcp_f32_e32 v29, v20
	v_pk_mul_f32 v[18:19], v[22:23], v[18:19]
	s_waitcnt vmcnt(14)
	v_and_b32_e32 v23, 0xffff0000, v138
	v_pk_mul_f32 v[12:13], v[12:13], v[2:3] op_sel_hi:[1,0]
	v_pk_mul_f32 v[20:21], v[28:29], v[26:27]
	v_pk_mul_f32 v[14:15], v[14:15], v[2:3] op_sel_hi:[1,0]
	v_pk_mul_f32 v[16:17], v[20:21], v[16:17]
	v_lshlrev_b32_e32 v20, 16, v141
	v_and_b32_e32 v21, 0xffff0000, v141
	v_mul_f32_e32 v26, 0xbfb8aa3b, v20
	v_mul_f32_e32 v22, 0xbfb8aa3b, v21
	v_exp_f32_e32 v26, v26
	v_exp_f32_e32 v22, v22
	v_pk_mul_f32 v[8:9], v[8:9], v[2:3] op_sel_hi:[1,0]
	v_pk_mul_f32 v[10:11], v[10:11], v[2:3] op_sel_hi:[1,0]
	v_add_f32_e32 v26, 1.0, v26
	v_add_f32_e32 v22, 1.0, v22
	v_rcp_f32_e32 v26, v26
	v_rcp_f32_e32 v27, v22
	v_lshlrev_b32_e32 v22, 16, v138
	v_pk_mul_f32 v[4:5], v[4:5], v[2:3] op_sel_hi:[1,0]
	v_pk_mul_f32 v[6:7], v[6:7], v[2:3] op_sel_hi:[1,0]
	v_pk_mul_f32 v[20:21], v[26:27], v[20:21]
	s_nop 0
	v_pk_mul_f32 v[18:19], v[20:21], v[18:19]
	v_cvt_pk_bf16_f32 v20, v16, v17
	v_lshl_add_u64 v[16:17], s[2:3], 0, v[24:25]
	v_lshl_add_u64 v[16:17], v[16:17], 0, s[8:9]
	v_lshl_add_u64 v[16:17], s[60:61], 1, v[16:17]
	v_cvt_pk_bf16_f32 v21, v18, v19
	v_lshl_add_u64 v[16:17], v[16:17], 0, v[132:133]
	global_store_dwordx2 v[16:17], v[20:21], off sc1
	ds_read_b128 v[18:21], v184 offset:64
	v_mul_f32_e32 v24, 0xbfb8aa3b, v22
	v_exp_f32_e32 v24, v24
	s_waitcnt lgkmcnt(0)
	v_pk_mul_f32 v[12:13], v[18:19], v[12:13]
	v_mul_f32_e32 v18, 0xbfb8aa3b, v23
	v_exp_f32_e32 v18, v18
	v_add_f32_e32 v24, 1.0, v24
	v_rcp_f32_e32 v24, v24
	v_pk_mul_f32 v[14:15], v[20:21], v[14:15]
	v_add_f32_e32 v18, 1.0, v18
	v_rcp_f32_e32 v25, v18
	s_nop 0
	v_pk_mul_f32 v[18:19], v[24:25], v[22:23]
	s_nop 0
	v_pk_mul_f32 v[12:13], v[18:19], v[12:13]
	v_lshlrev_b32_e32 v18, 16, v139
	v_and_b32_e32 v19, 0xffff0000, v139
	v_mul_f32_e32 v22, 0xbfb8aa3b, v18
	v_mul_f32_e32 v20, 0xbfb8aa3b, v19
	v_exp_f32_e32 v22, v22
	v_exp_f32_e32 v20, v20
	v_cvt_pk_bf16_f32 v12, v12, v13
	v_add_f32_e32 v22, 1.0, v22
	v_add_f32_e32 v20, 1.0, v20
	v_rcp_f32_e32 v22, v22
	v_rcp_f32_e32 v23, v20
	s_nop 0
	v_pk_mul_f32 v[18:19], v[22:23], v[18:19]
	s_nop 0
	v_pk_mul_f32 v[14:15], v[18:19], v[14:15]
	s_waitcnt vmcnt(14)
	v_lshlrev_b32_e32 v18, 16, v136
	v_cvt_pk_bf16_f32 v13, v14, v15
	global_store_dwordx2 v[16:17], v[12:13], off offset:32 sc1
	ds_read_b128 v[12:15], v184 offset:128
	v_and_b32_e32 v19, 0xffff0000, v136
	v_mul_f32_e32 v20, 0xbfb8aa3b, v18
	v_exp_f32_e32 v20, v20
	s_waitcnt lgkmcnt(0)
	v_pk_mul_f32 v[8:9], v[12:13], v[8:9]
	v_mul_f32_e32 v12, 0xbfb8aa3b, v19
	v_exp_f32_e32 v12, v12
	v_add_f32_e32 v20, 1.0, v20
	v_rcp_f32_e32 v20, v20
	v_pk_mul_f32 v[10:11], v[14:15], v[10:11]
	v_add_f32_e32 v12, 1.0, v12
	v_rcp_f32_e32 v21, v12
	s_nop 0
	v_pk_mul_f32 v[12:13], v[20:21], v[18:19]
	s_nop 0
	v_pk_mul_f32 v[8:9], v[12:13], v[8:9]
	v_lshlrev_b32_e32 v12, 16, v137
	v_and_b32_e32 v13, 0xffff0000, v137
	v_mul_f32_e32 v18, 0xbfb8aa3b, v12
	v_mul_f32_e32 v14, 0xbfb8aa3b, v13
	v_exp_f32_e32 v18, v18
	v_exp_f32_e32 v14, v14
	v_cvt_pk_bf16_f32 v8, v8, v9
	v_add_f32_e32 v18, 1.0, v18
	v_add_f32_e32 v14, 1.0, v14
	v_rcp_f32_e32 v18, v18
	v_rcp_f32_e32 v19, v14
	s_nop 0
	v_pk_mul_f32 v[12:13], v[18:19], v[12:13]
	s_nop 0
	v_pk_mul_f32 v[10:11], v[12:13], v[10:11]
	s_waitcnt vmcnt(14)
	v_lshlrev_b32_e32 v12, 16, v134
	v_cvt_pk_bf16_f32 v9, v10, v11
	global_store_dwordx2 v[16:17], v[8:9], off offset:64 sc1
	ds_read_b128 v[8:11], v184 offset:192
	v_and_b32_e32 v13, 0xffff0000, v134
	v_mul_f32_e32 v14, 0xbfb8aa3b, v12
	v_exp_f32_e32 v14, v14
	s_waitcnt lgkmcnt(0)
	v_pk_mul_f32 v[4:5], v[4:5], v[8:9]
	v_mul_f32_e32 v8, 0xbfb8aa3b, v13
	v_exp_f32_e32 v8, v8
	v_add_f32_e32 v14, 1.0, v14
	v_rcp_f32_e32 v14, v14
	v_pk_mul_f32 v[6:7], v[6:7], v[10:11]
	v_add_f32_e32 v8, 1.0, v8
	v_rcp_f32_e32 v15, v8
	s_nop 0
	v_pk_mul_f32 v[8:9], v[14:15], v[12:13]
	s_nop 0
	v_pk_mul_f32 v[4:5], v[8:9], v[4:5]
	v_lshlrev_b32_e32 v8, 16, v135
	v_and_b32_e32 v9, 0xffff0000, v135
	v_mul_f32_e32 v12, 0xbfb8aa3b, v8
	v_mul_f32_e32 v2, 0xbfb8aa3b, v9
	v_exp_f32_e32 v12, v12
	v_exp_f32_e32 v2, v2
	v_cvt_pk_bf16_f32 v4, v4, v5
	v_add_f32_e32 v12, 1.0, v12
	v_add_f32_e32 v2, 1.0, v2
	v_rcp_f32_e32 v12, v12
	v_rcp_f32_e32 v13, v2
	s_nop 0
	v_pk_mul_f32 v[8:9], v[12:13], v[8:9]
	s_nop 0
	v_pk_mul_f32 v[6:7], v[8:9], v[6:7]
	s_nop 0
	v_cvt_pk_bf16_f32 v5, v6, v7
	global_store_dwordx2 v[16:17], v[4:5], off offset:96 sc1
	s_barrier

; #define LAS __attribute__((address_space(3)))
; #define LDS_WAIT() asm volatile("s_waitcnt lgkmcnt(0)" ::: "memory")
; __device__ __forceinline__ void tr_store(const TrItem& it, const f32x4 (&v)[8], const float (&g)[8], LAS float* scr, int lane) {
;     const int k0 = 64 * it.kb, kl = lane >> 3, nq = lane & 7; const bool ok = 4 * nq < it.nvalid;
; #pragma unroll
;     for (int i = 0; i < 8; ++i) { const int kk = 8 * i + kl; const f32x4 x = ok ? v[i] * g[i] : (f32x4){0.f, 0.f, 0.f, 0.f};
;         scr[kk * 33 + 4 * nq + 0] = x[0]; scr[kk * 33 + 4 * nq + 1] = x[1]; scr[kk * 33 + 4 * nq + 2] = x[2]; scr[kk * 33 + 4 * nq + 3] = x[3]; }
;     LDS_WAIT(); asm volatile("" ::: "memory");
.LBB0_926:
	s_waitcnt vmcnt(0)
	v_pk_mul_f32 v[104:105], v[2:3], v[18:19] op_sel_hi:[0,1]
	v_cmp_gt_i32_e32 vcc, s15, v97
	v_pk_mul_f32 v[106:107], v[2:3], v[20:21] op_sel_hi:[0,1]
	v_add_u32_e32 v124, s14, v95
	v_cndmask_b32_e32 v85, 0, v105, vcc
	v_cndmask_b32_e32 v94, 0, v104, vcc
	v_pk_mul_f32 v[104:105], v[2:3], v[22:23] op_sel:[1,0]
	v_cndmask_b32_e32 v1, 0, v107, vcc
	v_cndmask_b32_e32 v82, 0, v106, vcc
	ds_write2_b32 v102, v94, v85 offset1:1
	ds_write2_b32 v102, v82, v1 offset0:2 offset1:3
	v_pk_mul_f32 v[106:107], v[2:3], v[24:25] op_sel:[1,0]
	v_cndmask_b32_e32 v85, 0, v105, vcc
	v_cndmask_b32_e32 v94, 0, v104, vcc
	v_add_u32_e32 v104, 0x420, v102
	v_cndmask_b32_e32 v1, 0, v107, vcc
	v_cndmask_b32_e32 v82, 0, v106, vcc
	ds_write2_b32 v104, v94, v85 offset1:1
	v_add_u32_e32 v85, 0x428, v102
	v_pk_mul_f32 v[104:105], v[4:5], v[26:27] op_sel_hi:[0,1]
	ds_write2_b32 v85, v82, v1 offset1:1
	v_pk_mul_f32 v[106:107], v[4:5], v[28:29] op_sel_hi:[0,1]
	v_cndmask_b32_e32 v85, 0, v105, vcc
	v_cndmask_b32_e32 v94, 0, v104, vcc
	v_add_u32_e32 v104, 0x840, v102
	v_cndmask_b32_e32 v1, 0, v107, vcc
	v_cndmask_b32_e32 v82, 0, v106, vcc
	ds_write2_b32 v104, v94, v85 offset1:1
	v_add_u32_e32 v85, 0x848, v102
	ds_write2_b32 v85, v82, v1 offset1:1
	v_mov_b32_e32 v82, v5
	v_pk_mul_f32 v[104:105], v[82:83], v[30:31] op_sel_hi:[0,1]
	v_pk_mul_f32 v[106:107], v[82:83], v[32:33] op_sel_hi:[0,1]
	v_cndmask_b32_e32 v85, 0, v105, vcc
	v_cndmask_b32_e32 v94, 0, v104, vcc
	v_add_u32_e32 v104, 0xc60, v102
	v_cndmask_b32_e32 v1, 0, v107, vcc
	v_cndmask_b32_e32 v82, 0, v106, vcc
	ds_write2_b32 v104, v94, v85 offset1:1
	v_add_u32_e32 v85, 0xc68, v102
	v_pk_mul_f32 v[104:105], v[6:7], v[34:35] op_sel_hi:[0,1]
	ds_write2_b32 v85, v82, v1 offset1:1
	v_pk_mul_f32 v[106:107], v[6:7], v[36:37] op_sel_hi:[0,1]
	v_cndmask_b32_e32 v85, 0, v105, vcc
	v_cndmask_b32_e32 v94, 0, v104, vcc
	v_add_u32_e32 v104, 0x1080, v102
	v_cndmask_b32_e32 v1, 0, v107, vcc
	v_cndmask_b32_e32 v82, 0, v106, vcc
	ds_write2_b32 v104, v94, v85 offset1:1
	v_add_u32_e32 v85, 0x1088, v102
	ds_write2_b32 v85, v82, v1 offset1:1
	v_mov_b32_e32 v82, v7
	v_pk_mul_f32 v[104:105], v[82:83], v[38:39] op_sel_hi:[0,1]
	v_pk_mul_f32 v[106:107], v[82:83], v[40:41] op_sel_hi:[0,1]
	v_cndmask_b32_e32 v85, 0, v105, vcc
	v_cndmask_b32_e32 v94, 0, v104, vcc
	v_add_u32_e32 v104, 0x14a0, v102
	v_cndmask_b32_e32 v1, 0, v107, vcc
	v_cndmask_b32_e32 v82, 0, v106, vcc
	ds_write2_b32 v104, v94, v85 offset1:1
	v_add_u32_e32 v85, 0x14a8, v102
	v_pk_mul_f32 v[104:105], v[8:9], v[42:43] op_sel_hi:[0,1]
	ds_write2_b32 v85, v82, v1 offset1:1
	v_pk_mul_f32 v[106:107], v[8:9], v[44:45] op_sel_hi:[0,1]
	v_cndmask_b32_e32 v85, 0, v105, vcc
	v_cndmask_b32_e32 v94, 0, v104, vcc
	v_add_u32_e32 v104, 0x18c0, v102
	v_cndmask_b32_e32 v1, 0, v107, vcc
	v_cndmask_b32_e32 v82, 0, v106, vcc
	ds_write2_b32 v104, v94, v85 offset1:1
	v_add_u32_e32 v85, 0x18c8, v102
	ds_write2_b32 v85, v82, v1 offset1:1
	v_mov_b32_e32 v82, v9
	v_pk_mul_f32 v[104:105], v[82:83], v[46:47] op_sel_hi:[0,1]
	v_pk_mul_f32 v[106:107], v[82:83], v[48:49] op_sel_hi:[0,1]
	v_cndmask_b32_e32 v85, 0, v105, vcc
	v_cndmask_b32_e32 v94, 0, v104, vcc
	v_add_u32_e32 v104, 0x1ce0, v102
	v_cndmask_b32_e32 v1, 0, v107, vcc
	v_cndmask_b32_e32 v82, 0, v106, vcc
	ds_write2_b32 v104, v94, v85 offset1:1
	v_add_u32_e32 v85, 0x1ce8, v102
	ds_write2_b32 v85, v82, v1 offset1:1
	s_waitcnt lgkmcnt(0)
	ds_read2_b32 v[108:109], v101 offset1:8
	ds_read2_b32 v[110:111], v101 offset0:33 offset1:41
	ds_read2_b32 v[112:113], v101 offset0:66 offset1:74
	ds_read2_b32 v[114:115], v101 offset0:99 offset1:107
	ds_read2_b32 v[116:117], v101 offset0:132 offset1:140
	s_waitcnt lgkmcnt(4)
	v_bfe_u32 v1, v108, 16, 1
	v_add3_u32 v1, v108, v1, s17
	s_waitcnt lgkmcnt(3)
	v_bfe_u32 v82, v110, 16, 1
	v_lshrrev_b32_e32 v1, 16, v1
	v_add3_u32 v82, v110, v82, s17
	ds_read2_b32 v[118:119], v101 offset0:165 offset1:173
	v_and_or_b32 v104, v82, s18, v1
	s_waitcnt lgkmcnt(3)
	v_bfe_u32 v1, v112, 16, 1
	v_add3_u32 v1, v112, v1, s17
	s_waitcnt lgkmcnt(2)
	v_bfe_u32 v82, v114, 16, 1
	ds_read2_b32 v[120:121], v101 offset0:198 offset1:206
	v_lshrrev_b32_e32 v1, 16, v1
	v_add3_u32 v82, v114, v82, s17
	ds_read2_b32 v[122:123], v101 offset0:231 offset1:239
	v_and_or_b32 v105, v82, s18, v1
	s_waitcnt lgkmcnt(3)
	v_bfe_u32 v1, v116, 16, 1
	v_add3_u32 v1, v116, v1, s17
	s_waitcnt lgkmcnt(2)
	v_bfe_u32 v82, v118, 16, 1
	v_lshrrev_b32_e32 v1, 16, v1
	v_add3_u32 v82, v118, v82, s17
	v_and_or_b32 v106, v82, s18, v1
	s_waitcnt lgkmcnt(1)
	v_bfe_u32 v1, v120, 16, 1
	s_lshl_b32 s6, s13, 6
	v_add3_u32 v1, v120, v1, s17
	s_waitcnt lgkmcnt(0)
; #define GAS __attribute__((address_space(1)))
; #define LAS __attribute__((address_space(3)))
; #define LDS_WAIT() asm volatile("s_waitcnt lgkmcnt(0)" ::: "memory")
; __device__ __forceinline__ unsigned pk2(float lo, float hi) { return f2bf(lo) | (f2bf(hi) << 16); }
; __device__ __forceinline__ void tr_store(const TrItem& it, const f32x4 (&v)[8], const float (&g)[8], LAS float* scr, int lane) {
;     ...
;     const int c = lane & 7;
; #pragma unroll
;     for (int j = 0; j < 4; ++j) { const int nn = (lane >> 3) + 8 * j; const LAS float* s = scr + (8 * c) * 33 + nn;
;         v4u o; o.x = pk2(s[0 * 33], s[1 * 33]); o.y = pk2(s[2 * 33], s[3 * 33]); o.z = pk2(s[4 * 33], s[5 * 33]); o.w = pk2(s[6 * 33], s[7 * 33]);
;         *(GAS v4u*)(it.WT + (size_t)(it.dst_row0 + nn) * it.Kdst + it.dst_koff + k0 + 8 * c) = o; }
;     LDS_WAIT(); asm volatile("" ::: "memory");
; __device__ __forceinline__ void p0_transposes(Frame& F, int it_lo, int it_hi, int gw, int NGW) {
;     ...
;         cur = nxt; it = nx;
; #pragma unroll
;         for (int i = 0; i < 8; ++i) { v[i] = v2[i]; g[i] = g2[i]; }
	v_bfe_u32 v82, v122, 16, 1
	v_ashrrev_i32_e32 v125, 31, v124
	v_readlane_b32 s8, v241, 36
	s_ashr_i32 s7, s6, 31
	v_lshrrev_b32_e32 v1, 16, v1
	v_add3_u32 v82, v122, v82, s17
	v_lshlrev_b64 v[124:125], 11, v[124:125]
	v_readlane_b32 s9, v241, 37
	v_and_or_b32 v107, v82, s18, v1
	s_lshl_b64 s[6:7], s[6:7], 1
	v_lshl_add_u64 v[124:125], s[8:9], 0, v[124:125]
	v_bfe_u32 v1, v109, 16, 1
	v_lshl_add_u64 v[124:125], v[124:125], 0, s[6:7]
	v_mov_b32_e32 v85, v83
	v_add3_u32 v1, v109, v1, s17
	v_bfe_u32 v82, v111, 16, 1
	v_lshl_add_u64 v[124:125], v[124:125], 0, v[84:85]
	v_lshrrev_b32_e32 v1, 16, v1
	v_add3_u32 v82, v111, v82, s17
	global_store_dwordx4 v[124:125], v[104:107], off sc1
	v_add_u32_e32 v108, s14, v98
	v_ashrrev_i32_e32 v109, 31, v108
	v_and_or_b32 v104, v82, s18, v1
	v_bfe_u32 v1, v113, 16, 1
	v_add3_u32 v1, v113, v1, s17
	v_bfe_u32 v82, v115, 16, 1
	v_lshrrev_b32_e32 v1, 16, v1
	v_add3_u32 v82, v115, v82, s17
	v_and_or_b32 v105, v82, s18, v1
	v_bfe_u32 v1, v117, 16, 1
	v_add3_u32 v1, v117, v1, s17
	v_bfe_u32 v82, v119, 16, 1
	v_lshrrev_b32_e32 v1, 16, v1
	v_add3_u32 v82, v119, v82, s17
	v_and_or_b32 v106, v82, s18, v1
	v_bfe_u32 v1, v121, 16, 1
	v_lshlrev_b64 v[108:109], 11, v[108:109]
	v_add3_u32 v1, v121, v1, s17
	v_bfe_u32 v82, v123, 16, 1
	v_lshl_add_u64 v[108:109], s[8:9], 0, v[108:109]
	v_lshrrev_b32_e32 v1, 16, v1
	v_add3_u32 v82, v123, v82, s17
	v_lshl_add_u64 v[108:109], v[108:109], 0, s[6:7]
	v_and_or_b32 v107, v82, s18, v1
	ds_read2_b32 v[110:111], v101 offset0:16 offset1:24
	v_lshl_add_u64 v[108:109], v[108:109], 0, v[84:85]
	global_store_dwordx4 v[108:109], v[104:107], off sc1
	ds_read2_b32 v[108:109], v101 offset0:49 offset1:57
	ds_read2_b32 v[112:113], v101 offset0:82 offset1:90
	ds_read2_b32 v[114:115], v101 offset0:115 offset1:123
	s_waitcnt lgkmcnt(3)
	v_bfe_u32 v1, v110, 16, 1
	v_add3_u32 v1, v110, v1, s17
	s_waitcnt lgkmcnt(2)
	v_bfe_u32 v82, v108, 16, 1
	ds_read2_b32 v[116:117], v101 offset0:148 offset1:156
	v_lshrrev_b32_e32 v1, 16, v1
	v_add3_u32 v82, v108, v82, s17
	ds_read2_b32 v[118:119], v101 offset0:181 offset1:189
	v_and_or_b32 v104, v82, s18, v1
	s_waitcnt lgkmcnt(3)
	v_bfe_u32 v1, v112, 16, 1
	v_add3_u32 v1, v112, v1, s17
	s_waitcnt lgkmcnt(2)
	v_bfe_u32 v82, v114, 16, 1
	ds_read2_b32 v[120:121], v101 offset0:214 offset1:222
	v_lshrrev_b32_e32 v1, 16, v1
	v_add3_u32 v82, v114, v82, s17
	ds_read2_b32 v[122:123], v101 offset0:247 offset1:255
	v_and_or_b32 v105, v82, s18, v1
	s_waitcnt lgkmcnt(3)
	v_bfe_u32 v1, v116, 16, 1
	v_add3_u32 v1, v116, v1, s17
	s_waitcnt lgkmcnt(2)
	v_bfe_u32 v82, v118, 16, 1
	v_lshrrev_b32_e32 v1, 16, v1
	v_add3_u32 v82, v118, v82, s17
	v_and_or_b32 v106, v82, s18, v1
	s_waitcnt lgkmcnt(1)
	v_bfe_u32 v1, v120, 16, 1
	v_add_u32_e32 v124, s14, v99
	v_add3_u32 v1, v120, v1, s17
	s_waitcnt lgkmcnt(0)
	v_bfe_u32 v82, v122, 16, 1
	v_ashrrev_i32_e32 v125, 31, v124
	v_lshrrev_b32_e32 v1, 16, v1
	v_add3_u32 v82, v122, v82, s17
	v_lshlrev_b64 v[124:125], 11, v[124:125]
	v_and_or_b32 v107, v82, s18, v1
	v_lshl_add_u64 v[124:125], s[8:9], 0, v[124:125]
	v_bfe_u32 v1, v111, 16, 1
	v_lshl_add_u64 v[124:125], v[124:125], 0, s[6:7]
	v_add3_u32 v1, v111, v1, s17
	v_bfe_u32 v82, v109, 16, 1
	v_lshl_add_u64 v[124:125], v[124:125], 0, v[84:85]
	v_lshrrev_b32_e32 v1, 16, v1
	v_add3_u32 v82, v109, v82, s17
	global_store_dwordx4 v[124:125], v[104:107], off sc1
	v_add_u32_e32 v108, s14, v100
	v_ashrrev_i32_e32 v109, 31, v108
	v_and_or_b32 v104, v82, s18, v1
	v_bfe_u32 v1, v113, 16, 1
	v_add3_u32 v1, v113, v1, s17
	v_bfe_u32 v82, v115, 16, 1
	v_lshrrev_b32_e32 v1, 16, v1
	v_add3_u32 v82, v115, v82, s17
	v_and_or_b32 v105, v82, s18, v1
	v_bfe_u32 v1, v117, 16, 1
	v_add3_u32 v1, v117, v1, s17
	v_bfe_u32 v82, v119, 16, 1
	v_lshrrev_b32_e32 v1, 16, v1
	v_add3_u32 v82, v119, v82, s17
	v_and_or_b32 v106, v82, s18, v1
	v_bfe_u32 v1, v121, 16, 1
	v_lshlrev_b64 v[108:109], 11, v[108:109]
	v_add3_u32 v1, v121, v1, s17
	v_bfe_u32 v82, v123, 16, 1
	v_lshl_add_u64 v[108:109], s[8:9], 0, v[108:109]
	v_lshrrev_b32_e32 v1, 16, v1
	v_add3_u32 v82, v123, v82, s17
	v_lshl_add_u64 v[108:109], v[108:109], 0, s[6:7]
	v_and_or_b32 v107, v82, s18, v1
	v_lshl_add_u64 v[108:109], v[108:109], 0, v[84:85]
	global_store_dwordx4 v[108:109], v[104:107], off sc1
	s_waitcnt lgkmcnt(0)
	s_andn2_b64 vcc, exec, s[4:5]
	s_cbranch_vccnz .LBB0_902
	v_mov_b64_e32 v[2:3], v[10:11]
	v_mov_b64_e32 v[4:5], v[12:13]
	v_mov_b64_e32 v[6:7], v[14:15]
	v_mov_b64_e32 v[8:9], v[16:17]
	s_mov_b32 s13, s20
	s_mov_b32 s14, s21
	s_mov_b32 s15, s22
	s_mov_b32 s12, s19
	v_mov_b32_e32 v18, v50
	v_mov_b32_e32 v19, v51
	v_mov_b32_e32 v20, v52
	v_mov_b32_e32 v21, v53
	v_mov_b32_e32 v22, v58
	v_mov_b32_e32 v23, v59
	v_mov_b32_e32 v24, v60
	v_mov_b32_e32 v25, v61
	v_mov_b32_e32 v26, v54
	v_mov_b32_e32 v27, v55
	v_mov_b32_e32 v28, v56
	v_mov_b32_e32 v29, v57
	v_mov_b32_e32 v30, v66
	v_mov_b32_e32 v31, v67
	v_mov_b32_e32 v32, v68
	v_mov_b32_e32 v33, v69
	v_mov_b32_e32 v34, v62
	v_mov_b32_e32 v35, v63
	v_mov_b32_e32 v36, v64
	v_mov_b32_e32 v37, v65
	v_mov_b32_e32 v38, v74
	v_mov_b32_e32 v39, v75
	v_mov_b32_e32 v40, v76
	v_mov_b32_e32 v41, v77
	v_mov_b32_e32 v42, v70
	v_mov_b32_e32 v43, v71
	v_mov_b32_e32 v44, v72
	v_mov_b32_e32 v45, v73
	v_mov_b32_e32 v46, v78
	v_mov_b32_e32 v47, v79
	v_mov_b32_e32 v48, v80
	v_mov_b32_e32 v49, v81
	s_branch .LBB0_902

; #define LAS __attribute__((address_space(3)))
; #define LDS_WAIT() asm volatile("s_waitcnt lgkmcnt(0)" ::: "memory")
; __device__ __forceinline__ void tr_store(const TrItem& it, const f32x4 (&v)[8], const float (&g)[8], LAS float* scr, int lane) {
;     const int k0 = 64 * it.kb, kl = lane >> 3, nq = lane & 7; const bool ok = 4 * nq < it.nvalid;
; #pragma unroll
;     for (int i = 0; i < 8; ++i) { const int kk = 8 * i + kl; const f32x4 x = ok ? v[i] * g[i] : (f32x4){0.f, 0.f, 0.f, 0.f};
;         scr[kk * 33 + 4 * nq + 0] = x[0]; scr[kk * 33 + 4 * nq + 1] = x[1]; scr[kk * 33 + 4 * nq + 2] = x[2]; scr[kk * 33 + 4 * nq + 3] = x[3]; }
;     LDS_WAIT(); asm volatile("" ::: "memory");
.LBB0_1017:
	s_waitcnt vmcnt(7)
	v_pk_mul_f32 v[100:101], v[6:7], v[74:75] op_sel_hi:[1,0]
	v_cmp_gt_i32_e32 vcc, s26, v92
	v_pk_mul_f32 v[102:103], v[8:9], v[74:75] op_sel_hi:[1,0]
	s_lshl_b32 s12, s23, 6
	v_cndmask_b32_e32 v81, 0, v101, vcc
	v_cndmask_b32_e32 v99, 0, v100, vcc
	s_waitcnt vmcnt(6)
	v_pk_mul_f32 v[100:101], v[10:11], v[74:75] op_sel:[0,1]
	v_cndmask_b32_e32 v1, 0, v103, vcc
	v_cndmask_b32_e32 v78, 0, v102, vcc
	ds_write2_b32 v97, v99, v81 offset1:1
	ds_write2_b32 v97, v78, v1 offset0:2 offset1:3
	v_pk_mul_f32 v[102:103], v[12:13], v[74:75] op_sel:[0,1]
	v_cndmask_b32_e32 v81, 0, v101, vcc
	v_cndmask_b32_e32 v99, 0, v100, vcc
	v_add_u32_e32 v100, 0x420, v97
	v_cndmask_b32_e32 v1, 0, v103, vcc
	v_cndmask_b32_e32 v78, 0, v102, vcc
	ds_write2_b32 v100, v99, v81 offset1:1
	v_add_u32_e32 v81, 0x428, v97
	s_waitcnt vmcnt(5)
	v_pk_mul_f32 v[100:101], v[14:15], v[76:77] op_sel_hi:[1,0]
	ds_write2_b32 v81, v78, v1 offset1:1
	v_pk_mul_f32 v[102:103], v[16:17], v[76:77] op_sel_hi:[1,0]
	v_cndmask_b32_e32 v81, 0, v101, vcc
	v_cndmask_b32_e32 v99, 0, v100, vcc
	v_add_u32_e32 v100, 0x840, v97
	v_cndmask_b32_e32 v1, 0, v103, vcc
	v_cndmask_b32_e32 v78, 0, v102, vcc
	ds_write2_b32 v100, v99, v81 offset1:1
	v_add_u32_e32 v81, 0x848, v97
	s_waitcnt vmcnt(4)
	v_pk_mul_f32 v[100:101], v[18:19], v[76:77] op_sel:[0,1]
	ds_write2_b32 v81, v78, v1 offset1:1
	v_pk_mul_f32 v[102:103], v[20:21], v[76:77] op_sel:[0,1]
	v_cndmask_b32_e32 v81, 0, v101, vcc
	v_cndmask_b32_e32 v99, 0, v100, vcc
	v_add_u32_e32 v100, 0xc60, v97
	v_cndmask_b32_e32 v1, 0, v103, vcc
	v_cndmask_b32_e32 v78, 0, v102, vcc
	ds_write2_b32 v100, v99, v81 offset1:1
	v_add_u32_e32 v81, 0xc68, v97
	s_waitcnt vmcnt(3)
	v_pk_mul_f32 v[100:101], v[22:23], v[2:3] op_sel_hi:[1,0]
	ds_write2_b32 v81, v78, v1 offset1:1
	v_pk_mul_f32 v[102:103], v[24:25], v[2:3] op_sel_hi:[1,0]
	v_cndmask_b32_e32 v81, 0, v101, vcc
	v_cndmask_b32_e32 v99, 0, v100, vcc
	v_add_u32_e32 v100, 0x1080, v97
	v_cndmask_b32_e32 v1, 0, v103, vcc
	v_cndmask_b32_e32 v78, 0, v102, vcc
	ds_write2_b32 v100, v99, v81 offset1:1
	v_add_u32_e32 v81, 0x1088, v97
	s_waitcnt vmcnt(2)
	v_pk_mul_f32 v[100:101], v[26:27], v[2:3] op_sel:[0,1]
	ds_write2_b32 v81, v78, v1 offset1:1
	v_pk_mul_f32 v[102:103], v[28:29], v[2:3] op_sel:[0,1]
	v_cndmask_b32_e32 v81, 0, v101, vcc
	v_cndmask_b32_e32 v99, 0, v100, vcc
	v_add_u32_e32 v100, 0x14a0, v97
	v_cndmask_b32_e32 v1, 0, v103, vcc
	v_cndmask_b32_e32 v78, 0, v102, vcc
	ds_write2_b32 v100, v99, v81 offset1:1
	v_add_u32_e32 v81, 0x14a8, v97
	s_waitcnt vmcnt(1)
	v_pk_mul_f32 v[100:101], v[30:31], v[4:5] op_sel_hi:[1,0]
	ds_write2_b32 v81, v78, v1 offset1:1
	v_pk_mul_f32 v[102:103], v[32:33], v[4:5] op_sel_hi:[1,0]
	v_cndmask_b32_e32 v81, 0, v101, vcc
	v_cndmask_b32_e32 v99, 0, v100, vcc
	v_add_u32_e32 v100, 0x18c0, v97
	v_cndmask_b32_e32 v1, 0, v103, vcc
	v_cndmask_b32_e32 v78, 0, v102, vcc
	ds_write2_b32 v100, v99, v81 offset1:1
	v_add_u32_e32 v81, 0x18c8, v97
	ds_write2_b32 v81, v78, v1 offset1:1
	v_mov_b32_e32 v78, v5
	s_waitcnt vmcnt(0)
	v_pk_mul_f32 v[100:101], v[34:35], v[78:79] op_sel_hi:[1,0]
	v_pk_mul_f32 v[102:103], v[36:37], v[78:79] op_sel_hi:[1,0]
	v_cndmask_b32_e32 v81, 0, v101, vcc
	v_cndmask_b32_e32 v99, 0, v100, vcc
	v_add_u32_e32 v100, 0x1ce0, v97
	v_cndmask_b32_e32 v1, 0, v103, vcc
	v_cndmask_b32_e32 v78, 0, v102, vcc
	ds_write2_b32 v100, v99, v81 offset1:1
	v_add_u32_e32 v81, 0x1ce8, v97
	ds_write2_b32 v81, v78, v1 offset1:1
	s_waitcnt lgkmcnt(0)
	ds_read2_b32 v[104:105], v96 offset1:8
	ds_read2_b32 v[106:107], v96 offset0:33 offset1:41
	ds_read2_b32 v[108:109], v96 offset0:66 offset1:74
	ds_read2_b32 v[110:111], v96 offset0:99 offset1:107
	ds_read2_b32 v[112:113], v96 offset0:132 offset1:140
	s_waitcnt lgkmcnt(4)
	v_bfe_u32 v1, v104, 16, 1
	v_add3_u32 v1, v104, v1, s27
	s_waitcnt lgkmcnt(3)
	v_bfe_u32 v78, v106, 16, 1
	v_lshrrev_b32_e32 v1, 16, v1
	v_add3_u32 v78, v106, v78, s27
	ds_read2_b32 v[114:115], v96 offset0:165 offset1:173
	v_and_or_b32 v100, v78, s28, v1
	s_waitcnt lgkmcnt(3)
	v_bfe_u32 v1, v108, 16, 1
	v_add3_u32 v1, v108, v1, s27
	s_waitcnt lgkmcnt(2)
	v_bfe_u32 v78, v110, 16, 1
	ds_read2_b32 v[116:117], v96 offset0:198 offset1:206
	v_lshrrev_b32_e32 v1, 16, v1
	v_add3_u32 v78, v110, v78, s27
	ds_read2_b32 v[118:119], v96 offset0:231 offset1:239
	v_and_or_b32 v101, v78, s28, v1
	s_waitcnt lgkmcnt(3)
	v_bfe_u32 v1, v112, 16, 1
	v_add3_u32 v1, v112, v1, s27
	s_waitcnt lgkmcnt(2)
	v_bfe_u32 v78, v114, 16, 1
	v_lshrrev_b32_e32 v1, 16, v1
	v_add3_u32 v78, v114, v78, s27
	v_and_or_b32 v102, v78, s28, v1
	s_waitcnt lgkmcnt(1)
	v_bfe_u32 v1, v116, 16, 1
	v_add3_u32 v1, v116, v1, s27
	s_waitcnt lgkmcnt(0)
; #define GAS __attribute__((address_space(1)))
; #define LAS __attribute__((address_space(3)))
; #define LDS_WAIT() asm volatile("s_waitcnt lgkmcnt(0)" ::: "memory")
; __device__ __forceinline__ unsigned pk2(float lo, float hi) { return f2bf(lo) | (f2bf(hi) << 16); }
; __device__ __forceinline__ void tr_store(const TrItem& it, const f32x4 (&v)[8], const float (&g)[8], LAS float* scr, int lane) {
;     ...
;     const int c = lane & 7;
; #pragma unroll
;     for (int j = 0; j < 4; ++j) { const int nn = (lane >> 3) + 8 * j; const LAS float* s = scr + (8 * c) * 33 + nn;
;         v4u o; o.x = pk2(s[0 * 33], s[1 * 33]); o.y = pk2(s[2 * 33], s[3 * 33]); o.z = pk2(s[4 * 33], s[5 * 33]); o.w = pk2(s[6 * 33], s[7 * 33]);
;         *(GAS v4u*)(it.WT + (size_t)(it.dst_row0 + nn) * it.Kdst + it.dst_koff + k0 + 8 * c) = o; }
;     LDS_WAIT(); asm volatile("" ::: "memory");
; __device__ __forceinline__ void p0_transposes(Frame& F, int it_lo, int it_hi, int gw, int NGW) {
;     ...
;         cur = nxt; it = nx;
; #pragma unroll
;         for (int i = 0; i < 8; ++i) { v[i] = v2[i]; g[i] = g2[i]; }
	v_bfe_u32 v78, v118, 16, 1
	v_lshrrev_b32_e32 v1, 16, v1
	v_add3_u32 v78, v118, v78, s27
	v_and_or_b32 v103, v78, s28, v1
	v_add_u32_e32 v1, s24, v90
	v_mad_u64_u32 v[120:121], s[2:3], v1, s25, 0
	v_ashrrev_i32_e32 v81, 31, v1
	v_mov_b32_e32 v78, v121
	v_mad_u64_u32 v[122:123], s[2:3], v81, s25, v[78:79]
	v_mov_b32_e32 v121, v122
	s_ashr_i32 s13, s12, 31
	v_lshl_add_u64 v[120:121], v[120:121], 1, s[0:1]
	s_lshl_b64 s[2:3], s[4:5], 1
	v_lshl_add_u64 v[120:121], v[120:121], 0, s[2:3]
	s_lshl_b64 s[12:13], s[12:13], 1
	v_bfe_u32 v1, v105, 16, 1
	v_lshl_add_u64 v[120:121], v[120:121], 0, s[12:13]
	v_mov_b32_e32 v81, v79
	v_add3_u32 v1, v105, v1, s27
	v_bfe_u32 v78, v107, 16, 1
	v_lshl_add_u64 v[120:121], v[120:121], 0, v[80:81]
	v_lshrrev_b32_e32 v1, 16, v1
	v_add3_u32 v78, v107, v78, s27
	global_store_dwordx4 v[120:121], v[100:103], off sc1
	s_andn2_b64 vcc, exec, s[8:9]
	s_nop 0
	v_and_or_b32 v100, v78, s28, v1
	v_bfe_u32 v1, v109, 16, 1
	v_add3_u32 v1, v109, v1, s27
	v_bfe_u32 v78, v111, 16, 1
	v_lshrrev_b32_e32 v1, 16, v1
	v_add3_u32 v78, v111, v78, s27
	v_and_or_b32 v101, v78, s28, v1
	v_bfe_u32 v1, v113, 16, 1
	v_add3_u32 v1, v113, v1, s27
	v_bfe_u32 v78, v115, 16, 1
	v_lshrrev_b32_e32 v1, 16, v1
	v_add3_u32 v78, v115, v78, s27
	v_and_or_b32 v102, v78, s28, v1
	v_bfe_u32 v1, v117, 16, 1
	v_add3_u32 v1, v117, v1, s27
	v_bfe_u32 v78, v119, 16, 1
	v_lshrrev_b32_e32 v1, 16, v1
	v_add3_u32 v78, v119, v78, s27
	v_and_or_b32 v103, v78, s28, v1
	v_add_u32_e32 v1, s24, v93
	v_mad_u64_u32 v[104:105], s[14:15], v1, s25, 0
	v_ashrrev_i32_e32 v99, 31, v1
	v_mov_b32_e32 v78, v105
	v_mad_u64_u32 v[106:107], s[14:15], v99, s25, v[78:79]
	v_mov_b32_e32 v105, v106
	v_lshl_add_u64 v[104:105], v[104:105], 1, s[0:1]
	v_lshl_add_u64 v[104:105], v[104:105], 0, s[2:3]
	v_lshl_add_u64 v[104:105], v[104:105], 0, s[12:13]
	ds_read2_b32 v[106:107], v96 offset0:16 offset1:24
	v_lshl_add_u64 v[104:105], v[104:105], 0, v[80:81]
	global_store_dwordx4 v[104:105], v[100:103], off sc1
	ds_read2_b32 v[104:105], v96 offset0:49 offset1:57
	ds_read2_b32 v[108:109], v96 offset0:82 offset1:90
	ds_read2_b32 v[110:111], v96 offset0:115 offset1:123
	s_waitcnt lgkmcnt(3)
	v_bfe_u32 v1, v106, 16, 1
	v_add3_u32 v1, v106, v1, s27
	s_waitcnt lgkmcnt(2)
	v_bfe_u32 v78, v104, 16, 1
	ds_read2_b32 v[112:113], v96 offset0:148 offset1:156
	v_lshrrev_b32_e32 v1, 16, v1
	v_add3_u32 v78, v104, v78, s27
	ds_read2_b32 v[114:115], v96 offset0:181 offset1:189
	v_and_or_b32 v100, v78, s28, v1
	s_waitcnt lgkmcnt(3)
	v_bfe_u32 v1, v108, 16, 1
	v_add3_u32 v1, v108, v1, s27
	s_waitcnt lgkmcnt(2)
	v_bfe_u32 v78, v110, 16, 1
	ds_read2_b32 v[116:117], v96 offset0:214 offset1:222
	v_lshrrev_b32_e32 v1, 16, v1
	v_add3_u32 v78, v110, v78, s27
	ds_read2_b32 v[118:119], v96 offset0:247 offset1:255
	v_and_or_b32 v101, v78, s28, v1
	s_waitcnt lgkmcnt(3)
	v_bfe_u32 v1, v112, 16, 1
	v_add3_u32 v1, v112, v1, s27
	s_waitcnt lgkmcnt(2)
	v_bfe_u32 v78, v114, 16, 1
	v_lshrrev_b32_e32 v1, 16, v1
	v_add3_u32 v78, v114, v78, s27
	v_and_or_b32 v102, v78, s28, v1
	s_waitcnt lgkmcnt(1)
	v_bfe_u32 v1, v116, 16, 1
	v_add3_u32 v1, v116, v1, s27
	s_waitcnt lgkmcnt(0)
	v_bfe_u32 v78, v118, 16, 1
	v_lshrrev_b32_e32 v1, 16, v1
	v_add3_u32 v78, v118, v78, s27
	v_and_or_b32 v103, v78, s28, v1
	v_add_u32_e32 v1, s24, v94
	v_mad_u64_u32 v[120:121], s[14:15], v1, s25, 0
	v_ashrrev_i32_e32 v99, 31, v1
	v_mov_b32_e32 v78, v121
	v_mad_u64_u32 v[122:123], s[14:15], v99, s25, v[78:79]
	v_mov_b32_e32 v121, v122
	v_lshl_add_u64 v[120:121], v[120:121], 1, s[0:1]
	v_lshl_add_u64 v[120:121], v[120:121], 0, s[2:3]
	v_bfe_u32 v1, v107, 16, 1
	v_lshl_add_u64 v[120:121], v[120:121], 0, s[12:13]
	v_add3_u32 v1, v107, v1, s27
	v_bfe_u32 v78, v105, 16, 1
	v_lshl_add_u64 v[120:121], v[120:121], 0, v[80:81]
	v_lshrrev_b32_e32 v1, 16, v1
	v_add3_u32 v78, v105, v78, s27
	global_store_dwordx4 v[120:121], v[100:103], off sc1
	s_nop 1
	v_and_or_b32 v100, v78, s28, v1
	v_bfe_u32 v1, v109, 16, 1
	v_add3_u32 v1, v109, v1, s27
	v_bfe_u32 v78, v111, 16, 1
	v_lshrrev_b32_e32 v1, 16, v1
	v_add3_u32 v78, v111, v78, s27
	v_and_or_b32 v101, v78, s28, v1
	v_bfe_u32 v1, v113, 16, 1
	v_add3_u32 v1, v113, v1, s27
	v_bfe_u32 v78, v115, 16, 1
	v_lshrrev_b32_e32 v1, 16, v1
	v_add3_u32 v78, v115, v78, s27
	v_and_or_b32 v102, v78, s28, v1
	v_bfe_u32 v1, v117, 16, 1
	v_add3_u32 v1, v117, v1, s27
	v_bfe_u32 v78, v119, 16, 1
	v_lshrrev_b32_e32 v1, 16, v1
	v_add3_u32 v78, v119, v78, s27
	v_and_or_b32 v103, v78, s28, v1
	v_add_u32_e32 v1, s24, v95
	v_mad_u64_u32 v[104:105], s[14:15], v1, s25, 0
	v_ashrrev_i32_e32 v99, 31, v1
	v_mov_b32_e32 v78, v105
	v_mad_u64_u32 v[106:107], s[14:15], v99, s25, v[78:79]
	v_mov_b32_e32 v105, v106
	v_lshl_add_u64 v[104:105], v[104:105], 1, s[0:1]
	v_lshl_add_u64 v[104:105], v[104:105], 0, s[2:3]
	v_lshl_add_u64 v[104:105], v[104:105], 0, s[12:13]
	v_lshl_add_u64 v[104:105], v[104:105], 0, v[80:81]
	global_store_dwordx4 v[104:105], v[100:103], off sc1
	s_waitcnt lgkmcnt(0)
	s_cbranch_vccnz .LBB0_974
	v_mov_b64_e32 v[2:3], v[70:71]
	v_mov_b64_e32 v[4:5], v[72:73]
	v_mov_b64_e32 v[76:77], v[84:85]
	v_mov_b64_e32 v[74:75], v[82:83]
	s_mov_b32 s4, s34
	s_mov_b32 s23, s30
	s_mov_b32 s24, s31
	s_mov_b32 s25, s33
	s_mov_b32 s26, s35
	s_mov_b64 s[0:1], s[10:11]
	s_mov_b32 s22, s29
	v_mov_b32_e32 v6, v38
	v_mov_b32_e32 v7, v39
	v_mov_b32_e32 v8, v40
	v_mov_b32_e32 v9, v41
	v_mov_b32_e32 v10, v46
	v_mov_b32_e32 v11, v47
	v_mov_b32_e32 v12, v48
	v_mov_b32_e32 v13, v49
	v_mov_b32_e32 v14, v42
	v_mov_b32_e32 v15, v43
	v_mov_b32_e32 v16, v44
	v_mov_b32_e32 v17, v45
	v_mov_b32_e32 v18, v54
	v_mov_b32_e32 v19, v55
	v_mov_b32_e32 v20, v56
	v_mov_b32_e32 v21, v57
	v_mov_b32_e32 v22, v50
	v_mov_b32_e32 v23, v51
	v_mov_b32_e32 v24, v52
	v_mov_b32_e32 v25, v53
	v_mov_b32_e32 v26, v62
	v_mov_b32_e32 v27, v63
	v_mov_b32_e32 v28, v64
	v_mov_b32_e32 v29, v65
	v_mov_b32_e32 v30, v58
	v_mov_b32_e32 v31, v59
	v_mov_b32_e32 v32, v60
	v_mov_b32_e32 v33, v61
	v_mov_b32_e32 v34, v66
	v_mov_b32_e32 v35, v67
	v_mov_b32_e32 v36, v68
	v_mov_b32_e32 v37, v69
	s_branch .LBB0_974
